# norm loop H/U stores made write-through (sc1) so the grid barrier finds fewer dirty L2 lines; on top of QKV rope pipelining
# speedup vs baseline: 1.0055x; 1.0040x over previous
; __device__ __forceinline__ float bf_lo(unsigned w) { return __uint_as_float(w << 16); }
; __device__ __forceinline__ float bf_hi(unsigned w) { return __uint_as_float(w & 0xffff0000u); }
; template <int R, bool SRCB> ...
;     ...
;         for (int j = 0; j < 2; ++j) { const int c = 8 * lane + 512 * j;
;             if (SRCB) { const u32x4 t = *(const u32x4*)((const bf16_t*)hp_ + (size_t)r * DM + c);
;                 h[r][j][0] = (f32x4){hf_lo(t.x), hf_hi(t.x), hf_lo(t.y), hf_hi(t.y)}; h[r][j][1] = (f32x4){hf_lo(t.z), hf_hi(t.z), hf_lo(t.w), hf_hi(t.w)}; }
;             else { h[r][j][0] = *(const f32x4*)((const float*)hp_ + (size_t)r * DM + c); h[r][j][1] = *(const f32x4*)((const float*)hp_ + (size_t)r * DM + c + 4); }
;             if (Y) yr[r][j] = *(const u32x4*)(Y + (size_t)(row0 + r) * DM + c); }
;     if (Y) {
;         f32x4 gg[2][2];
; #pragma unroll
;         for (int j = 0; j < 2; ++j)
; #pragma unroll
;             for (int k = 0; k < 2; ++k) { const int c = 8 * lane + 512 * j + 4 * k; gg[j][k] = *(const f32x4*)(gpost + c) * *(const f32x4*)(gate + (size_t)mrow * 9216 + c); }
; #pragma unroll
;         for (int r = 0; r < R; ++r) {
;             f32x4 y[2][2]; float ss = 0.f;
; #pragma unroll
;             for (int j = 0; j < 2; ++j) { const u32x4 t = yr[r][j];
;                 y[j][0] = (f32x4){bf_lo(t.x), bf_hi(t.x), bf_lo(t.y), bf_hi(t.y)}; y[j][1] = (f32x4){bf_lo(t.z), bf_hi(t.z), bf_lo(t.w), bf_hi(t.w)};
;                 if (R == 1 && YP) {
; #pragma unroll
;                     for (int k = 0; k < 2; ++k) { const float* pp = YP + (size_t)(row0 - M_LAT) * DM + 8 * lane + 512 * j + 4 * k; f32x4 s = *(const f32x4*)pp;
; #pragma unroll
;                         for (int q = 1; q < pg8::NSL; ++q) s = s + *(const f32x4*)(pp + (size_t)q * 2048 * DM);
;                         y[j][k] = s; } }
; #pragma unroll
;                 for (int k = 0; k < 2; ++k) ss += (y[j][k][0] * y[j][k][0] + y[j][k][1] * y[j][k][1]) + (y[j][k][2] * y[j][k][2] + y[j][k][3] * y[j][k][3]); }
;             const float rr = __builtin_amdgcn_rsqf(wave_sum(ss) * (1.0f / DM) + 1e-6f) * w;
; #pragma unroll
;             for (int j = 0; j < 2; ++j)
; #pragma unroll
;                 for (int k = 0; k < 2; ++k) h[r][j][k] = h[r][j][k] + gg[j][k] * (y[j][k] * rr);
;     ...
;         f32x4 gp[2][2], sc1[2][2], sh[2][2];
; #pragma unroll
;         for (int j = 0; j < 2; ++j)
; #pragma unroll
nrmx_chunk:
	s_lshr_b32 s2, s23, 8
	s_and_b32 s3, s23, 0xff
	s_lshl_b32 s4, s2, 23
	s_lshl_b32 s3, s3, 13
	s_add_u32 s4, s4, s3
	s_add_u32 s42, s98, s4
	s_addc_u32 s43, s99, 0
	s_add_u32 s44, s14, s4
	s_addc_u32 s45, s15, 0
	s_mul_i32 s2, s2, 0x9000
	s_add_u32 s8, s36, s2
	s_addc_u32 s9, s37, 0
	s_add_u32 s10, s30, s2
	s_addc_u32 s11, s31, 0
	s_add_u32 s12, s28, s2
	s_addc_u32 s13, s29, 0
	global_load_dwordx4 v[0:3], v182, s[34:35]
	global_load_dwordx4 v[4:7], v182, s[34:35] offset:16
	global_load_dwordx4 v[8:11], v182, s[34:35] offset:2048
	global_load_dwordx4 v[12:15], v182, s[34:35] offset:2064
	global_load_dwordx4 v[116:119], v182, s[8:9]
	global_load_dwordx4 v[120:123], v182, s[8:9] offset:16
	global_load_dwordx4 v[124:127], v182, s[8:9] offset:2048
	global_load_dwordx4 v[128:131], v182, s[8:9] offset:2064
	global_load_dwordx4 v[16:19], v182, s[26:27]
	global_load_dwordx4 v[20:23], v182, s[26:27] offset:16
	global_load_dwordx4 v[24:27], v182, s[26:27] offset:2048
	global_load_dwordx4 v[28:31], v182, s[26:27] offset:2064
	global_load_dwordx4 v[32:35], v182, s[10:11]
	global_load_dwordx4 v[36:39], v182, s[10:11] offset:16
	global_load_dwordx4 v[40:43], v182, s[10:11] offset:2048
	global_load_dwordx4 v[44:47], v182, s[10:11] offset:2064
	global_load_dwordx4 v[48:51], v182, s[12:13]
	global_load_dwordx4 v[52:55], v182, s[12:13] offset:16
	global_load_dwordx4 v[56:59], v182, s[12:13] offset:2048
	global_load_dwordx4 v[60:63], v182, s[12:13] offset:2064
	global_load_dwordx4 v[64:67], v184, s[42:43] offset:-4096
	global_load_dwordx4 v[68:71], v184, s[42:43] offset:-3072
	global_load_dwordx4 v[148:151], v184, s[44:45] offset:-4096
	global_load_dwordx4 v[152:155], v184, s[44:45] offset:-3072
	global_load_dwordx4 v[72:75], v184, s[42:43] offset:-2048
	global_load_dwordx4 v[76:79], v184, s[42:43] offset:-1024
	global_load_dwordx4 v[156:159], v184, s[44:45] offset:-2048
	global_load_dwordx4 v[160:163], v184, s[44:45] offset:-1024
	global_load_dwordx4 v[80:83], v184, s[42:43] offset:0
	global_load_dwordx4 v[84:87], v184, s[42:43] offset:1024
	global_load_dwordx4 v[164:167], v184, s[44:45] offset:0
	global_load_dwordx4 v[168:171], v184, s[44:45] offset:1024
	global_load_dwordx4 v[88:91], v184, s[42:43] offset:2048
	global_load_dwordx4 v[92:95], v184, s[42:43] offset:3072
	global_load_dwordx4 v[172:175], v184, s[44:45] offset:2048
	global_load_dwordx4 v[176:179], v184, s[44:45] offset:3072
	s_waitcnt vmcnt(16)
	v_pk_mul_f32 v[0:1], v[0:1], v[116:117]
	v_pk_mul_f32 v[2:3], v[2:3], v[118:119]
	v_pk_mul_f32 v[4:5], v[4:5], v[120:121]
	v_pk_mul_f32 v[6:7], v[6:7], v[122:123]
	v_pk_mul_f32 v[8:9], v[8:9], v[124:125]
	v_pk_mul_f32 v[10:11], v[10:11], v[126:127]
	v_pk_mul_f32 v[12:13], v[12:13], v[128:129]
	v_pk_mul_f32 v[14:15], v[14:15], v[130:131]
	v_pk_add_f32 v[32:33], v[32:33], 1.0 op_sel_hi:[1,0]
	v_pk_add_f32 v[34:35], v[34:35], 1.0 op_sel_hi:[1,0]
	v_pk_add_f32 v[36:37], v[36:37], 1.0 op_sel_hi:[1,0]
	v_pk_add_f32 v[38:39], v[38:39], 1.0 op_sel_hi:[1,0]
	v_pk_add_f32 v[40:41], v[40:41], 1.0 op_sel_hi:[1,0]
	v_pk_add_f32 v[42:43], v[42:43], 1.0 op_sel_hi:[1,0]
	v_pk_add_f32 v[44:45], v[44:45], 1.0 op_sel_hi:[1,0]
	v_pk_add_f32 v[46:47], v[46:47], 1.0 op_sel_hi:[1,0]
	s_waitcnt vmcnt(12)
	v_lshlrev_b32_e32 v116, 16, v148
	v_and_b32_e32 v117, 0xffff0000, v148
	v_lshlrev_b32_e32 v118, 16, v149
	v_and_b32_e32 v119, 0xffff0000, v149
	v_lshlrev_b32_e32 v120, 16, v150
	v_and_b32_e32 v121, 0xffff0000, v150
	v_lshlrev_b32_e32 v122, 16, v151
	v_and_b32_e32 v123, 0xffff0000, v151
	v_lshlrev_b32_e32 v124, 16, v152
	v_and_b32_e32 v125, 0xffff0000, v152
	v_lshlrev_b32_e32 v126, 16, v153
	v_and_b32_e32 v127, 0xffff0000, v153
	v_lshlrev_b32_e32 v128, 16, v154
	v_and_b32_e32 v129, 0xffff0000, v154
	v_lshlrev_b32_e32 v130, 16, v155
	v_and_b32_e32 v131, 0xffff0000, v155
	v_cvt_f32_f16_e32 v198, v64
	v_cvt_f32_f16_sdwa v199, v64 dst_sel:DWORD dst_unused:UNUSED_PAD src0_sel:WORD_1
	v_cvt_f32_f16_e32 v200, v65
	v_cvt_f32_f16_sdwa v201, v65 dst_sel:DWORD dst_unused:UNUSED_PAD src0_sel:WORD_1
	v_cvt_f32_f16_e32 v202, v66
	v_cvt_f32_f16_sdwa v203, v66 dst_sel:DWORD dst_unused:UNUSED_PAD src0_sel:WORD_1
	v_cvt_f32_f16_e32 v204, v67
	v_cvt_f32_f16_sdwa v205, v67 dst_sel:DWORD dst_unused:UNUSED_PAD src0_sel:WORD_1
	v_cvt_f32_f16_e32 v206, v68
	v_cvt_f32_f16_sdwa v207, v68 dst_sel:DWORD dst_unused:UNUSED_PAD src0_sel:WORD_1
	v_cvt_f32_f16_e32 v208, v69
	v_cvt_f32_f16_sdwa v209, v69 dst_sel:DWORD dst_unused:UNUSED_PAD src0_sel:WORD_1
	v_cvt_f32_f16_e32 v210, v70
	v_cvt_f32_f16_sdwa v211, v70 dst_sel:DWORD dst_unused:UNUSED_PAD src0_sel:WORD_1
	v_cvt_f32_f16_e32 v212, v71
	v_cvt_f32_f16_sdwa v213, v71 dst_sel:DWORD dst_unused:UNUSED_PAD src0_sel:WORD_1
	global_load_dwordx4 v[64:67], v185, s[42:43] offset:-4096
	global_load_dwordx4 v[68:71], v185, s[42:43] offset:-3072
	global_load_dwordx4 v[148:151], v185, s[44:45] offset:-4096
	global_load_dwordx4 v[152:155], v185, s[44:45] offset:-3072
	v_pk_mul_f32 v[140:141], v[116:117], v[116:117]
	v_pk_fma_f32 v[140:141], v[118:119], v[118:119], v[140:141]
	v_pk_fma_f32 v[140:141], v[120:121], v[120:121], v[140:141]
	v_pk_fma_f32 v[140:141], v[122:123], v[122:123], v[140:141]
	v_pk_fma_f32 v[140:141], v[124:125], v[124:125], v[140:141]
	v_pk_fma_f32 v[140:141], v[126:127], v[126:127], v[140:141]
	v_pk_fma_f32 v[140:141], v[128:129], v[128:129], v[140:141]
	v_pk_fma_f32 v[140:141], v[130:131], v[130:131], v[140:141]
	v_add_f32_e32 v140, v140, v141
	s_nop 1
	v_add_f32_dpp v140, v140, v140 quad_perm:[1,0,3,2] row_mask:0xf bank_mask:0xf
	s_nop 1
	v_add_f32_dpp v140, v140, v140 quad_perm:[2,3,0,1] row_mask:0xf bank_mask:0xf
	s_nop 1
; __device__ __forceinline__ unsigned pk2(float lo, float hi) { return pg8::cvt_pk_bf16(lo, hi); }
; template <int R, bool SRCB> ...
;     ...
;             const float rr = __builtin_amdgcn_rsqf(wave_sum(ss) * (1.0f / DM) + 1e-6f) * w;
; #pragma unroll
;             for (int j = 0; j < 2; ++j)
; #pragma unroll
;                 for (int k = 0; k < 2; ++k) h[r][j][k] = h[r][j][k] + gg[j][k] * (y[j][k] * rr);
;         }
;     }
; #pragma unroll
;     for (int r = 0; r < R; ++r)
; #pragma unroll
;         for (int j = 0; j < 2; ++j) { const int c = 8 * lane + 512 * j;
;             if (final_out) { *(f32x4*)(final_out + (size_t)(row0 + r) * DM + c) = h[r][j][0]; *(f32x4*)(final_out + (size_t)(row0 + r) * DM + c + 4) = h[r][j][1]; }
;             else { u32x4 t; t.x = pkh2(h[r][j][0][0], h[r][j][0][1]); t.y = pkh2(h[r][j][0][2], h[r][j][0][3]); t.z = pkh2(h[r][j][1][0], h[r][j][1][1]); t.w = pkh2(h[r][j][1][2], h[r][j][1][3]);
;                 *(u32x4*)(hout + (size_t)(row0 + r) * DM + c) = t; } }
;     if (U) {
;         f32x4 gp[2][2], sc1[2][2], sh[2][2];
; #pragma unroll
;         for (int j = 0; j < 2; ++j)
; #pragma unroll
;             for (int k = 0; k < 2; ++k) { const int c = 8 * lane + 512 * j + 4 * k; gp[j][k] = *(const f32x4*)(gpre + c); sc1[j][k] = *(const f32x4*)(scale + (size_t)mrow * 9216 + c) + 1.0f; sh[j][k] = *(const f32x4*)(shift + (size_t)mrow * 9216 + c); }
; #pragma unroll
;         for (int r = 0; r < R; ++r) {
;             float ss = 0.f;
; #pragma unroll
;             for (int j = 0; j < 2; ++j)
; #pragma unroll
;                 for (int k = 0; k < 2; ++k) ss += (h[r][j][k][0] * h[r][j][k][0] + h[r][j][k][1] * h[r][j][k][1]) + (h[r][j][k][2] * h[r][j][k][2] + h[r][j][k][3] * h[r][j][k][3]);
;             const float rr = __builtin_amdgcn_rsqf(wave_sum(ss) * (1.0f / DM) + 1e-6f);
; #pragma unroll
;             for (int j = 0; j < 2; ++j) { const f32x4 v0 = (h[r][j][0] * rr * gp[j][0]) * sc1[j][0] + sh[j][0], v1 = (h[r][j][1] * rr * gp[j][1]) * sc1[j][1] + sh[j][1];
;                 u32x4 t; t.x = pk2(v0[0], v0[1]); t.y = pk2(v0[2], v0[3]); t.z = pk2(v1[0], v1[1]); t.w = pk2(v1[2], v1[3]);
;                 *(u32x4*)(U + (size_t)(row0 + r) * DM + 8 * lane + 512 * j) = t; }
	v_add_f32_dpp v140, v140, v140 row_ror:4 row_mask:0xf bank_mask:0xf
	s_nop 1
	v_add_f32_dpp v140, v140, v140 row_ror:8 row_mask:0xf bank_mask:0xf
	s_nop 1
	v_add_f32_dpp v140, v140, v140 row_bcast:15 row_mask:0xa bank_mask:0xf
	s_nop 1
	v_add_f32_dpp v140, v140, v140 row_bcast:31 row_mask:0xc bank_mask:0xf
	s_nop 1
	v_fmamk_f32 v140, v140, 0x3a800000, v224
	v_rsq_f32_e32 v140, v140
	s_nop 0
	v_mul_f32_e32 v140, v144, v140
	s_nop 0
	v_readlane_b32 s4, v140, 63
	s_nop 1
	v_pk_mul_f32 v[116:117], v[116:117], s[4:5] op_sel_hi:[1,0]
	v_pk_mul_f32 v[118:119], v[118:119], s[4:5] op_sel_hi:[1,0]
	v_pk_mul_f32 v[120:121], v[120:121], s[4:5] op_sel_hi:[1,0]
	v_pk_mul_f32 v[122:123], v[122:123], s[4:5] op_sel_hi:[1,0]
	v_pk_mul_f32 v[124:125], v[124:125], s[4:5] op_sel_hi:[1,0]
	v_pk_mul_f32 v[126:127], v[126:127], s[4:5] op_sel_hi:[1,0]
	v_pk_mul_f32 v[128:129], v[128:129], s[4:5] op_sel_hi:[1,0]
	v_pk_mul_f32 v[130:131], v[130:131], s[4:5] op_sel_hi:[1,0]
	v_pk_fma_f32 v[198:199], v[0:1], v[116:117], v[198:199]
	v_pk_fma_f32 v[200:201], v[2:3], v[118:119], v[200:201]
	v_pk_fma_f32 v[202:203], v[4:5], v[120:121], v[202:203]
	v_pk_fma_f32 v[204:205], v[6:7], v[122:123], v[204:205]
	v_pk_fma_f32 v[206:207], v[8:9], v[124:125], v[206:207]
	v_pk_fma_f32 v[208:209], v[10:11], v[126:127], v[208:209]
	v_pk_fma_f32 v[210:211], v[12:13], v[128:129], v[210:211]
	v_pk_fma_f32 v[212:213], v[14:15], v[130:131], v[212:213]
	v_cvt_f16_f32_e32 v132, v198
	v_cvt_f16_f32_e32 v133, v200
	v_cvt_f16_f32_e32 v134, v202
	v_cvt_f16_f32_e32 v135, v204
	v_cvt_f16_f32_e32 v136, v206
	v_cvt_f16_f32_e32 v137, v208
	v_cvt_f16_f32_e32 v138, v210
	v_cvt_f16_f32_e32 v139, v212
	v_cvt_f16_f32_sdwa v132, v199 dst_sel:WORD_1 dst_unused:UNUSED_PRESERVE src0_sel:DWORD
	v_cvt_f16_f32_sdwa v133, v201 dst_sel:WORD_1 dst_unused:UNUSED_PRESERVE src0_sel:DWORD
	v_cvt_f16_f32_sdwa v134, v203 dst_sel:WORD_1 dst_unused:UNUSED_PRESERVE src0_sel:DWORD
	v_cvt_f16_f32_sdwa v135, v205 dst_sel:WORD_1 dst_unused:UNUSED_PRESERVE src0_sel:DWORD
	v_cvt_f16_f32_sdwa v136, v207 dst_sel:WORD_1 dst_unused:UNUSED_PRESERVE src0_sel:DWORD
	v_cvt_f16_f32_sdwa v137, v209 dst_sel:WORD_1 dst_unused:UNUSED_PRESERVE src0_sel:DWORD
	v_cvt_f16_f32_sdwa v138, v211 dst_sel:WORD_1 dst_unused:UNUSED_PRESERVE src0_sel:DWORD
	v_cvt_f16_f32_sdwa v139, v213 dst_sel:WORD_1 dst_unused:UNUSED_PRESERVE src0_sel:DWORD
	s_nop 0
	global_store_dwordx4 v184, v[132:135], s[42:43] offset:-4096 sc1
	global_store_dwordx4 v184, v[136:139], s[42:43] offset:-3072 sc1
	v_pk_mul_f32 v[140:141], v[198:199], v[198:199]
	v_pk_fma_f32 v[140:141], v[200:201], v[200:201], v[140:141]
	v_pk_fma_f32 v[140:141], v[202:203], v[202:203], v[140:141]
	v_pk_fma_f32 v[140:141], v[204:205], v[204:205], v[140:141]
	v_pk_fma_f32 v[140:141], v[206:207], v[206:207], v[140:141]
	v_pk_fma_f32 v[140:141], v[208:209], v[208:209], v[140:141]
	v_pk_fma_f32 v[140:141], v[210:211], v[210:211], v[140:141]
	v_pk_fma_f32 v[140:141], v[212:213], v[212:213], v[140:141]
	v_add_f32_e32 v140, v140, v141
	s_nop 1
	v_add_f32_dpp v140, v140, v140 quad_perm:[1,0,3,2] row_mask:0xf bank_mask:0xf
	s_nop 1
	v_add_f32_dpp v140, v140, v140 quad_perm:[2,3,0,1] row_mask:0xf bank_mask:0xf
	s_nop 1
	v_add_f32_dpp v140, v140, v140 row_ror:4 row_mask:0xf bank_mask:0xf
	s_nop 1
	v_add_f32_dpp v140, v140, v140 row_ror:8 row_mask:0xf bank_mask:0xf
	s_nop 1
	v_add_f32_dpp v140, v140, v140 row_bcast:15 row_mask:0xa bank_mask:0xf
	s_nop 1
	v_add_f32_dpp v140, v140, v140 row_bcast:31 row_mask:0xc bank_mask:0xf
	s_nop 1
	v_fmamk_f32 v140, v140, 0x3a800000, v224
	v_rsq_f32_e32 v140, v140
	s_nop 0
	v_readlane_b32 s6, v140, 63
	s_nop 1
	v_pk_mul_f32 v[198:199], v[198:199], s[6:7] op_sel_hi:[1,0]
	v_pk_mul_f32 v[200:201], v[200:201], s[6:7] op_sel_hi:[1,0]
	v_pk_mul_f32 v[202:203], v[202:203], s[6:7] op_sel_hi:[1,0]
	v_pk_mul_f32 v[204:205], v[204:205], s[6:7] op_sel_hi:[1,0]
	v_pk_mul_f32 v[206:207], v[206:207], s[6:7] op_sel_hi:[1,0]
	v_pk_mul_f32 v[208:209], v[208:209], s[6:7] op_sel_hi:[1,0]
	v_pk_mul_f32 v[210:211], v[210:211], s[6:7] op_sel_hi:[1,0]
	v_pk_mul_f32 v[212:213], v[212:213], s[6:7] op_sel_hi:[1,0]
	v_pk_mul_f32 v[198:199], v[16:17], v[198:199]
	v_pk_mul_f32 v[200:201], v[18:19], v[200:201]
	v_pk_mul_f32 v[202:203], v[20:21], v[202:203]
	v_pk_mul_f32 v[204:205], v[22:23], v[204:205]
	v_pk_mul_f32 v[206:207], v[24:25], v[206:207]
	v_pk_mul_f32 v[208:209], v[26:27], v[208:209]
	v_pk_mul_f32 v[210:211], v[28:29], v[210:211]
	v_pk_mul_f32 v[212:213], v[30:31], v[212:213]
	v_pk_fma_f32 v[198:199], v[32:33], v[198:199], v[48:49]
	v_pk_fma_f32 v[200:201], v[34:35], v[200:201], v[50:51]
	v_pk_fma_f32 v[202:203], v[36:37], v[202:203], v[52:53]
	v_pk_fma_f32 v[204:205], v[38:39], v[204:205], v[54:55]
	v_pk_fma_f32 v[206:207], v[40:41], v[206:207], v[56:57]
	v_pk_fma_f32 v[208:209], v[42:43], v[208:209], v[58:59]
	v_pk_fma_f32 v[210:211], v[44:45], v[210:211], v[60:61]
	v_pk_fma_f32 v[212:213], v[46:47], v[212:213], v[62:63]
	v_cvt_pk_bf16_f32 v230, v198, v199
	v_cvt_pk_bf16_f32 v231, v200, v201
	v_cvt_pk_bf16_f32 v232, v202, v203
	v_cvt_pk_bf16_f32 v233, v204, v205
	v_cvt_pk_bf16_f32 v234, v206, v207
	v_cvt_pk_bf16_f32 v235, v208, v209
	v_cvt_pk_bf16_f32 v236, v210, v211
	v_cvt_pk_bf16_f32 v237, v212, v213
	global_store_dwordx4 v184, v[230:233], s[44:45] offset:-4096 sc1
	global_store_dwordx4 v184, v[234:237], s[44:45] offset:-3072 sc1
	s_waitcnt vmcnt(16)
; __device__ __forceinline__ float bf_lo(unsigned w) { return __uint_as_float(w << 16); }
; __device__ __forceinline__ float bf_hi(unsigned w) { return __uint_as_float(w & 0xffff0000u); }
; __device__ __forceinline__ unsigned pkh2(float lo, float hi) { return (unsigned)__builtin_bit_cast(unsigned short, (_Float16)lo) | ((unsigned)__builtin_bit_cast(unsigned short, (_Float16)hi) << 16); }
; template <int R, bool SRCB> ...
;     ...
;         for (int r = 0; r < R; ++r) {
;             f32x4 y[2][2]; float ss = 0.f;
; #pragma unroll
;             for (int j = 0; j < 2; ++j) { const u32x4 t = yr[r][j];
;                 y[j][0] = (f32x4){bf_lo(t.x), bf_hi(t.x), bf_lo(t.y), bf_hi(t.y)}; y[j][1] = (f32x4){bf_lo(t.z), bf_hi(t.z), bf_lo(t.w), bf_hi(t.w)};
;                 if (R == 1 && YP) {
; #pragma unroll
;                     for (int k = 0; k < 2; ++k) { const float* pp = YP + (size_t)(row0 - M_LAT) * DM + 8 * lane + 512 * j + 4 * k; f32x4 s = *(const f32x4*)pp;
; #pragma unroll
;                         for (int q = 1; q < pg8::NSL; ++q) s = s + *(const f32x4*)(pp + (size_t)q * 2048 * DM);
;                         y[j][k] = s; } }
; #pragma unroll
;                 for (int k = 0; k < 2; ++k) ss += (y[j][k][0] * y[j][k][0] + y[j][k][1] * y[j][k][1]) + (y[j][k][2] * y[j][k][2] + y[j][k][3] * y[j][k][3]); }
;             const float rr = __builtin_amdgcn_rsqf(wave_sum(ss) * (1.0f / DM) + 1e-6f) * w;
; #pragma unroll
;             for (int j = 0; j < 2; ++j)
; #pragma unroll
;                 for (int k = 0; k < 2; ++k) h[r][j][k] = h[r][j][k] + gg[j][k] * (y[j][k] * rr);
;         }
;     }
; #pragma unroll
;     for (int r = 0; r < R; ++r)
; #pragma unroll
;         for (int j = 0; j < 2; ++j) { const int c = 8 * lane + 512 * j;
;             if (final_out) { *(f32x4*)(final_out + (size_t)(row0 + r) * DM + c) = h[r][j][0]; *(f32x4*)(final_out + (size_t)(row0 + r) * DM + c + 4) = h[r][j][1]; }
;             else { u32x4 t; t.x = pkh2(h[r][j][0][0], h[r][j][0][1]); t.y = pkh2(h[r][j][0][2], h[r][j][0][3]); t.z = pkh2(h[r][j][1][0], h[r][j][1][1]); t.w = pkh2(h[r][j][1][2], h[r][j][1][3]);
;                 *(u32x4*)(hout + (size_t)(row0 + r) * DM + c) = t; } }
	v_lshlrev_b32_e32 v116, 16, v156
	v_and_b32_e32 v117, 0xffff0000, v156
	v_lshlrev_b32_e32 v118, 16, v157
	v_and_b32_e32 v119, 0xffff0000, v157
	v_lshlrev_b32_e32 v120, 16, v158
	v_and_b32_e32 v121, 0xffff0000, v158
	v_lshlrev_b32_e32 v122, 16, v159
	v_and_b32_e32 v123, 0xffff0000, v159
	v_lshlrev_b32_e32 v124, 16, v160
	v_and_b32_e32 v125, 0xffff0000, v160
	v_lshlrev_b32_e32 v126, 16, v161
	v_and_b32_e32 v127, 0xffff0000, v161
	v_lshlrev_b32_e32 v128, 16, v162
	v_and_b32_e32 v129, 0xffff0000, v162
	v_lshlrev_b32_e32 v130, 16, v163
	v_and_b32_e32 v131, 0xffff0000, v163
	v_cvt_f32_f16_e32 v198, v72
	v_cvt_f32_f16_sdwa v199, v72 dst_sel:DWORD dst_unused:UNUSED_PAD src0_sel:WORD_1
	v_cvt_f32_f16_e32 v200, v73
	v_cvt_f32_f16_sdwa v201, v73 dst_sel:DWORD dst_unused:UNUSED_PAD src0_sel:WORD_1
	v_cvt_f32_f16_e32 v202, v74
	v_cvt_f32_f16_sdwa v203, v74 dst_sel:DWORD dst_unused:UNUSED_PAD src0_sel:WORD_1
	v_cvt_f32_f16_e32 v204, v75
	v_cvt_f32_f16_sdwa v205, v75 dst_sel:DWORD dst_unused:UNUSED_PAD src0_sel:WORD_1
	v_cvt_f32_f16_e32 v206, v76
	v_cvt_f32_f16_sdwa v207, v76 dst_sel:DWORD dst_unused:UNUSED_PAD src0_sel:WORD_1
	v_cvt_f32_f16_e32 v208, v77
	v_cvt_f32_f16_sdwa v209, v77 dst_sel:DWORD dst_unused:UNUSED_PAD src0_sel:WORD_1
	v_cvt_f32_f16_e32 v210, v78
	v_cvt_f32_f16_sdwa v211, v78 dst_sel:DWORD dst_unused:UNUSED_PAD src0_sel:WORD_1
	v_cvt_f32_f16_e32 v212, v79
	v_cvt_f32_f16_sdwa v213, v79 dst_sel:DWORD dst_unused:UNUSED_PAD src0_sel:WORD_1
	global_load_dwordx4 v[72:75], v185, s[42:43] offset:-2048
	global_load_dwordx4 v[76:79], v185, s[42:43] offset:-1024
	global_load_dwordx4 v[156:159], v185, s[44:45] offset:-2048
	global_load_dwordx4 v[160:163], v185, s[44:45] offset:-1024
	v_pk_mul_f32 v[140:141], v[116:117], v[116:117]
	v_pk_fma_f32 v[140:141], v[118:119], v[118:119], v[140:141]
	v_pk_fma_f32 v[140:141], v[120:121], v[120:121], v[140:141]
	v_pk_fma_f32 v[140:141], v[122:123], v[122:123], v[140:141]
	v_pk_fma_f32 v[140:141], v[124:125], v[124:125], v[140:141]
	v_pk_fma_f32 v[140:141], v[126:127], v[126:127], v[140:141]
	v_pk_fma_f32 v[140:141], v[128:129], v[128:129], v[140:141]
	v_pk_fma_f32 v[140:141], v[130:131], v[130:131], v[140:141]
	v_add_f32_e32 v140, v140, v141
	s_nop 1
	v_add_f32_dpp v140, v140, v140 quad_perm:[1,0,3,2] row_mask:0xf bank_mask:0xf
	s_nop 1
	v_add_f32_dpp v140, v140, v140 quad_perm:[2,3,0,1] row_mask:0xf bank_mask:0xf
	s_nop 1
	v_add_f32_dpp v140, v140, v140 row_ror:4 row_mask:0xf bank_mask:0xf
	s_nop 1
	v_add_f32_dpp v140, v140, v140 row_ror:8 row_mask:0xf bank_mask:0xf
	s_nop 1
	v_add_f32_dpp v140, v140, v140 row_bcast:15 row_mask:0xa bank_mask:0xf
	s_nop 1
	v_add_f32_dpp v140, v140, v140 row_bcast:31 row_mask:0xc bank_mask:0xf
	s_nop 1
	v_fmamk_f32 v140, v140, 0x3a800000, v224
	v_rsq_f32_e32 v140, v140
	s_nop 0
	v_mul_f32_e32 v140, v144, v140
	s_nop 0
	v_readlane_b32 s4, v140, 63
	s_nop 1
	v_pk_mul_f32 v[116:117], v[116:117], s[4:5] op_sel_hi:[1,0]
	v_pk_mul_f32 v[118:119], v[118:119], s[4:5] op_sel_hi:[1,0]
	v_pk_mul_f32 v[120:121], v[120:121], s[4:5] op_sel_hi:[1,0]
	v_pk_mul_f32 v[122:123], v[122:123], s[4:5] op_sel_hi:[1,0]
	v_pk_mul_f32 v[124:125], v[124:125], s[4:5] op_sel_hi:[1,0]
	v_pk_mul_f32 v[126:127], v[126:127], s[4:5] op_sel_hi:[1,0]
	v_pk_mul_f32 v[128:129], v[128:129], s[4:5] op_sel_hi:[1,0]
	v_pk_mul_f32 v[130:131], v[130:131], s[4:5] op_sel_hi:[1,0]
	v_pk_fma_f32 v[198:199], v[0:1], v[116:117], v[198:199]
	v_pk_fma_f32 v[200:201], v[2:3], v[118:119], v[200:201]
	v_pk_fma_f32 v[202:203], v[4:5], v[120:121], v[202:203]
	v_pk_fma_f32 v[204:205], v[6:7], v[122:123], v[204:205]
	v_pk_fma_f32 v[206:207], v[8:9], v[124:125], v[206:207]
	v_pk_fma_f32 v[208:209], v[10:11], v[126:127], v[208:209]
	v_pk_fma_f32 v[210:211], v[12:13], v[128:129], v[210:211]
	v_pk_fma_f32 v[212:213], v[14:15], v[130:131], v[212:213]
	v_cvt_f16_f32_e32 v132, v198
	v_cvt_f16_f32_e32 v133, v200
	v_cvt_f16_f32_e32 v134, v202
	v_cvt_f16_f32_e32 v135, v204
	v_cvt_f16_f32_e32 v136, v206
	v_cvt_f16_f32_e32 v137, v208
	v_cvt_f16_f32_e32 v138, v210
	v_cvt_f16_f32_e32 v139, v212
	v_cvt_f16_f32_sdwa v132, v199 dst_sel:WORD_1 dst_unused:UNUSED_PRESERVE src0_sel:DWORD
	v_cvt_f16_f32_sdwa v133, v201 dst_sel:WORD_1 dst_unused:UNUSED_PRESERVE src0_sel:DWORD
	v_cvt_f16_f32_sdwa v134, v203 dst_sel:WORD_1 dst_unused:UNUSED_PRESERVE src0_sel:DWORD
	v_cvt_f16_f32_sdwa v135, v205 dst_sel:WORD_1 dst_unused:UNUSED_PRESERVE src0_sel:DWORD
	v_cvt_f16_f32_sdwa v136, v207 dst_sel:WORD_1 dst_unused:UNUSED_PRESERVE src0_sel:DWORD
	v_cvt_f16_f32_sdwa v137, v209 dst_sel:WORD_1 dst_unused:UNUSED_PRESERVE src0_sel:DWORD
	v_cvt_f16_f32_sdwa v138, v211 dst_sel:WORD_1 dst_unused:UNUSED_PRESERVE src0_sel:DWORD
	v_cvt_f16_f32_sdwa v139, v213 dst_sel:WORD_1 dst_unused:UNUSED_PRESERVE src0_sel:DWORD
	s_nop 0
	global_store_dwordx4 v184, v[132:135], s[42:43] offset:-2048 sc1
	global_store_dwordx4 v184, v[136:139], s[42:43] offset:-1024 sc1
	v_pk_mul_f32 v[140:141], v[198:199], v[198:199]
	v_pk_fma_f32 v[140:141], v[200:201], v[200:201], v[140:141]
	v_pk_fma_f32 v[140:141], v[202:203], v[202:203], v[140:141]
	v_pk_fma_f32 v[140:141], v[204:205], v[204:205], v[140:141]
	v_pk_fma_f32 v[140:141], v[206:207], v[206:207], v[140:141]
	v_pk_fma_f32 v[140:141], v[208:209], v[208:209], v[140:141]
	v_pk_fma_f32 v[140:141], v[210:211], v[210:211], v[140:141]
	v_pk_fma_f32 v[140:141], v[212:213], v[212:213], v[140:141]
	v_add_f32_e32 v140, v140, v141
	s_nop 1
	v_add_f32_dpp v140, v140, v140 quad_perm:[1,0,3,2] row_mask:0xf bank_mask:0xf
	s_nop 1
	v_add_f32_dpp v140, v140, v140 quad_perm:[2,3,0,1] row_mask:0xf bank_mask:0xf
	s_nop 1
	v_add_f32_dpp v140, v140, v140 row_ror:4 row_mask:0xf bank_mask:0xf
; __device__ __forceinline__ unsigned pk2(float lo, float hi) { return pg8::cvt_pk_bf16(lo, hi); }
; __device__ __forceinline__ float bf_lo(unsigned w) { return __uint_as_float(w << 16); }
; __device__ __forceinline__ float bf_hi(unsigned w) { return __uint_as_float(w & 0xffff0000u); }
; template <int R, bool SRCB> ...
;     ...
;         for (int r = 0; r < R; ++r) {
;             f32x4 y[2][2]; float ss = 0.f;
; #pragma unroll
;             for (int j = 0; j < 2; ++j) { const u32x4 t = yr[r][j];
;                 y[j][0] = (f32x4){bf_lo(t.x), bf_hi(t.x), bf_lo(t.y), bf_hi(t.y)}; y[j][1] = (f32x4){bf_lo(t.z), bf_hi(t.z), bf_lo(t.w), bf_hi(t.w)};
;                 if (R == 1 && YP) {
; #pragma unroll
;                     for (int k = 0; k < 2; ++k) { const float* pp = YP + (size_t)(row0 - M_LAT) * DM + 8 * lane + 512 * j + 4 * k; f32x4 s = *(const f32x4*)pp;
; #pragma unroll
;                         for (int q = 1; q < pg8::NSL; ++q) s = s + *(const f32x4*)(pp + (size_t)q * 2048 * DM);
;                         y[j][k] = s; } }
; #pragma unroll
;                 for (int k = 0; k < 2; ++k) ss += (y[j][k][0] * y[j][k][0] + y[j][k][1] * y[j][k][1]) + (y[j][k][2] * y[j][k][2] + y[j][k][3] * y[j][k][3]); }
;             const float rr = __builtin_amdgcn_rsqf(wave_sum(ss) * (1.0f / DM) + 1e-6f) * w;
; #pragma unroll
;             for (int j = 0; j < 2; ++j)
; #pragma unroll
;                 for (int k = 0; k < 2; ++k) h[r][j][k] = h[r][j][k] + gg[j][k] * (y[j][k] * rr);
;     ...
;         for (int r = 0; r < R; ++r) {
;             float ss = 0.f;
; #pragma unroll
;             for (int j = 0; j < 2; ++j)
; #pragma unroll
;                 for (int k = 0; k < 2; ++k) ss += (h[r][j][k][0] * h[r][j][k][0] + h[r][j][k][1] * h[r][j][k][1]) + (h[r][j][k][2] * h[r][j][k][2] + h[r][j][k][3] * h[r][j][k][3]);
;             const float rr = __builtin_amdgcn_rsqf(wave_sum(ss) * (1.0f / DM) + 1e-6f);
; #pragma unroll
;             for (int j = 0; j < 2; ++j) { const f32x4 v0 = (h[r][j][0] * rr * gp[j][0]) * sc1[j][0] + sh[j][0], v1 = (h[r][j][1] * rr * gp[j][1]) * sc1[j][1] + sh[j][1];
;                 u32x4 t; t.x = pk2(v0[0], v0[1]); t.y = pk2(v0[2], v0[3]); t.z = pk2(v1[0], v1[1]); t.w = pk2(v1[2], v1[3]);
;                 *(u32x4*)(U + (size_t)(row0 + r) * DM + 8 * lane + 512 * j) = t; }
	s_nop 1
	v_add_f32_dpp v140, v140, v140 row_ror:8 row_mask:0xf bank_mask:0xf
	s_nop 1
	v_add_f32_dpp v140, v140, v140 row_bcast:15 row_mask:0xa bank_mask:0xf
	s_nop 1
	v_add_f32_dpp v140, v140, v140 row_bcast:31 row_mask:0xc bank_mask:0xf
	s_nop 1
	v_fmamk_f32 v140, v140, 0x3a800000, v224
	v_rsq_f32_e32 v140, v140
	s_nop 0
	v_readlane_b32 s6, v140, 63
	s_nop 1
	v_pk_mul_f32 v[198:199], v[198:199], s[6:7] op_sel_hi:[1,0]
	v_pk_mul_f32 v[200:201], v[200:201], s[6:7] op_sel_hi:[1,0]
	v_pk_mul_f32 v[202:203], v[202:203], s[6:7] op_sel_hi:[1,0]
	v_pk_mul_f32 v[204:205], v[204:205], s[6:7] op_sel_hi:[1,0]
	v_pk_mul_f32 v[206:207], v[206:207], s[6:7] op_sel_hi:[1,0]
	v_pk_mul_f32 v[208:209], v[208:209], s[6:7] op_sel_hi:[1,0]
	v_pk_mul_f32 v[210:211], v[210:211], s[6:7] op_sel_hi:[1,0]
	v_pk_mul_f32 v[212:213], v[212:213], s[6:7] op_sel_hi:[1,0]
	v_pk_mul_f32 v[198:199], v[16:17], v[198:199]
	v_pk_mul_f32 v[200:201], v[18:19], v[200:201]
	v_pk_mul_f32 v[202:203], v[20:21], v[202:203]
	v_pk_mul_f32 v[204:205], v[22:23], v[204:205]
	v_pk_mul_f32 v[206:207], v[24:25], v[206:207]
	v_pk_mul_f32 v[208:209], v[26:27], v[208:209]
	v_pk_mul_f32 v[210:211], v[28:29], v[210:211]
	v_pk_mul_f32 v[212:213], v[30:31], v[212:213]
	v_pk_fma_f32 v[198:199], v[32:33], v[198:199], v[48:49]
	v_pk_fma_f32 v[200:201], v[34:35], v[200:201], v[50:51]
	v_pk_fma_f32 v[202:203], v[36:37], v[202:203], v[52:53]
	v_pk_fma_f32 v[204:205], v[38:39], v[204:205], v[54:55]
	v_pk_fma_f32 v[206:207], v[40:41], v[206:207], v[56:57]
	v_pk_fma_f32 v[208:209], v[42:43], v[208:209], v[58:59]
	v_pk_fma_f32 v[210:211], v[44:45], v[210:211], v[60:61]
	v_pk_fma_f32 v[212:213], v[46:47], v[212:213], v[62:63]
	v_cvt_pk_bf16_f32 v230, v198, v199
	v_cvt_pk_bf16_f32 v231, v200, v201
	v_cvt_pk_bf16_f32 v232, v202, v203
	v_cvt_pk_bf16_f32 v233, v204, v205
	v_cvt_pk_bf16_f32 v234, v206, v207
	v_cvt_pk_bf16_f32 v235, v208, v209
	v_cvt_pk_bf16_f32 v236, v210, v211
	v_cvt_pk_bf16_f32 v237, v212, v213
	global_store_dwordx4 v184, v[230:233], s[44:45] offset:-2048 sc1
	global_store_dwordx4 v184, v[234:237], s[44:45] offset:-1024 sc1
	s_waitcnt vmcnt(20)
	v_lshlrev_b32_e32 v116, 16, v164
	v_and_b32_e32 v117, 0xffff0000, v164
	v_lshlrev_b32_e32 v118, 16, v165
	v_and_b32_e32 v119, 0xffff0000, v165
	v_lshlrev_b32_e32 v120, 16, v166
	v_and_b32_e32 v121, 0xffff0000, v166
	v_lshlrev_b32_e32 v122, 16, v167
	v_and_b32_e32 v123, 0xffff0000, v167
	v_lshlrev_b32_e32 v124, 16, v168
	v_and_b32_e32 v125, 0xffff0000, v168
	v_lshlrev_b32_e32 v126, 16, v169
	v_and_b32_e32 v127, 0xffff0000, v169
	v_lshlrev_b32_e32 v128, 16, v170
	v_and_b32_e32 v129, 0xffff0000, v170
	v_lshlrev_b32_e32 v130, 16, v171
	v_and_b32_e32 v131, 0xffff0000, v171
	v_cvt_f32_f16_e32 v198, v80
	v_cvt_f32_f16_sdwa v199, v80 dst_sel:DWORD dst_unused:UNUSED_PAD src0_sel:WORD_1
	v_cvt_f32_f16_e32 v200, v81
	v_cvt_f32_f16_sdwa v201, v81 dst_sel:DWORD dst_unused:UNUSED_PAD src0_sel:WORD_1
	v_cvt_f32_f16_e32 v202, v82
	v_cvt_f32_f16_sdwa v203, v82 dst_sel:DWORD dst_unused:UNUSED_PAD src0_sel:WORD_1
	v_cvt_f32_f16_e32 v204, v83
	v_cvt_f32_f16_sdwa v205, v83 dst_sel:DWORD dst_unused:UNUSED_PAD src0_sel:WORD_1
	v_cvt_f32_f16_e32 v206, v84
	v_cvt_f32_f16_sdwa v207, v84 dst_sel:DWORD dst_unused:UNUSED_PAD src0_sel:WORD_1
	v_cvt_f32_f16_e32 v208, v85
	v_cvt_f32_f16_sdwa v209, v85 dst_sel:DWORD dst_unused:UNUSED_PAD src0_sel:WORD_1
	v_cvt_f32_f16_e32 v210, v86
	v_cvt_f32_f16_sdwa v211, v86 dst_sel:DWORD dst_unused:UNUSED_PAD src0_sel:WORD_1
	v_cvt_f32_f16_e32 v212, v87
	v_cvt_f32_f16_sdwa v213, v87 dst_sel:DWORD dst_unused:UNUSED_PAD src0_sel:WORD_1
	global_load_dwordx4 v[80:83], v185, s[42:43] offset:0
	global_load_dwordx4 v[84:87], v185, s[42:43] offset:1024
	global_load_dwordx4 v[164:167], v185, s[44:45] offset:0
	global_load_dwordx4 v[168:171], v185, s[44:45] offset:1024
	v_pk_mul_f32 v[140:141], v[116:117], v[116:117]
	v_pk_fma_f32 v[140:141], v[118:119], v[118:119], v[140:141]
	v_pk_fma_f32 v[140:141], v[120:121], v[120:121], v[140:141]
	v_pk_fma_f32 v[140:141], v[122:123], v[122:123], v[140:141]
	v_pk_fma_f32 v[140:141], v[124:125], v[124:125], v[140:141]
	v_pk_fma_f32 v[140:141], v[126:127], v[126:127], v[140:141]
	v_pk_fma_f32 v[140:141], v[128:129], v[128:129], v[140:141]
	v_pk_fma_f32 v[140:141], v[130:131], v[130:131], v[140:141]
	v_add_f32_e32 v140, v140, v141
	s_nop 1
	v_add_f32_dpp v140, v140, v140 quad_perm:[1,0,3,2] row_mask:0xf bank_mask:0xf
	s_nop 1
	v_add_f32_dpp v140, v140, v140 quad_perm:[2,3,0,1] row_mask:0xf bank_mask:0xf
	s_nop 1
	v_add_f32_dpp v140, v140, v140 row_ror:4 row_mask:0xf bank_mask:0xf
	s_nop 1
	v_add_f32_dpp v140, v140, v140 row_ror:8 row_mask:0xf bank_mask:0xf
	s_nop 1
	v_add_f32_dpp v140, v140, v140 row_bcast:15 row_mask:0xa bank_mask:0xf
	s_nop 1
	v_add_f32_dpp v140, v140, v140 row_bcast:31 row_mask:0xc bank_mask:0xf
	s_nop 1
	v_fmamk_f32 v140, v140, 0x3a800000, v224
	v_rsq_f32_e32 v140, v140
	s_nop 0
	v_mul_f32_e32 v140, v144, v140
	s_nop 0
	v_readlane_b32 s4, v140, 63
	s_nop 1
	v_pk_mul_f32 v[116:117], v[116:117], s[4:5] op_sel_hi:[1,0]
	v_pk_mul_f32 v[118:119], v[118:119], s[4:5] op_sel_hi:[1,0]
	v_pk_mul_f32 v[120:121], v[120:121], s[4:5] op_sel_hi:[1,0]
	v_pk_mul_f32 v[122:123], v[122:123], s[4:5] op_sel_hi:[1,0]
	v_pk_mul_f32 v[124:125], v[124:125], s[4:5] op_sel_hi:[1,0]
	v_pk_mul_f32 v[126:127], v[126:127], s[4:5] op_sel_hi:[1,0]
	v_pk_mul_f32 v[128:129], v[128:129], s[4:5] op_sel_hi:[1,0]
	v_pk_mul_f32 v[130:131], v[130:131], s[4:5] op_sel_hi:[1,0]
	v_pk_fma_f32 v[198:199], v[0:1], v[116:117], v[198:199]
	v_pk_fma_f32 v[200:201], v[2:3], v[118:119], v[200:201]
	v_pk_fma_f32 v[202:203], v[4:5], v[120:121], v[202:203]
; __device__ __forceinline__ unsigned pk2(float lo, float hi) { return pg8::cvt_pk_bf16(lo, hi); }
; __device__ __forceinline__ unsigned pkh2(float lo, float hi) { return (unsigned)__builtin_bit_cast(unsigned short, (_Float16)lo) | ((unsigned)__builtin_bit_cast(unsigned short, (_Float16)hi) << 16); }
; template <int R, bool SRCB> ...
;     ...
;         for (int j = 0; j < 2; ++j) { const int c = 8 * lane + 512 * j;
;             if (final_out) { *(f32x4*)(final_out + (size_t)(row0 + r) * DM + c) = h[r][j][0]; *(f32x4*)(final_out + (size_t)(row0 + r) * DM + c + 4) = h[r][j][1]; }
;             else { u32x4 t; t.x = pkh2(h[r][j][0][0], h[r][j][0][1]); t.y = pkh2(h[r][j][0][2], h[r][j][0][3]); t.z = pkh2(h[r][j][1][0], h[r][j][1][1]); t.w = pkh2(h[r][j][1][2], h[r][j][1][3]);
;                 *(u32x4*)(hout + (size_t)(row0 + r) * DM + c) = t; } }
;     if (U) {
;         f32x4 gp[2][2], sc1[2][2], sh[2][2];
; #pragma unroll
;         for (int j = 0; j < 2; ++j)
; #pragma unroll
;             for (int k = 0; k < 2; ++k) { const int c = 8 * lane + 512 * j + 4 * k; gp[j][k] = *(const f32x4*)(gpre + c); sc1[j][k] = *(const f32x4*)(scale + (size_t)mrow * 9216 + c) + 1.0f; sh[j][k] = *(const f32x4*)(shift + (size_t)mrow * 9216 + c); }
; #pragma unroll
;         for (int r = 0; r < R; ++r) {
;             float ss = 0.f;
; #pragma unroll
;             for (int j = 0; j < 2; ++j)
; #pragma unroll
;                 for (int k = 0; k < 2; ++k) ss += (h[r][j][k][0] * h[r][j][k][0] + h[r][j][k][1] * h[r][j][k][1]) + (h[r][j][k][2] * h[r][j][k][2] + h[r][j][k][3] * h[r][j][k][3]);
;             const float rr = __builtin_amdgcn_rsqf(wave_sum(ss) * (1.0f / DM) + 1e-6f);
; #pragma unroll
;             for (int j = 0; j < 2; ++j) { const f32x4 v0 = (h[r][j][0] * rr * gp[j][0]) * sc1[j][0] + sh[j][0], v1 = (h[r][j][1] * rr * gp[j][1]) * sc1[j][1] + sh[j][1];
;                 u32x4 t; t.x = pk2(v0[0], v0[1]); t.y = pk2(v0[2], v0[3]); t.z = pk2(v1[0], v1[1]); t.w = pk2(v1[2], v1[3]);
;                 *(u32x4*)(U + (size_t)(row0 + r) * DM + 8 * lane + 512 * j) = t; }
	v_pk_fma_f32 v[204:205], v[6:7], v[122:123], v[204:205]
	v_pk_fma_f32 v[206:207], v[8:9], v[124:125], v[206:207]
	v_pk_fma_f32 v[208:209], v[10:11], v[126:127], v[208:209]
	v_pk_fma_f32 v[210:211], v[12:13], v[128:129], v[210:211]
	v_pk_fma_f32 v[212:213], v[14:15], v[130:131], v[212:213]
	v_cvt_f16_f32_e32 v132, v198
	v_cvt_f16_f32_e32 v133, v200
	v_cvt_f16_f32_e32 v134, v202
	v_cvt_f16_f32_e32 v135, v204
	v_cvt_f16_f32_e32 v136, v206
	v_cvt_f16_f32_e32 v137, v208
	v_cvt_f16_f32_e32 v138, v210
	v_cvt_f16_f32_e32 v139, v212
	v_cvt_f16_f32_sdwa v132, v199 dst_sel:WORD_1 dst_unused:UNUSED_PRESERVE src0_sel:DWORD
	v_cvt_f16_f32_sdwa v133, v201 dst_sel:WORD_1 dst_unused:UNUSED_PRESERVE src0_sel:DWORD
	v_cvt_f16_f32_sdwa v134, v203 dst_sel:WORD_1 dst_unused:UNUSED_PRESERVE src0_sel:DWORD
	v_cvt_f16_f32_sdwa v135, v205 dst_sel:WORD_1 dst_unused:UNUSED_PRESERVE src0_sel:DWORD
	v_cvt_f16_f32_sdwa v136, v207 dst_sel:WORD_1 dst_unused:UNUSED_PRESERVE src0_sel:DWORD
	v_cvt_f16_f32_sdwa v137, v209 dst_sel:WORD_1 dst_unused:UNUSED_PRESERVE src0_sel:DWORD
	v_cvt_f16_f32_sdwa v138, v211 dst_sel:WORD_1 dst_unused:UNUSED_PRESERVE src0_sel:DWORD
	v_cvt_f16_f32_sdwa v139, v213 dst_sel:WORD_1 dst_unused:UNUSED_PRESERVE src0_sel:DWORD
	s_nop 0
	global_store_dwordx4 v184, v[132:135], s[42:43] offset:0 sc1
	global_store_dwordx4 v184, v[136:139], s[42:43] offset:1024 sc1
	v_pk_mul_f32 v[140:141], v[198:199], v[198:199]
	v_pk_fma_f32 v[140:141], v[200:201], v[200:201], v[140:141]
	v_pk_fma_f32 v[140:141], v[202:203], v[202:203], v[140:141]
	v_pk_fma_f32 v[140:141], v[204:205], v[204:205], v[140:141]
	v_pk_fma_f32 v[140:141], v[206:207], v[206:207], v[140:141]
	v_pk_fma_f32 v[140:141], v[208:209], v[208:209], v[140:141]
	v_pk_fma_f32 v[140:141], v[210:211], v[210:211], v[140:141]
	v_pk_fma_f32 v[140:141], v[212:213], v[212:213], v[140:141]
	v_add_f32_e32 v140, v140, v141
	s_nop 1
	v_add_f32_dpp v140, v140, v140 quad_perm:[1,0,3,2] row_mask:0xf bank_mask:0xf
	s_nop 1
	v_add_f32_dpp v140, v140, v140 quad_perm:[2,3,0,1] row_mask:0xf bank_mask:0xf
	s_nop 1
	v_add_f32_dpp v140, v140, v140 row_ror:4 row_mask:0xf bank_mask:0xf
	s_nop 1
	v_add_f32_dpp v140, v140, v140 row_ror:8 row_mask:0xf bank_mask:0xf
	s_nop 1
	v_add_f32_dpp v140, v140, v140 row_bcast:15 row_mask:0xa bank_mask:0xf
	s_nop 1
	v_add_f32_dpp v140, v140, v140 row_bcast:31 row_mask:0xc bank_mask:0xf
	s_nop 1
	v_fmamk_f32 v140, v140, 0x3a800000, v224
	v_rsq_f32_e32 v140, v140
	s_nop 0
	v_readlane_b32 s6, v140, 63
	s_nop 1
	v_pk_mul_f32 v[198:199], v[198:199], s[6:7] op_sel_hi:[1,0]
	v_pk_mul_f32 v[200:201], v[200:201], s[6:7] op_sel_hi:[1,0]
	v_pk_mul_f32 v[202:203], v[202:203], s[6:7] op_sel_hi:[1,0]
	v_pk_mul_f32 v[204:205], v[204:205], s[6:7] op_sel_hi:[1,0]
	v_pk_mul_f32 v[206:207], v[206:207], s[6:7] op_sel_hi:[1,0]
	v_pk_mul_f32 v[208:209], v[208:209], s[6:7] op_sel_hi:[1,0]
	v_pk_mul_f32 v[210:211], v[210:211], s[6:7] op_sel_hi:[1,0]
	v_pk_mul_f32 v[212:213], v[212:213], s[6:7] op_sel_hi:[1,0]
	v_pk_mul_f32 v[198:199], v[16:17], v[198:199]
	v_pk_mul_f32 v[200:201], v[18:19], v[200:201]
	v_pk_mul_f32 v[202:203], v[20:21], v[202:203]
	v_pk_mul_f32 v[204:205], v[22:23], v[204:205]
	v_pk_mul_f32 v[206:207], v[24:25], v[206:207]
	v_pk_mul_f32 v[208:209], v[26:27], v[208:209]
	v_pk_mul_f32 v[210:211], v[28:29], v[210:211]
	v_pk_mul_f32 v[212:213], v[30:31], v[212:213]
	v_pk_fma_f32 v[198:199], v[32:33], v[198:199], v[48:49]
	v_pk_fma_f32 v[200:201], v[34:35], v[200:201], v[50:51]
	v_pk_fma_f32 v[202:203], v[36:37], v[202:203], v[52:53]
	v_pk_fma_f32 v[204:205], v[38:39], v[204:205], v[54:55]
	v_pk_fma_f32 v[206:207], v[40:41], v[206:207], v[56:57]
	v_pk_fma_f32 v[208:209], v[42:43], v[208:209], v[58:59]
	v_pk_fma_f32 v[210:211], v[44:45], v[210:211], v[60:61]
	v_pk_fma_f32 v[212:213], v[46:47], v[212:213], v[62:63]
	v_cvt_pk_bf16_f32 v230, v198, v199
	v_cvt_pk_bf16_f32 v231, v200, v201
	v_cvt_pk_bf16_f32 v232, v202, v203
	v_cvt_pk_bf16_f32 v233, v204, v205
	v_cvt_pk_bf16_f32 v234, v206, v207
	v_cvt_pk_bf16_f32 v235, v208, v209
	v_cvt_pk_bf16_f32 v236, v210, v211
	v_cvt_pk_bf16_f32 v237, v212, v213
	global_store_dwordx4 v184, v[230:233], s[44:45] offset:0 sc1
	global_store_dwordx4 v184, v[234:237], s[44:45] offset:1024 sc1
	s_waitcnt vmcnt(24)
; __device__ __forceinline__ float bf_lo(unsigned w) { return __uint_as_float(w << 16); }
; __device__ __forceinline__ float bf_hi(unsigned w) { return __uint_as_float(w & 0xffff0000u); }
; __device__ __forceinline__ unsigned pkh2(float lo, float hi) { return (unsigned)__builtin_bit_cast(unsigned short, (_Float16)lo) | ((unsigned)__builtin_bit_cast(unsigned short, (_Float16)hi) << 16); }
; template <int R, bool SRCB> ...
;     ...
;         for (int r = 0; r < R; ++r) {
;             f32x4 y[2][2]; float ss = 0.f;
; #pragma unroll
;             for (int j = 0; j < 2; ++j) { const u32x4 t = yr[r][j];
;                 y[j][0] = (f32x4){bf_lo(t.x), bf_hi(t.x), bf_lo(t.y), bf_hi(t.y)}; y[j][1] = (f32x4){bf_lo(t.z), bf_hi(t.z), bf_lo(t.w), bf_hi(t.w)};
;                 if (R == 1 && YP) {
; #pragma unroll
;                     for (int k = 0; k < 2; ++k) { const float* pp = YP + (size_t)(row0 - M_LAT) * DM + 8 * lane + 512 * j + 4 * k; f32x4 s = *(const f32x4*)pp;
; #pragma unroll
;                         for (int q = 1; q < pg8::NSL; ++q) s = s + *(const f32x4*)(pp + (size_t)q * 2048 * DM);
;                         y[j][k] = s; } }
; #pragma unroll
;                 for (int k = 0; k < 2; ++k) ss += (y[j][k][0] * y[j][k][0] + y[j][k][1] * y[j][k][1]) + (y[j][k][2] * y[j][k][2] + y[j][k][3] * y[j][k][3]); }
;             const float rr = __builtin_amdgcn_rsqf(wave_sum(ss) * (1.0f / DM) + 1e-6f) * w;
; #pragma unroll
;             for (int j = 0; j < 2; ++j)
; #pragma unroll
;                 for (int k = 0; k < 2; ++k) h[r][j][k] = h[r][j][k] + gg[j][k] * (y[j][k] * rr);
;         }
;     }
; #pragma unroll
;     for (int r = 0; r < R; ++r)
; #pragma unroll
;         for (int j = 0; j < 2; ++j) { const int c = 8 * lane + 512 * j;
;             if (final_out) { *(f32x4*)(final_out + (size_t)(row0 + r) * DM + c) = h[r][j][0]; *(f32x4*)(final_out + (size_t)(row0 + r) * DM + c + 4) = h[r][j][1]; }
;             else { u32x4 t; t.x = pkh2(h[r][j][0][0], h[r][j][0][1]); t.y = pkh2(h[r][j][0][2], h[r][j][0][3]); t.z = pkh2(h[r][j][1][0], h[r][j][1][1]); t.w = pkh2(h[r][j][1][2], h[r][j][1][3]);
;                 *(u32x4*)(hout + (size_t)(row0 + r) * DM + c) = t; } }
	v_lshlrev_b32_e32 v116, 16, v172
	v_and_b32_e32 v117, 0xffff0000, v172
	v_lshlrev_b32_e32 v118, 16, v173
	v_and_b32_e32 v119, 0xffff0000, v173
	v_lshlrev_b32_e32 v120, 16, v174
	v_and_b32_e32 v121, 0xffff0000, v174
	v_lshlrev_b32_e32 v122, 16, v175
	v_and_b32_e32 v123, 0xffff0000, v175
	v_lshlrev_b32_e32 v124, 16, v176
	v_and_b32_e32 v125, 0xffff0000, v176
	v_lshlrev_b32_e32 v126, 16, v177
	v_and_b32_e32 v127, 0xffff0000, v177
	v_lshlrev_b32_e32 v128, 16, v178
	v_and_b32_e32 v129, 0xffff0000, v178
	v_lshlrev_b32_e32 v130, 16, v179
	v_and_b32_e32 v131, 0xffff0000, v179
	v_cvt_f32_f16_e32 v198, v88
	v_cvt_f32_f16_sdwa v199, v88 dst_sel:DWORD dst_unused:UNUSED_PAD src0_sel:WORD_1
	v_cvt_f32_f16_e32 v200, v89
	v_cvt_f32_f16_sdwa v201, v89 dst_sel:DWORD dst_unused:UNUSED_PAD src0_sel:WORD_1
	v_cvt_f32_f16_e32 v202, v90
	v_cvt_f32_f16_sdwa v203, v90 dst_sel:DWORD dst_unused:UNUSED_PAD src0_sel:WORD_1
	v_cvt_f32_f16_e32 v204, v91
	v_cvt_f32_f16_sdwa v205, v91 dst_sel:DWORD dst_unused:UNUSED_PAD src0_sel:WORD_1
	v_cvt_f32_f16_e32 v206, v92
	v_cvt_f32_f16_sdwa v207, v92 dst_sel:DWORD dst_unused:UNUSED_PAD src0_sel:WORD_1
	v_cvt_f32_f16_e32 v208, v93
	v_cvt_f32_f16_sdwa v209, v93 dst_sel:DWORD dst_unused:UNUSED_PAD src0_sel:WORD_1
	v_cvt_f32_f16_e32 v210, v94
	v_cvt_f32_f16_sdwa v211, v94 dst_sel:DWORD dst_unused:UNUSED_PAD src0_sel:WORD_1
	v_cvt_f32_f16_e32 v212, v95
	v_cvt_f32_f16_sdwa v213, v95 dst_sel:DWORD dst_unused:UNUSED_PAD src0_sel:WORD_1
	global_load_dwordx4 v[88:91], v185, s[42:43] offset:2048
	global_load_dwordx4 v[92:95], v185, s[42:43] offset:3072
	global_load_dwordx4 v[172:175], v185, s[44:45] offset:2048
	global_load_dwordx4 v[176:179], v185, s[44:45] offset:3072
	v_pk_mul_f32 v[140:141], v[116:117], v[116:117]
	v_pk_fma_f32 v[140:141], v[118:119], v[118:119], v[140:141]
	v_pk_fma_f32 v[140:141], v[120:121], v[120:121], v[140:141]
	v_pk_fma_f32 v[140:141], v[122:123], v[122:123], v[140:141]
	v_pk_fma_f32 v[140:141], v[124:125], v[124:125], v[140:141]
	v_pk_fma_f32 v[140:141], v[126:127], v[126:127], v[140:141]
	v_pk_fma_f32 v[140:141], v[128:129], v[128:129], v[140:141]
	v_pk_fma_f32 v[140:141], v[130:131], v[130:131], v[140:141]
	v_add_f32_e32 v140, v140, v141
	s_nop 1
	v_add_f32_dpp v140, v140, v140 quad_perm:[1,0,3,2] row_mask:0xf bank_mask:0xf
	s_nop 1
	v_add_f32_dpp v140, v140, v140 quad_perm:[2,3,0,1] row_mask:0xf bank_mask:0xf
	s_nop 1
	v_add_f32_dpp v140, v140, v140 row_ror:4 row_mask:0xf bank_mask:0xf
	s_nop 1
	v_add_f32_dpp v140, v140, v140 row_ror:8 row_mask:0xf bank_mask:0xf
	s_nop 1
	v_add_f32_dpp v140, v140, v140 row_bcast:15 row_mask:0xa bank_mask:0xf
	s_nop 1
	v_add_f32_dpp v140, v140, v140 row_bcast:31 row_mask:0xc bank_mask:0xf
	s_nop 1
	v_fmamk_f32 v140, v140, 0x3a800000, v224
	v_rsq_f32_e32 v140, v140
	s_nop 0
	v_mul_f32_e32 v140, v144, v140
	s_nop 0
	v_readlane_b32 s4, v140, 63
	s_nop 1
	v_pk_mul_f32 v[116:117], v[116:117], s[4:5] op_sel_hi:[1,0]
	v_pk_mul_f32 v[118:119], v[118:119], s[4:5] op_sel_hi:[1,0]
	v_pk_mul_f32 v[120:121], v[120:121], s[4:5] op_sel_hi:[1,0]
	v_pk_mul_f32 v[122:123], v[122:123], s[4:5] op_sel_hi:[1,0]
	v_pk_mul_f32 v[124:125], v[124:125], s[4:5] op_sel_hi:[1,0]
	v_pk_mul_f32 v[126:127], v[126:127], s[4:5] op_sel_hi:[1,0]
	v_pk_mul_f32 v[128:129], v[128:129], s[4:5] op_sel_hi:[1,0]
	v_pk_mul_f32 v[130:131], v[130:131], s[4:5] op_sel_hi:[1,0]
	v_pk_fma_f32 v[198:199], v[0:1], v[116:117], v[198:199]
	v_pk_fma_f32 v[200:201], v[2:3], v[118:119], v[200:201]
	v_pk_fma_f32 v[202:203], v[4:5], v[120:121], v[202:203]
	v_pk_fma_f32 v[204:205], v[6:7], v[122:123], v[204:205]
	v_pk_fma_f32 v[206:207], v[8:9], v[124:125], v[206:207]
	v_pk_fma_f32 v[208:209], v[10:11], v[126:127], v[208:209]
	v_pk_fma_f32 v[210:211], v[12:13], v[128:129], v[210:211]
	v_pk_fma_f32 v[212:213], v[14:15], v[130:131], v[212:213]
	v_cvt_f16_f32_e32 v132, v198
	v_cvt_f16_f32_e32 v133, v200
	v_cvt_f16_f32_e32 v134, v202
	v_cvt_f16_f32_e32 v135, v204
	v_cvt_f16_f32_e32 v136, v206
	v_cvt_f16_f32_e32 v137, v208
	v_cvt_f16_f32_e32 v138, v210
	v_cvt_f16_f32_e32 v139, v212
	v_cvt_f16_f32_sdwa v132, v199 dst_sel:WORD_1 dst_unused:UNUSED_PRESERVE src0_sel:DWORD
	v_cvt_f16_f32_sdwa v133, v201 dst_sel:WORD_1 dst_unused:UNUSED_PRESERVE src0_sel:DWORD
	v_cvt_f16_f32_sdwa v134, v203 dst_sel:WORD_1 dst_unused:UNUSED_PRESERVE src0_sel:DWORD
	v_cvt_f16_f32_sdwa v135, v205 dst_sel:WORD_1 dst_unused:UNUSED_PRESERVE src0_sel:DWORD
	v_cvt_f16_f32_sdwa v136, v207 dst_sel:WORD_1 dst_unused:UNUSED_PRESERVE src0_sel:DWORD
	v_cvt_f16_f32_sdwa v137, v209 dst_sel:WORD_1 dst_unused:UNUSED_PRESERVE src0_sel:DWORD
	v_cvt_f16_f32_sdwa v138, v211 dst_sel:WORD_1 dst_unused:UNUSED_PRESERVE src0_sel:DWORD
	v_cvt_f16_f32_sdwa v139, v213 dst_sel:WORD_1 dst_unused:UNUSED_PRESERVE src0_sel:DWORD
	s_nop 0
	global_store_dwordx4 v184, v[132:135], s[42:43] offset:2048 sc1
	global_store_dwordx4 v184, v[136:139], s[42:43] offset:3072 sc1
	v_pk_mul_f32 v[140:141], v[198:199], v[198:199]
	v_pk_fma_f32 v[140:141], v[200:201], v[200:201], v[140:141]
	v_pk_fma_f32 v[140:141], v[202:203], v[202:203], v[140:141]
	v_pk_fma_f32 v[140:141], v[204:205], v[204:205], v[140:141]
	v_pk_fma_f32 v[140:141], v[206:207], v[206:207], v[140:141]
	v_pk_fma_f32 v[140:141], v[208:209], v[208:209], v[140:141]
	v_pk_fma_f32 v[140:141], v[210:211], v[210:211], v[140:141]
	v_pk_fma_f32 v[140:141], v[212:213], v[212:213], v[140:141]
	v_add_f32_e32 v140, v140, v141
	s_nop 1
	v_add_f32_dpp v140, v140, v140 quad_perm:[1,0,3,2] row_mask:0xf bank_mask:0xf
	s_nop 1
	v_add_f32_dpp v140, v140, v140 quad_perm:[2,3,0,1] row_mask:0xf bank_mask:0xf
	s_nop 1
	v_add_f32_dpp v140, v140, v140 row_ror:4 row_mask:0xf bank_mask:0xf
; __device__ __forceinline__ unsigned pk2(float lo, float hi) { return pg8::cvt_pk_bf16(lo, hi); }
; __device__ __forceinline__ float bf_lo(unsigned w) { return __uint_as_float(w << 16); }
; __device__ __forceinline__ float bf_hi(unsigned w) { return __uint_as_float(w & 0xffff0000u); }
; template <int R, bool SRCB> ...
;     ...
;         for (int r = 0; r < R; ++r) {
;             f32x4 y[2][2]; float ss = 0.f;
; #pragma unroll
;             for (int j = 0; j < 2; ++j) { const u32x4 t = yr[r][j];
;                 y[j][0] = (f32x4){bf_lo(t.x), bf_hi(t.x), bf_lo(t.y), bf_hi(t.y)}; y[j][1] = (f32x4){bf_lo(t.z), bf_hi(t.z), bf_lo(t.w), bf_hi(t.w)};
;                 if (R == 1 && YP) {
; #pragma unroll
;                     for (int k = 0; k < 2; ++k) { const float* pp = YP + (size_t)(row0 - M_LAT) * DM + 8 * lane + 512 * j + 4 * k; f32x4 s = *(const f32x4*)pp;
; #pragma unroll
;                         for (int q = 1; q < pg8::NSL; ++q) s = s + *(const f32x4*)(pp + (size_t)q * 2048 * DM);
;                         y[j][k] = s; } }
; #pragma unroll
;                 for (int k = 0; k < 2; ++k) ss += (y[j][k][0] * y[j][k][0] + y[j][k][1] * y[j][k][1]) + (y[j][k][2] * y[j][k][2] + y[j][k][3] * y[j][k][3]); }
;             const float rr = __builtin_amdgcn_rsqf(wave_sum(ss) * (1.0f / DM) + 1e-6f) * w;
; #pragma unroll
;             for (int j = 0; j < 2; ++j)
; #pragma unroll
;                 for (int k = 0; k < 2; ++k) h[r][j][k] = h[r][j][k] + gg[j][k] * (y[j][k] * rr);
;     ...
;         for (int r = 0; r < R; ++r) {
;             float ss = 0.f;
; #pragma unroll
;             for (int j = 0; j < 2; ++j)
; #pragma unroll
;                 for (int k = 0; k < 2; ++k) ss += (h[r][j][k][0] * h[r][j][k][0] + h[r][j][k][1] * h[r][j][k][1]) + (h[r][j][k][2] * h[r][j][k][2] + h[r][j][k][3] * h[r][j][k][3]);
;             const float rr = __builtin_amdgcn_rsqf(wave_sum(ss) * (1.0f / DM) + 1e-6f);
; #pragma unroll
;             for (int j = 0; j < 2; ++j) { const f32x4 v0 = (h[r][j][0] * rr * gp[j][0]) * sc1[j][0] + sh[j][0], v1 = (h[r][j][1] * rr * gp[j][1]) * sc1[j][1] + sh[j][1];
;                 u32x4 t; t.x = pk2(v0[0], v0[1]); t.y = pk2(v0[2], v0[3]); t.z = pk2(v1[0], v1[1]); t.w = pk2(v1[2], v1[3]);
;                 *(u32x4*)(U + (size_t)(row0 + r) * DM + 8 * lane + 512 * j) = t; }
	s_nop 1
	v_add_f32_dpp v140, v140, v140 row_ror:8 row_mask:0xf bank_mask:0xf
	s_nop 1
	v_add_f32_dpp v140, v140, v140 row_bcast:15 row_mask:0xa bank_mask:0xf
	s_nop 1
	v_add_f32_dpp v140, v140, v140 row_bcast:31 row_mask:0xc bank_mask:0xf
	s_nop 1
	v_fmamk_f32 v140, v140, 0x3a800000, v224
	v_rsq_f32_e32 v140, v140
	s_nop 0
	v_readlane_b32 s6, v140, 63
	s_nop 1
	v_pk_mul_f32 v[198:199], v[198:199], s[6:7] op_sel_hi:[1,0]
	v_pk_mul_f32 v[200:201], v[200:201], s[6:7] op_sel_hi:[1,0]
	v_pk_mul_f32 v[202:203], v[202:203], s[6:7] op_sel_hi:[1,0]
	v_pk_mul_f32 v[204:205], v[204:205], s[6:7] op_sel_hi:[1,0]
	v_pk_mul_f32 v[206:207], v[206:207], s[6:7] op_sel_hi:[1,0]
	v_pk_mul_f32 v[208:209], v[208:209], s[6:7] op_sel_hi:[1,0]
	v_pk_mul_f32 v[210:211], v[210:211], s[6:7] op_sel_hi:[1,0]
	v_pk_mul_f32 v[212:213], v[212:213], s[6:7] op_sel_hi:[1,0]
	v_pk_mul_f32 v[198:199], v[16:17], v[198:199]
	v_pk_mul_f32 v[200:201], v[18:19], v[200:201]
	v_pk_mul_f32 v[202:203], v[20:21], v[202:203]
	v_pk_mul_f32 v[204:205], v[22:23], v[204:205]
	v_pk_mul_f32 v[206:207], v[24:25], v[206:207]
	v_pk_mul_f32 v[208:209], v[26:27], v[208:209]
	v_pk_mul_f32 v[210:211], v[28:29], v[210:211]
	v_pk_mul_f32 v[212:213], v[30:31], v[212:213]
	v_pk_fma_f32 v[198:199], v[32:33], v[198:199], v[48:49]
	v_pk_fma_f32 v[200:201], v[34:35], v[200:201], v[50:51]
	v_pk_fma_f32 v[202:203], v[36:37], v[202:203], v[52:53]
	v_pk_fma_f32 v[204:205], v[38:39], v[204:205], v[54:55]
	v_pk_fma_f32 v[206:207], v[40:41], v[206:207], v[56:57]
	v_pk_fma_f32 v[208:209], v[42:43], v[208:209], v[58:59]
	v_pk_fma_f32 v[210:211], v[44:45], v[210:211], v[60:61]
	v_pk_fma_f32 v[212:213], v[46:47], v[212:213], v[62:63]
	v_cvt_pk_bf16_f32 v230, v198, v199
	v_cvt_pk_bf16_f32 v231, v200, v201
	v_cvt_pk_bf16_f32 v232, v202, v203
	v_cvt_pk_bf16_f32 v233, v204, v205
	v_cvt_pk_bf16_f32 v234, v206, v207
	v_cvt_pk_bf16_f32 v235, v208, v209
	v_cvt_pk_bf16_f32 v236, v210, v211
	v_cvt_pk_bf16_f32 v237, v212, v213
	global_store_dwordx4 v184, v[230:233], s[44:45] offset:2048 sc1
	global_store_dwordx4 v184, v[234:237], s[44:45] offset:3072 sc1
	s_waitcnt vmcnt(28)
	v_lshlrev_b32_e32 v116, 16, v148
	v_and_b32_e32 v117, 0xffff0000, v148
	v_lshlrev_b32_e32 v118, 16, v149
	v_and_b32_e32 v119, 0xffff0000, v149
	v_lshlrev_b32_e32 v120, 16, v150
	v_and_b32_e32 v121, 0xffff0000, v150
	v_lshlrev_b32_e32 v122, 16, v151
	v_and_b32_e32 v123, 0xffff0000, v151
	v_lshlrev_b32_e32 v124, 16, v152
	v_and_b32_e32 v125, 0xffff0000, v152
	v_lshlrev_b32_e32 v126, 16, v153
	v_and_b32_e32 v127, 0xffff0000, v153
	v_lshlrev_b32_e32 v128, 16, v154
	v_and_b32_e32 v129, 0xffff0000, v154
	v_lshlrev_b32_e32 v130, 16, v155
	v_and_b32_e32 v131, 0xffff0000, v155
	v_cvt_f32_f16_e32 v198, v64
	v_cvt_f32_f16_sdwa v199, v64 dst_sel:DWORD dst_unused:UNUSED_PAD src0_sel:WORD_1
	v_cvt_f32_f16_e32 v200, v65
	v_cvt_f32_f16_sdwa v201, v65 dst_sel:DWORD dst_unused:UNUSED_PAD src0_sel:WORD_1
	v_cvt_f32_f16_e32 v202, v66
	v_cvt_f32_f16_sdwa v203, v66 dst_sel:DWORD dst_unused:UNUSED_PAD src0_sel:WORD_1
	v_cvt_f32_f16_e32 v204, v67
	v_cvt_f32_f16_sdwa v205, v67 dst_sel:DWORD dst_unused:UNUSED_PAD src0_sel:WORD_1
	v_cvt_f32_f16_e32 v206, v68
	v_cvt_f32_f16_sdwa v207, v68 dst_sel:DWORD dst_unused:UNUSED_PAD src0_sel:WORD_1
	v_cvt_f32_f16_e32 v208, v69
	v_cvt_f32_f16_sdwa v209, v69 dst_sel:DWORD dst_unused:UNUSED_PAD src0_sel:WORD_1
	v_cvt_f32_f16_e32 v210, v70
	v_cvt_f32_f16_sdwa v211, v70 dst_sel:DWORD dst_unused:UNUSED_PAD src0_sel:WORD_1
	v_cvt_f32_f16_e32 v212, v71
	v_cvt_f32_f16_sdwa v213, v71 dst_sel:DWORD dst_unused:UNUSED_PAD src0_sel:WORD_1
	global_load_dwordx4 v[64:67], v186, s[42:43] offset:-4096
	global_load_dwordx4 v[68:71], v186, s[42:43] offset:-3072
	global_load_dwordx4 v[148:151], v186, s[44:45] offset:-4096
	global_load_dwordx4 v[152:155], v186, s[44:45] offset:-3072
	v_pk_mul_f32 v[140:141], v[116:117], v[116:117]
	v_pk_fma_f32 v[140:141], v[118:119], v[118:119], v[140:141]
	v_pk_fma_f32 v[140:141], v[120:121], v[120:121], v[140:141]
	v_pk_fma_f32 v[140:141], v[122:123], v[122:123], v[140:141]
	v_pk_fma_f32 v[140:141], v[124:125], v[124:125], v[140:141]
	v_pk_fma_f32 v[140:141], v[126:127], v[126:127], v[140:141]
	v_pk_fma_f32 v[140:141], v[128:129], v[128:129], v[140:141]
	v_pk_fma_f32 v[140:141], v[130:131], v[130:131], v[140:141]
	v_add_f32_e32 v140, v140, v141
	s_nop 1
	v_add_f32_dpp v140, v140, v140 quad_perm:[1,0,3,2] row_mask:0xf bank_mask:0xf
	s_nop 1
	v_add_f32_dpp v140, v140, v140 quad_perm:[2,3,0,1] row_mask:0xf bank_mask:0xf
	s_nop 1
	v_add_f32_dpp v140, v140, v140 row_ror:4 row_mask:0xf bank_mask:0xf
	s_nop 1
	v_add_f32_dpp v140, v140, v140 row_ror:8 row_mask:0xf bank_mask:0xf
	s_nop 1
	v_add_f32_dpp v140, v140, v140 row_bcast:15 row_mask:0xa bank_mask:0xf
	s_nop 1
	v_add_f32_dpp v140, v140, v140 row_bcast:31 row_mask:0xc bank_mask:0xf
	s_nop 1
	v_fmamk_f32 v140, v140, 0x3a800000, v224
	v_rsq_f32_e32 v140, v140
	s_nop 0
	v_mul_f32_e32 v140, v144, v140
	s_nop 0
	v_readlane_b32 s4, v140, 63
	s_nop 1
	v_pk_mul_f32 v[116:117], v[116:117], s[4:5] op_sel_hi:[1,0]
	v_pk_mul_f32 v[118:119], v[118:119], s[4:5] op_sel_hi:[1,0]
	v_pk_mul_f32 v[120:121], v[120:121], s[4:5] op_sel_hi:[1,0]
	v_pk_mul_f32 v[122:123], v[122:123], s[4:5] op_sel_hi:[1,0]
	v_pk_mul_f32 v[124:125], v[124:125], s[4:5] op_sel_hi:[1,0]
	v_pk_mul_f32 v[126:127], v[126:127], s[4:5] op_sel_hi:[1,0]
	v_pk_mul_f32 v[128:129], v[128:129], s[4:5] op_sel_hi:[1,0]
	v_pk_mul_f32 v[130:131], v[130:131], s[4:5] op_sel_hi:[1,0]
	v_pk_fma_f32 v[198:199], v[0:1], v[116:117], v[198:199]
	v_pk_fma_f32 v[200:201], v[2:3], v[118:119], v[200:201]
	v_pk_fma_f32 v[202:203], v[4:5], v[120:121], v[202:203]
; __device__ __forceinline__ unsigned pk2(float lo, float hi) { return pg8::cvt_pk_bf16(lo, hi); }
; __device__ __forceinline__ unsigned pkh2(float lo, float hi) { return (unsigned)__builtin_bit_cast(unsigned short, (_Float16)lo) | ((unsigned)__builtin_bit_cast(unsigned short, (_Float16)hi) << 16); }
; template <int R, bool SRCB> ...
;     ...
;         for (int j = 0; j < 2; ++j) { const int c = 8 * lane + 512 * j;
;             if (final_out) { *(f32x4*)(final_out + (size_t)(row0 + r) * DM + c) = h[r][j][0]; *(f32x4*)(final_out + (size_t)(row0 + r) * DM + c + 4) = h[r][j][1]; }
;             else { u32x4 t; t.x = pkh2(h[r][j][0][0], h[r][j][0][1]); t.y = pkh2(h[r][j][0][2], h[r][j][0][3]); t.z = pkh2(h[r][j][1][0], h[r][j][1][1]); t.w = pkh2(h[r][j][1][2], h[r][j][1][3]);
;                 *(u32x4*)(hout + (size_t)(row0 + r) * DM + c) = t; } }
;     if (U) {
;         f32x4 gp[2][2], sc1[2][2], sh[2][2];
; #pragma unroll
;         for (int j = 0; j < 2; ++j)
; #pragma unroll
;             for (int k = 0; k < 2; ++k) { const int c = 8 * lane + 512 * j + 4 * k; gp[j][k] = *(const f32x4*)(gpre + c); sc1[j][k] = *(const f32x4*)(scale + (size_t)mrow * 9216 + c) + 1.0f; sh[j][k] = *(const f32x4*)(shift + (size_t)mrow * 9216 + c); }
; #pragma unroll
;         for (int r = 0; r < R; ++r) {
;             float ss = 0.f;
; #pragma unroll
;             for (int j = 0; j < 2; ++j)
; #pragma unroll
;                 for (int k = 0; k < 2; ++k) ss += (h[r][j][k][0] * h[r][j][k][0] + h[r][j][k][1] * h[r][j][k][1]) + (h[r][j][k][2] * h[r][j][k][2] + h[r][j][k][3] * h[r][j][k][3]);
;             const float rr = __builtin_amdgcn_rsqf(wave_sum(ss) * (1.0f / DM) + 1e-6f);
; #pragma unroll
;             for (int j = 0; j < 2; ++j) { const f32x4 v0 = (h[r][j][0] * rr * gp[j][0]) * sc1[j][0] + sh[j][0], v1 = (h[r][j][1] * rr * gp[j][1]) * sc1[j][1] + sh[j][1];
;                 u32x4 t; t.x = pk2(v0[0], v0[1]); t.y = pk2(v0[2], v0[3]); t.z = pk2(v1[0], v1[1]); t.w = pk2(v1[2], v1[3]);
;                 *(u32x4*)(U + (size_t)(row0 + r) * DM + 8 * lane + 512 * j) = t; }
	v_pk_fma_f32 v[204:205], v[6:7], v[122:123], v[204:205]
	v_pk_fma_f32 v[206:207], v[8:9], v[124:125], v[206:207]
	v_pk_fma_f32 v[208:209], v[10:11], v[126:127], v[208:209]
	v_pk_fma_f32 v[210:211], v[12:13], v[128:129], v[210:211]
	v_pk_fma_f32 v[212:213], v[14:15], v[130:131], v[212:213]
	v_cvt_f16_f32_e32 v132, v198
	v_cvt_f16_f32_e32 v133, v200
	v_cvt_f16_f32_e32 v134, v202
	v_cvt_f16_f32_e32 v135, v204
	v_cvt_f16_f32_e32 v136, v206
	v_cvt_f16_f32_e32 v137, v208
	v_cvt_f16_f32_e32 v138, v210
	v_cvt_f16_f32_e32 v139, v212
	v_cvt_f16_f32_sdwa v132, v199 dst_sel:WORD_1 dst_unused:UNUSED_PRESERVE src0_sel:DWORD
	v_cvt_f16_f32_sdwa v133, v201 dst_sel:WORD_1 dst_unused:UNUSED_PRESERVE src0_sel:DWORD
	v_cvt_f16_f32_sdwa v134, v203 dst_sel:WORD_1 dst_unused:UNUSED_PRESERVE src0_sel:DWORD
	v_cvt_f16_f32_sdwa v135, v205 dst_sel:WORD_1 dst_unused:UNUSED_PRESERVE src0_sel:DWORD
	v_cvt_f16_f32_sdwa v136, v207 dst_sel:WORD_1 dst_unused:UNUSED_PRESERVE src0_sel:DWORD
	v_cvt_f16_f32_sdwa v137, v209 dst_sel:WORD_1 dst_unused:UNUSED_PRESERVE src0_sel:DWORD
	v_cvt_f16_f32_sdwa v138, v211 dst_sel:WORD_1 dst_unused:UNUSED_PRESERVE src0_sel:DWORD
	v_cvt_f16_f32_sdwa v139, v213 dst_sel:WORD_1 dst_unused:UNUSED_PRESERVE src0_sel:DWORD
	s_nop 0
	global_store_dwordx4 v185, v[132:135], s[42:43] offset:-4096 sc1
	global_store_dwordx4 v185, v[136:139], s[42:43] offset:-3072 sc1
	v_pk_mul_f32 v[140:141], v[198:199], v[198:199]
	v_pk_fma_f32 v[140:141], v[200:201], v[200:201], v[140:141]
	v_pk_fma_f32 v[140:141], v[202:203], v[202:203], v[140:141]
	v_pk_fma_f32 v[140:141], v[204:205], v[204:205], v[140:141]
	v_pk_fma_f32 v[140:141], v[206:207], v[206:207], v[140:141]
	v_pk_fma_f32 v[140:141], v[208:209], v[208:209], v[140:141]
	v_pk_fma_f32 v[140:141], v[210:211], v[210:211], v[140:141]
	v_pk_fma_f32 v[140:141], v[212:213], v[212:213], v[140:141]
	v_add_f32_e32 v140, v140, v141
	s_nop 1
	v_add_f32_dpp v140, v140, v140 quad_perm:[1,0,3,2] row_mask:0xf bank_mask:0xf
	s_nop 1
	v_add_f32_dpp v140, v140, v140 quad_perm:[2,3,0,1] row_mask:0xf bank_mask:0xf
	s_nop 1
	v_add_f32_dpp v140, v140, v140 row_ror:4 row_mask:0xf bank_mask:0xf
	s_nop 1
	v_add_f32_dpp v140, v140, v140 row_ror:8 row_mask:0xf bank_mask:0xf
	s_nop 1
	v_add_f32_dpp v140, v140, v140 row_bcast:15 row_mask:0xa bank_mask:0xf
	s_nop 1
	v_add_f32_dpp v140, v140, v140 row_bcast:31 row_mask:0xc bank_mask:0xf
	s_nop 1
	v_fmamk_f32 v140, v140, 0x3a800000, v224
	v_rsq_f32_e32 v140, v140
	s_nop 0
	v_readlane_b32 s6, v140, 63
	s_nop 1
	v_pk_mul_f32 v[198:199], v[198:199], s[6:7] op_sel_hi:[1,0]
	v_pk_mul_f32 v[200:201], v[200:201], s[6:7] op_sel_hi:[1,0]
	v_pk_mul_f32 v[202:203], v[202:203], s[6:7] op_sel_hi:[1,0]
	v_pk_mul_f32 v[204:205], v[204:205], s[6:7] op_sel_hi:[1,0]
	v_pk_mul_f32 v[206:207], v[206:207], s[6:7] op_sel_hi:[1,0]
	v_pk_mul_f32 v[208:209], v[208:209], s[6:7] op_sel_hi:[1,0]
	v_pk_mul_f32 v[210:211], v[210:211], s[6:7] op_sel_hi:[1,0]
	v_pk_mul_f32 v[212:213], v[212:213], s[6:7] op_sel_hi:[1,0]
	v_pk_mul_f32 v[198:199], v[16:17], v[198:199]
	v_pk_mul_f32 v[200:201], v[18:19], v[200:201]
	v_pk_mul_f32 v[202:203], v[20:21], v[202:203]
	v_pk_mul_f32 v[204:205], v[22:23], v[204:205]
	v_pk_mul_f32 v[206:207], v[24:25], v[206:207]
	v_pk_mul_f32 v[208:209], v[26:27], v[208:209]
	v_pk_mul_f32 v[210:211], v[28:29], v[210:211]
	v_pk_mul_f32 v[212:213], v[30:31], v[212:213]
	v_pk_fma_f32 v[198:199], v[32:33], v[198:199], v[48:49]
	v_pk_fma_f32 v[200:201], v[34:35], v[200:201], v[50:51]
	v_pk_fma_f32 v[202:203], v[36:37], v[202:203], v[52:53]
	v_pk_fma_f32 v[204:205], v[38:39], v[204:205], v[54:55]
	v_pk_fma_f32 v[206:207], v[40:41], v[206:207], v[56:57]
	v_pk_fma_f32 v[208:209], v[42:43], v[208:209], v[58:59]
	v_pk_fma_f32 v[210:211], v[44:45], v[210:211], v[60:61]
	v_pk_fma_f32 v[212:213], v[46:47], v[212:213], v[62:63]
	v_cvt_pk_bf16_f32 v230, v198, v199
	v_cvt_pk_bf16_f32 v231, v200, v201
	v_cvt_pk_bf16_f32 v232, v202, v203
	v_cvt_pk_bf16_f32 v233, v204, v205
	v_cvt_pk_bf16_f32 v234, v206, v207
	v_cvt_pk_bf16_f32 v235, v208, v209
	v_cvt_pk_bf16_f32 v236, v210, v211
	v_cvt_pk_bf16_f32 v237, v212, v213
	global_store_dwordx4 v185, v[230:233], s[44:45] offset:-4096 sc1
	global_store_dwordx4 v185, v[234:237], s[44:45] offset:-3072 sc1
	s_waitcnt vmcnt(28)
; __device__ __forceinline__ float bf_lo(unsigned w) { return __uint_as_float(w << 16); }
; __device__ __forceinline__ float bf_hi(unsigned w) { return __uint_as_float(w & 0xffff0000u); }
; __device__ __forceinline__ unsigned pkh2(float lo, float hi) { return (unsigned)__builtin_bit_cast(unsigned short, (_Float16)lo) | ((unsigned)__builtin_bit_cast(unsigned short, (_Float16)hi) << 16); }
; template <int R, bool SRCB> ...
;     ...
;         for (int r = 0; r < R; ++r) {
;             f32x4 y[2][2]; float ss = 0.f;
; #pragma unroll
;             for (int j = 0; j < 2; ++j) { const u32x4 t = yr[r][j];
;                 y[j][0] = (f32x4){bf_lo(t.x), bf_hi(t.x), bf_lo(t.y), bf_hi(t.y)}; y[j][1] = (f32x4){bf_lo(t.z), bf_hi(t.z), bf_lo(t.w), bf_hi(t.w)};
;                 if (R == 1 && YP) {
; #pragma unroll
;                     for (int k = 0; k < 2; ++k) { const float* pp = YP + (size_t)(row0 - M_LAT) * DM + 8 * lane + 512 * j + 4 * k; f32x4 s = *(const f32x4*)pp;
; #pragma unroll
;                         for (int q = 1; q < pg8::NSL; ++q) s = s + *(const f32x4*)(pp + (size_t)q * 2048 * DM);
;                         y[j][k] = s; } }
; #pragma unroll
;                 for (int k = 0; k < 2; ++k) ss += (y[j][k][0] * y[j][k][0] + y[j][k][1] * y[j][k][1]) + (y[j][k][2] * y[j][k][2] + y[j][k][3] * y[j][k][3]); }
;             const float rr = __builtin_amdgcn_rsqf(wave_sum(ss) * (1.0f / DM) + 1e-6f) * w;
; #pragma unroll
;             for (int j = 0; j < 2; ++j)
; #pragma unroll
;                 for (int k = 0; k < 2; ++k) h[r][j][k] = h[r][j][k] + gg[j][k] * (y[j][k] * rr);
;         }
;     }
; #pragma unroll
;     for (int r = 0; r < R; ++r)
; #pragma unroll
;         for (int j = 0; j < 2; ++j) { const int c = 8 * lane + 512 * j;
;             if (final_out) { *(f32x4*)(final_out + (size_t)(row0 + r) * DM + c) = h[r][j][0]; *(f32x4*)(final_out + (size_t)(row0 + r) * DM + c + 4) = h[r][j][1]; }
;             else { u32x4 t; t.x = pkh2(h[r][j][0][0], h[r][j][0][1]); t.y = pkh2(h[r][j][0][2], h[r][j][0][3]); t.z = pkh2(h[r][j][1][0], h[r][j][1][1]); t.w = pkh2(h[r][j][1][2], h[r][j][1][3]);
;                 *(u32x4*)(hout + (size_t)(row0 + r) * DM + c) = t; } }
	v_lshlrev_b32_e32 v116, 16, v156
	v_and_b32_e32 v117, 0xffff0000, v156
	v_lshlrev_b32_e32 v118, 16, v157
	v_and_b32_e32 v119, 0xffff0000, v157
	v_lshlrev_b32_e32 v120, 16, v158
	v_and_b32_e32 v121, 0xffff0000, v158
	v_lshlrev_b32_e32 v122, 16, v159
	v_and_b32_e32 v123, 0xffff0000, v159
	v_lshlrev_b32_e32 v124, 16, v160
	v_and_b32_e32 v125, 0xffff0000, v160
	v_lshlrev_b32_e32 v126, 16, v161
	v_and_b32_e32 v127, 0xffff0000, v161
	v_lshlrev_b32_e32 v128, 16, v162
	v_and_b32_e32 v129, 0xffff0000, v162
	v_lshlrev_b32_e32 v130, 16, v163
	v_and_b32_e32 v131, 0xffff0000, v163
	v_cvt_f32_f16_e32 v198, v72
	v_cvt_f32_f16_sdwa v199, v72 dst_sel:DWORD dst_unused:UNUSED_PAD src0_sel:WORD_1
	v_cvt_f32_f16_e32 v200, v73
	v_cvt_f32_f16_sdwa v201, v73 dst_sel:DWORD dst_unused:UNUSED_PAD src0_sel:WORD_1
	v_cvt_f32_f16_e32 v202, v74
	v_cvt_f32_f16_sdwa v203, v74 dst_sel:DWORD dst_unused:UNUSED_PAD src0_sel:WORD_1
	v_cvt_f32_f16_e32 v204, v75
	v_cvt_f32_f16_sdwa v205, v75 dst_sel:DWORD dst_unused:UNUSED_PAD src0_sel:WORD_1
	v_cvt_f32_f16_e32 v206, v76
	v_cvt_f32_f16_sdwa v207, v76 dst_sel:DWORD dst_unused:UNUSED_PAD src0_sel:WORD_1
	v_cvt_f32_f16_e32 v208, v77
	v_cvt_f32_f16_sdwa v209, v77 dst_sel:DWORD dst_unused:UNUSED_PAD src0_sel:WORD_1
	v_cvt_f32_f16_e32 v210, v78
	v_cvt_f32_f16_sdwa v211, v78 dst_sel:DWORD dst_unused:UNUSED_PAD src0_sel:WORD_1
	v_cvt_f32_f16_e32 v212, v79
	v_cvt_f32_f16_sdwa v213, v79 dst_sel:DWORD dst_unused:UNUSED_PAD src0_sel:WORD_1
	global_load_dwordx4 v[72:75], v186, s[42:43] offset:-2048
	global_load_dwordx4 v[76:79], v186, s[42:43] offset:-1024
	global_load_dwordx4 v[156:159], v186, s[44:45] offset:-2048
	global_load_dwordx4 v[160:163], v186, s[44:45] offset:-1024
	v_pk_mul_f32 v[140:141], v[116:117], v[116:117]
	v_pk_fma_f32 v[140:141], v[118:119], v[118:119], v[140:141]
	v_pk_fma_f32 v[140:141], v[120:121], v[120:121], v[140:141]
	v_pk_fma_f32 v[140:141], v[122:123], v[122:123], v[140:141]
	v_pk_fma_f32 v[140:141], v[124:125], v[124:125], v[140:141]
	v_pk_fma_f32 v[140:141], v[126:127], v[126:127], v[140:141]
	v_pk_fma_f32 v[140:141], v[128:129], v[128:129], v[140:141]
	v_pk_fma_f32 v[140:141], v[130:131], v[130:131], v[140:141]
	v_add_f32_e32 v140, v140, v141
	s_nop 1
	v_add_f32_dpp v140, v140, v140 quad_perm:[1,0,3,2] row_mask:0xf bank_mask:0xf
	s_nop 1
	v_add_f32_dpp v140, v140, v140 quad_perm:[2,3,0,1] row_mask:0xf bank_mask:0xf
	s_nop 1
	v_add_f32_dpp v140, v140, v140 row_ror:4 row_mask:0xf bank_mask:0xf
	s_nop 1
	v_add_f32_dpp v140, v140, v140 row_ror:8 row_mask:0xf bank_mask:0xf
	s_nop 1
	v_add_f32_dpp v140, v140, v140 row_bcast:15 row_mask:0xa bank_mask:0xf
	s_nop 1
	v_add_f32_dpp v140, v140, v140 row_bcast:31 row_mask:0xc bank_mask:0xf
	s_nop 1
	v_fmamk_f32 v140, v140, 0x3a800000, v224
	v_rsq_f32_e32 v140, v140
	s_nop 0
	v_mul_f32_e32 v140, v144, v140
	s_nop 0
	v_readlane_b32 s4, v140, 63
	s_nop 1
	v_pk_mul_f32 v[116:117], v[116:117], s[4:5] op_sel_hi:[1,0]
	v_pk_mul_f32 v[118:119], v[118:119], s[4:5] op_sel_hi:[1,0]
	v_pk_mul_f32 v[120:121], v[120:121], s[4:5] op_sel_hi:[1,0]
	v_pk_mul_f32 v[122:123], v[122:123], s[4:5] op_sel_hi:[1,0]
	v_pk_mul_f32 v[124:125], v[124:125], s[4:5] op_sel_hi:[1,0]
	v_pk_mul_f32 v[126:127], v[126:127], s[4:5] op_sel_hi:[1,0]
	v_pk_mul_f32 v[128:129], v[128:129], s[4:5] op_sel_hi:[1,0]
	v_pk_mul_f32 v[130:131], v[130:131], s[4:5] op_sel_hi:[1,0]
	v_pk_fma_f32 v[198:199], v[0:1], v[116:117], v[198:199]
	v_pk_fma_f32 v[200:201], v[2:3], v[118:119], v[200:201]
	v_pk_fma_f32 v[202:203], v[4:5], v[120:121], v[202:203]
	v_pk_fma_f32 v[204:205], v[6:7], v[122:123], v[204:205]
	v_pk_fma_f32 v[206:207], v[8:9], v[124:125], v[206:207]
	v_pk_fma_f32 v[208:209], v[10:11], v[126:127], v[208:209]
	v_pk_fma_f32 v[210:211], v[12:13], v[128:129], v[210:211]
	v_pk_fma_f32 v[212:213], v[14:15], v[130:131], v[212:213]
	v_cvt_f16_f32_e32 v132, v198
	v_cvt_f16_f32_e32 v133, v200
	v_cvt_f16_f32_e32 v134, v202
	v_cvt_f16_f32_e32 v135, v204
	v_cvt_f16_f32_e32 v136, v206
	v_cvt_f16_f32_e32 v137, v208
	v_cvt_f16_f32_e32 v138, v210
	v_cvt_f16_f32_e32 v139, v212
	v_cvt_f16_f32_sdwa v132, v199 dst_sel:WORD_1 dst_unused:UNUSED_PRESERVE src0_sel:DWORD
	v_cvt_f16_f32_sdwa v133, v201 dst_sel:WORD_1 dst_unused:UNUSED_PRESERVE src0_sel:DWORD
	v_cvt_f16_f32_sdwa v134, v203 dst_sel:WORD_1 dst_unused:UNUSED_PRESERVE src0_sel:DWORD
	v_cvt_f16_f32_sdwa v135, v205 dst_sel:WORD_1 dst_unused:UNUSED_PRESERVE src0_sel:DWORD
	v_cvt_f16_f32_sdwa v136, v207 dst_sel:WORD_1 dst_unused:UNUSED_PRESERVE src0_sel:DWORD
	v_cvt_f16_f32_sdwa v137, v209 dst_sel:WORD_1 dst_unused:UNUSED_PRESERVE src0_sel:DWORD
	v_cvt_f16_f32_sdwa v138, v211 dst_sel:WORD_1 dst_unused:UNUSED_PRESERVE src0_sel:DWORD
	v_cvt_f16_f32_sdwa v139, v213 dst_sel:WORD_1 dst_unused:UNUSED_PRESERVE src0_sel:DWORD
	s_nop 0
	global_store_dwordx4 v185, v[132:135], s[42:43] offset:-2048 sc1
	global_store_dwordx4 v185, v[136:139], s[42:43] offset:-1024 sc1
	v_pk_mul_f32 v[140:141], v[198:199], v[198:199]
	v_pk_fma_f32 v[140:141], v[200:201], v[200:201], v[140:141]
	v_pk_fma_f32 v[140:141], v[202:203], v[202:203], v[140:141]
	v_pk_fma_f32 v[140:141], v[204:205], v[204:205], v[140:141]
	v_pk_fma_f32 v[140:141], v[206:207], v[206:207], v[140:141]
	v_pk_fma_f32 v[140:141], v[208:209], v[208:209], v[140:141]
	v_pk_fma_f32 v[140:141], v[210:211], v[210:211], v[140:141]
	v_pk_fma_f32 v[140:141], v[212:213], v[212:213], v[140:141]
	v_add_f32_e32 v140, v140, v141
	s_nop 1
	v_add_f32_dpp v140, v140, v140 quad_perm:[1,0,3,2] row_mask:0xf bank_mask:0xf
	s_nop 1
	v_add_f32_dpp v140, v140, v140 quad_perm:[2,3,0,1] row_mask:0xf bank_mask:0xf
	s_nop 1
	v_add_f32_dpp v140, v140, v140 row_ror:4 row_mask:0xf bank_mask:0xf
; template <int R, bool SRCB> ...
;     ...
;         for (int r = 0; r < R; ++r) {
;             f32x4 y[2][2]; float ss = 0.f;
; #pragma unroll
;             for (int j = 0; j < 2; ++j) { const u32x4 t = yr[r][j];
;                 y[j][0] = (f32x4){bf_lo(t.x), bf_hi(t.x), bf_lo(t.y), bf_hi(t.y)}; y[j][1] = (f32x4){bf_lo(t.z), bf_hi(t.z), bf_lo(t.w), bf_hi(t.w)};
;                 if (R == 1 && YP) {
; #pragma unroll
;                     for (int k = 0; k < 2; ++k) { const float* pp = YP + (size_t)(row0 - M_LAT) * DM + 8 * lane + 512 * j + 4 * k; f32x4 s = *(const f32x4*)pp;
; #pragma unroll
;                         for (int q = 1; q < pg8::NSL; ++q) s = s + *(const f32x4*)(pp + (size_t)q * 2048 * DM);
;                         y[j][k] = s; } }
; #pragma unroll
;                 for (int k = 0; k < 2; ++k) ss += (y[j][k][0] * y[j][k][0] + y[j][k][1] * y[j][k][1]) + (y[j][k][2] * y[j][k][2] + y[j][k][3] * y[j][k][3]); }
;             const float rr = __builtin_amdgcn_rsqf(wave_sum(ss) * (1.0f / DM) + 1e-6f) * w;
; #pragma unroll
;             for (int j = 0; j < 2; ++j)
; #pragma unroll
;                 for (int k = 0; k < 2; ++k) h[r][j][k] = h[r][j][k] + gg[j][k] * (y[j][k] * rr);
;         }
;     }
; #pragma unroll
;     for (int r = 0; r < R; ++r)
; #pragma unroll
;         for (int j = 0; j < 2; ++j) { const int c = 8 * lane + 512 * j;
;             if (final_out) { *(f32x4*)(final_out + (size_t)(row0 + r) * DM + c) = h[r][j][0]; *(f32x4*)(final_out + (size_t)(row0 + r) * DM + c + 4) = h[r][j][1]; }
;             else { u32x4 t; t.x = pkh2(h[r][j][0][0], h[r][j][0][1]); t.y = pkh2(h[r][j][0][2], h[r][j][0][3]); t.z = pkh2(h[r][j][1][0], h[r][j][1][1]); t.w = pkh2(h[r][j][1][2], h[r][j][1][3]);
;                 *(u32x4*)(hout + (size_t)(row0 + r) * DM + c) = t; } }
;     if (U) {
;         f32x4 gp[2][2], sc1[2][2], sh[2][2];
; #pragma unroll
;         for (int j = 0; j < 2; ++j)
; #pragma unroll
;             for (int k = 0; k < 2; ++k) { const int c = 8 * lane + 512 * j + 4 * k; gp[j][k] = *(const f32x4*)(gpre + c); sc1[j][k] = *(const f32x4*)(scale + (size_t)mrow * 9216 + c) + 1.0f; sh[j][k] = *(const f32x4*)(shift + (size_t)mrow * 9216 + c); }
; #pragma unroll
;         for (int r = 0; r < R; ++r) {
;             float ss = 0.f;
; #pragma unroll
;             for (int j = 0; j < 2; ++j)
; #pragma unroll
	s_nop 1
	v_add_f32_dpp v140, v140, v140 row_ror:8 row_mask:0xf bank_mask:0xf
	s_nop 1
	v_add_f32_dpp v140, v140, v140 row_bcast:15 row_mask:0xa bank_mask:0xf
	s_nop 1
	v_add_f32_dpp v140, v140, v140 row_bcast:31 row_mask:0xc bank_mask:0xf
	s_nop 1
	v_fmamk_f32 v140, v140, 0x3a800000, v224
	v_rsq_f32_e32 v140, v140
	s_nop 0
	v_readlane_b32 s6, v140, 63
	s_nop 1
	v_pk_mul_f32 v[198:199], v[198:199], s[6:7] op_sel_hi:[1,0]
	v_pk_mul_f32 v[200:201], v[200:201], s[6:7] op_sel_hi:[1,0]
	v_pk_mul_f32 v[202:203], v[202:203], s[6:7] op_sel_hi:[1,0]
	v_pk_mul_f32 v[204:205], v[204:205], s[6:7] op_sel_hi:[1,0]
	v_pk_mul_f32 v[206:207], v[206:207], s[6:7] op_sel_hi:[1,0]
	v_pk_mul_f32 v[208:209], v[208:209], s[6:7] op_sel_hi:[1,0]
	v_pk_mul_f32 v[210:211], v[210:211], s[6:7] op_sel_hi:[1,0]
	v_pk_mul_f32 v[212:213], v[212:213], s[6:7] op_sel_hi:[1,0]
	v_pk_mul_f32 v[198:199], v[16:17], v[198:199]
	v_pk_mul_f32 v[200:201], v[18:19], v[200:201]
	v_pk_mul_f32 v[202:203], v[20:21], v[202:203]
	v_pk_mul_f32 v[204:205], v[22:23], v[204:205]
	v_pk_mul_f32 v[206:207], v[24:25], v[206:207]
	v_pk_mul_f32 v[208:209], v[26:27], v[208:209]
	v_pk_mul_f32 v[210:211], v[28:29], v[210:211]
	v_pk_mul_f32 v[212:213], v[30:31], v[212:213]
	v_pk_fma_f32 v[198:199], v[32:33], v[198:199], v[48:49]
	v_pk_fma_f32 v[200:201], v[34:35], v[200:201], v[50:51]
	v_pk_fma_f32 v[202:203], v[36:37], v[202:203], v[52:53]
	v_pk_fma_f32 v[204:205], v[38:39], v[204:205], v[54:55]
	v_pk_fma_f32 v[206:207], v[40:41], v[206:207], v[56:57]
	v_pk_fma_f32 v[208:209], v[42:43], v[208:209], v[58:59]
	v_pk_fma_f32 v[210:211], v[44:45], v[210:211], v[60:61]
	v_pk_fma_f32 v[212:213], v[46:47], v[212:213], v[62:63]
	v_cvt_pk_bf16_f32 v230, v198, v199
	v_cvt_pk_bf16_f32 v231, v200, v201
	v_cvt_pk_bf16_f32 v232, v202, v203
	v_cvt_pk_bf16_f32 v233, v204, v205
	v_cvt_pk_bf16_f32 v234, v206, v207
	v_cvt_pk_bf16_f32 v235, v208, v209
	v_cvt_pk_bf16_f32 v236, v210, v211
	v_cvt_pk_bf16_f32 v237, v212, v213
	global_store_dwordx4 v185, v[230:233], s[44:45] offset:-2048 sc1
	global_store_dwordx4 v185, v[234:237], s[44:45] offset:-1024 sc1
	s_waitcnt vmcnt(28)
	v_lshlrev_b32_e32 v116, 16, v164
	v_and_b32_e32 v117, 0xffff0000, v164
	v_lshlrev_b32_e32 v118, 16, v165
	v_and_b32_e32 v119, 0xffff0000, v165
	v_lshlrev_b32_e32 v120, 16, v166
	v_and_b32_e32 v121, 0xffff0000, v166
	v_lshlrev_b32_e32 v122, 16, v167
	v_and_b32_e32 v123, 0xffff0000, v167
	v_lshlrev_b32_e32 v124, 16, v168
	v_and_b32_e32 v125, 0xffff0000, v168
	v_lshlrev_b32_e32 v126, 16, v169
	v_and_b32_e32 v127, 0xffff0000, v169
	v_lshlrev_b32_e32 v128, 16, v170
	v_and_b32_e32 v129, 0xffff0000, v170
	v_lshlrev_b32_e32 v130, 16, v171
	v_and_b32_e32 v131, 0xffff0000, v171
	v_cvt_f32_f16_e32 v198, v80
	v_cvt_f32_f16_sdwa v199, v80 dst_sel:DWORD dst_unused:UNUSED_PAD src0_sel:WORD_1
	v_cvt_f32_f16_e32 v200, v81
	v_cvt_f32_f16_sdwa v201, v81 dst_sel:DWORD dst_unused:UNUSED_PAD src0_sel:WORD_1
	v_cvt_f32_f16_e32 v202, v82
	v_cvt_f32_f16_sdwa v203, v82 dst_sel:DWORD dst_unused:UNUSED_PAD src0_sel:WORD_1
	v_cvt_f32_f16_e32 v204, v83
	v_cvt_f32_f16_sdwa v205, v83 dst_sel:DWORD dst_unused:UNUSED_PAD src0_sel:WORD_1
	v_cvt_f32_f16_e32 v206, v84
	v_cvt_f32_f16_sdwa v207, v84 dst_sel:DWORD dst_unused:UNUSED_PAD src0_sel:WORD_1
	v_cvt_f32_f16_e32 v208, v85
	v_cvt_f32_f16_sdwa v209, v85 dst_sel:DWORD dst_unused:UNUSED_PAD src0_sel:WORD_1
	v_cvt_f32_f16_e32 v210, v86
	v_cvt_f32_f16_sdwa v211, v86 dst_sel:DWORD dst_unused:UNUSED_PAD src0_sel:WORD_1
	v_cvt_f32_f16_e32 v212, v87
	v_cvt_f32_f16_sdwa v213, v87 dst_sel:DWORD dst_unused:UNUSED_PAD src0_sel:WORD_1
	global_load_dwordx4 v[80:83], v186, s[42:43] offset:0
	global_load_dwordx4 v[84:87], v186, s[42:43] offset:1024
	global_load_dwordx4 v[164:167], v186, s[44:45] offset:0
	global_load_dwordx4 v[168:171], v186, s[44:45] offset:1024
	v_pk_mul_f32 v[140:141], v[116:117], v[116:117]
	v_pk_fma_f32 v[140:141], v[118:119], v[118:119], v[140:141]
	v_pk_fma_f32 v[140:141], v[120:121], v[120:121], v[140:141]
	v_pk_fma_f32 v[140:141], v[122:123], v[122:123], v[140:141]
	v_pk_fma_f32 v[140:141], v[124:125], v[124:125], v[140:141]
	v_pk_fma_f32 v[140:141], v[126:127], v[126:127], v[140:141]
	v_pk_fma_f32 v[140:141], v[128:129], v[128:129], v[140:141]
	v_pk_fma_f32 v[140:141], v[130:131], v[130:131], v[140:141]
	v_add_f32_e32 v140, v140, v141
	s_nop 1
	v_add_f32_dpp v140, v140, v140 quad_perm:[1,0,3,2] row_mask:0xf bank_mask:0xf
	s_nop 1
	v_add_f32_dpp v140, v140, v140 quad_perm:[2,3,0,1] row_mask:0xf bank_mask:0xf
	s_nop 1
	v_add_f32_dpp v140, v140, v140 row_ror:4 row_mask:0xf bank_mask:0xf
	s_nop 1
	v_add_f32_dpp v140, v140, v140 row_ror:8 row_mask:0xf bank_mask:0xf
	s_nop 1
	v_add_f32_dpp v140, v140, v140 row_bcast:15 row_mask:0xa bank_mask:0xf
	s_nop 1
	v_add_f32_dpp v140, v140, v140 row_bcast:31 row_mask:0xc bank_mask:0xf
	s_nop 1
	v_fmamk_f32 v140, v140, 0x3a800000, v224
	v_rsq_f32_e32 v140, v140
	s_nop 0
	v_mul_f32_e32 v140, v144, v140
	s_nop 0
	v_readlane_b32 s4, v140, 63
	s_nop 1
	v_pk_mul_f32 v[116:117], v[116:117], s[4:5] op_sel_hi:[1,0]
	v_pk_mul_f32 v[118:119], v[118:119], s[4:5] op_sel_hi:[1,0]
	v_pk_mul_f32 v[120:121], v[120:121], s[4:5] op_sel_hi:[1,0]
	v_pk_mul_f32 v[122:123], v[122:123], s[4:5] op_sel_hi:[1,0]
	v_pk_mul_f32 v[124:125], v[124:125], s[4:5] op_sel_hi:[1,0]
	v_pk_mul_f32 v[126:127], v[126:127], s[4:5] op_sel_hi:[1,0]
	v_pk_mul_f32 v[128:129], v[128:129], s[4:5] op_sel_hi:[1,0]
	v_pk_mul_f32 v[130:131], v[130:131], s[4:5] op_sel_hi:[1,0]
	v_pk_fma_f32 v[198:199], v[0:1], v[116:117], v[198:199]
	v_pk_fma_f32 v[200:201], v[2:3], v[118:119], v[200:201]
	v_pk_fma_f32 v[202:203], v[4:5], v[120:121], v[202:203]
; __device__ __forceinline__ unsigned pk2(float lo, float hi) { return pg8::cvt_pk_bf16(lo, hi); }
; __device__ __forceinline__ unsigned pkh2(float lo, float hi) { return (unsigned)__builtin_bit_cast(unsigned short, (_Float16)lo) | ((unsigned)__builtin_bit_cast(unsigned short, (_Float16)hi) << 16); }
; template <int R, bool SRCB> ...
;     ...
;                 for (int k = 0; k < 2; ++k) h[r][j][k] = h[r][j][k] + gg[j][k] * (y[j][k] * rr);
;         }
;     }
; #pragma unroll
;     for (int r = 0; r < R; ++r)
; #pragma unroll
;         for (int j = 0; j < 2; ++j) { const int c = 8 * lane + 512 * j;
;             if (final_out) { *(f32x4*)(final_out + (size_t)(row0 + r) * DM + c) = h[r][j][0]; *(f32x4*)(final_out + (size_t)(row0 + r) * DM + c + 4) = h[r][j][1]; }
;             else { u32x4 t; t.x = pkh2(h[r][j][0][0], h[r][j][0][1]); t.y = pkh2(h[r][j][0][2], h[r][j][0][3]); t.z = pkh2(h[r][j][1][0], h[r][j][1][1]); t.w = pkh2(h[r][j][1][2], h[r][j][1][3]);
;                 *(u32x4*)(hout + (size_t)(row0 + r) * DM + c) = t; } }
;     if (U) {
;         f32x4 gp[2][2], sc1[2][2], sh[2][2];
; #pragma unroll
;         for (int j = 0; j < 2; ++j)
; #pragma unroll
;             for (int k = 0; k < 2; ++k) { const int c = 8 * lane + 512 * j + 4 * k; gp[j][k] = *(const f32x4*)(gpre + c); sc1[j][k] = *(const f32x4*)(scale + (size_t)mrow * 9216 + c) + 1.0f; sh[j][k] = *(const f32x4*)(shift + (size_t)mrow * 9216 + c); }
; #pragma unroll
;         for (int r = 0; r < R; ++r) {
;             float ss = 0.f;
; #pragma unroll
;             for (int j = 0; j < 2; ++j)
; #pragma unroll
;                 for (int k = 0; k < 2; ++k) ss += (h[r][j][k][0] * h[r][j][k][0] + h[r][j][k][1] * h[r][j][k][1]) + (h[r][j][k][2] * h[r][j][k][2] + h[r][j][k][3] * h[r][j][k][3]);
;             const float rr = __builtin_amdgcn_rsqf(wave_sum(ss) * (1.0f / DM) + 1e-6f);
; #pragma unroll
;             for (int j = 0; j < 2; ++j) { const f32x4 v0 = (h[r][j][0] * rr * gp[j][0]) * sc1[j][0] + sh[j][0], v1 = (h[r][j][1] * rr * gp[j][1]) * sc1[j][1] + sh[j][1];
;                 u32x4 t; t.x = pk2(v0[0], v0[1]); t.y = pk2(v0[2], v0[3]); t.z = pk2(v1[0], v1[1]); t.w = pk2(v1[2], v1[3]);
;                 *(u32x4*)(U + (size_t)(row0 + r) * DM + 8 * lane + 512 * j) = t; }
	v_pk_fma_f32 v[204:205], v[6:7], v[122:123], v[204:205]
	v_pk_fma_f32 v[206:207], v[8:9], v[124:125], v[206:207]
	v_pk_fma_f32 v[208:209], v[10:11], v[126:127], v[208:209]
	v_pk_fma_f32 v[210:211], v[12:13], v[128:129], v[210:211]
	v_pk_fma_f32 v[212:213], v[14:15], v[130:131], v[212:213]
	v_cvt_f16_f32_e32 v132, v198
	v_cvt_f16_f32_e32 v133, v200
	v_cvt_f16_f32_e32 v134, v202
	v_cvt_f16_f32_e32 v135, v204
	v_cvt_f16_f32_e32 v136, v206
	v_cvt_f16_f32_e32 v137, v208
	v_cvt_f16_f32_e32 v138, v210
	v_cvt_f16_f32_e32 v139, v212
	v_cvt_f16_f32_sdwa v132, v199 dst_sel:WORD_1 dst_unused:UNUSED_PRESERVE src0_sel:DWORD
	v_cvt_f16_f32_sdwa v133, v201 dst_sel:WORD_1 dst_unused:UNUSED_PRESERVE src0_sel:DWORD
	v_cvt_f16_f32_sdwa v134, v203 dst_sel:WORD_1 dst_unused:UNUSED_PRESERVE src0_sel:DWORD
	v_cvt_f16_f32_sdwa v135, v205 dst_sel:WORD_1 dst_unused:UNUSED_PRESERVE src0_sel:DWORD
	v_cvt_f16_f32_sdwa v136, v207 dst_sel:WORD_1 dst_unused:UNUSED_PRESERVE src0_sel:DWORD
	v_cvt_f16_f32_sdwa v137, v209 dst_sel:WORD_1 dst_unused:UNUSED_PRESERVE src0_sel:DWORD
	v_cvt_f16_f32_sdwa v138, v211 dst_sel:WORD_1 dst_unused:UNUSED_PRESERVE src0_sel:DWORD
	v_cvt_f16_f32_sdwa v139, v213 dst_sel:WORD_1 dst_unused:UNUSED_PRESERVE src0_sel:DWORD
	s_nop 0
	global_store_dwordx4 v185, v[132:135], s[42:43] offset:0 sc1
	global_store_dwordx4 v185, v[136:139], s[42:43] offset:1024 sc1
	v_pk_mul_f32 v[140:141], v[198:199], v[198:199]
	v_pk_fma_f32 v[140:141], v[200:201], v[200:201], v[140:141]
	v_pk_fma_f32 v[140:141], v[202:203], v[202:203], v[140:141]
	v_pk_fma_f32 v[140:141], v[204:205], v[204:205], v[140:141]
	v_pk_fma_f32 v[140:141], v[206:207], v[206:207], v[140:141]
	v_pk_fma_f32 v[140:141], v[208:209], v[208:209], v[140:141]
	v_pk_fma_f32 v[140:141], v[210:211], v[210:211], v[140:141]
	v_pk_fma_f32 v[140:141], v[212:213], v[212:213], v[140:141]
	v_add_f32_e32 v140, v140, v141
	s_nop 1
	v_add_f32_dpp v140, v140, v140 quad_perm:[1,0,3,2] row_mask:0xf bank_mask:0xf
	s_nop 1
	v_add_f32_dpp v140, v140, v140 quad_perm:[2,3,0,1] row_mask:0xf bank_mask:0xf
	s_nop 1
	v_add_f32_dpp v140, v140, v140 row_ror:4 row_mask:0xf bank_mask:0xf
	s_nop 1
	v_add_f32_dpp v140, v140, v140 row_ror:8 row_mask:0xf bank_mask:0xf
	s_nop 1
	v_add_f32_dpp v140, v140, v140 row_bcast:15 row_mask:0xa bank_mask:0xf
	s_nop 1
	v_add_f32_dpp v140, v140, v140 row_bcast:31 row_mask:0xc bank_mask:0xf
	s_nop 1
	v_fmamk_f32 v140, v140, 0x3a800000, v224
	v_rsq_f32_e32 v140, v140
	s_nop 0
	v_readlane_b32 s6, v140, 63
	s_nop 1
	v_pk_mul_f32 v[198:199], v[198:199], s[6:7] op_sel_hi:[1,0]
	v_pk_mul_f32 v[200:201], v[200:201], s[6:7] op_sel_hi:[1,0]
	v_pk_mul_f32 v[202:203], v[202:203], s[6:7] op_sel_hi:[1,0]
	v_pk_mul_f32 v[204:205], v[204:205], s[6:7] op_sel_hi:[1,0]
	v_pk_mul_f32 v[206:207], v[206:207], s[6:7] op_sel_hi:[1,0]
	v_pk_mul_f32 v[208:209], v[208:209], s[6:7] op_sel_hi:[1,0]
	v_pk_mul_f32 v[210:211], v[210:211], s[6:7] op_sel_hi:[1,0]
	v_pk_mul_f32 v[212:213], v[212:213], s[6:7] op_sel_hi:[1,0]
	v_pk_mul_f32 v[198:199], v[16:17], v[198:199]
	v_pk_mul_f32 v[200:201], v[18:19], v[200:201]
	v_pk_mul_f32 v[202:203], v[20:21], v[202:203]
	v_pk_mul_f32 v[204:205], v[22:23], v[204:205]
	v_pk_mul_f32 v[206:207], v[24:25], v[206:207]
	v_pk_mul_f32 v[208:209], v[26:27], v[208:209]
	v_pk_mul_f32 v[210:211], v[28:29], v[210:211]
	v_pk_mul_f32 v[212:213], v[30:31], v[212:213]
	v_pk_fma_f32 v[198:199], v[32:33], v[198:199], v[48:49]
	v_pk_fma_f32 v[200:201], v[34:35], v[200:201], v[50:51]
	v_pk_fma_f32 v[202:203], v[36:37], v[202:203], v[52:53]
	v_pk_fma_f32 v[204:205], v[38:39], v[204:205], v[54:55]
	v_pk_fma_f32 v[206:207], v[40:41], v[206:207], v[56:57]
	v_pk_fma_f32 v[208:209], v[42:43], v[208:209], v[58:59]
	v_pk_fma_f32 v[210:211], v[44:45], v[210:211], v[60:61]
	v_pk_fma_f32 v[212:213], v[46:47], v[212:213], v[62:63]
	v_cvt_pk_bf16_f32 v230, v198, v199
	v_cvt_pk_bf16_f32 v231, v200, v201
	v_cvt_pk_bf16_f32 v232, v202, v203
	v_cvt_pk_bf16_f32 v233, v204, v205
	v_cvt_pk_bf16_f32 v234, v206, v207
	v_cvt_pk_bf16_f32 v235, v208, v209
	v_cvt_pk_bf16_f32 v236, v210, v211
	v_cvt_pk_bf16_f32 v237, v212, v213
	global_store_dwordx4 v185, v[230:233], s[44:45] offset:0 sc1
	global_store_dwordx4 v185, v[234:237], s[44:45] offset:1024 sc1
	s_waitcnt vmcnt(28)
; template <int R, bool SRCB> ...
;     ...
;         for (int r = 0; r < R; ++r) {
;             f32x4 y[2][2]; float ss = 0.f;
; #pragma unroll
;             for (int j = 0; j < 2; ++j) { const u32x4 t = yr[r][j];
;                 y[j][0] = (f32x4){bf_lo(t.x), bf_hi(t.x), bf_lo(t.y), bf_hi(t.y)}; y[j][1] = (f32x4){bf_lo(t.z), bf_hi(t.z), bf_lo(t.w), bf_hi(t.w)};
;                 if (R == 1 && YP) {
; #pragma unroll
;                     for (int k = 0; k < 2; ++k) { const float* pp = YP + (size_t)(row0 - M_LAT) * DM + 8 * lane + 512 * j + 4 * k; f32x4 s = *(const f32x4*)pp;
; #pragma unroll
;                         for (int q = 1; q < pg8::NSL; ++q) s = s + *(const f32x4*)(pp + (size_t)q * 2048 * DM);
;                         y[j][k] = s; } }
; #pragma unroll
;                 for (int k = 0; k < 2; ++k) ss += (y[j][k][0] * y[j][k][0] + y[j][k][1] * y[j][k][1]) + (y[j][k][2] * y[j][k][2] + y[j][k][3] * y[j][k][3]); }
;             const float rr = __builtin_amdgcn_rsqf(wave_sum(ss) * (1.0f / DM) + 1e-6f) * w;
; #pragma unroll
;             for (int j = 0; j < 2; ++j)
; #pragma unroll
;                 for (int k = 0; k < 2; ++k) h[r][j][k] = h[r][j][k] + gg[j][k] * (y[j][k] * rr);
;         }
;     }
; #pragma unroll
;     for (int r = 0; r < R; ++r)
; #pragma unroll
;         for (int j = 0; j < 2; ++j) { const int c = 8 * lane + 512 * j;
;             if (final_out) { *(f32x4*)(final_out + (size_t)(row0 + r) * DM + c) = h[r][j][0]; *(f32x4*)(final_out + (size_t)(row0 + r) * DM + c + 4) = h[r][j][1]; }
;             else { u32x4 t; t.x = pkh2(h[r][j][0][0], h[r][j][0][1]); t.y = pkh2(h[r][j][0][2], h[r][j][0][3]); t.z = pkh2(h[r][j][1][0], h[r][j][1][1]); t.w = pkh2(h[r][j][1][2], h[r][j][1][3]);
;                 *(u32x4*)(hout + (size_t)(row0 + r) * DM + c) = t; } }
;     if (U) {
;         f32x4 gp[2][2], sc1[2][2], sh[2][2];
; #pragma unroll
;         for (int j = 0; j < 2; ++j)
; #pragma unroll
;             for (int k = 0; k < 2; ++k) { const int c = 8 * lane + 512 * j + 4 * k; gp[j][k] = *(const f32x4*)(gpre + c); sc1[j][k] = *(const f32x4*)(scale + (size_t)mrow * 9216 + c) + 1.0f; sh[j][k] = *(const f32x4*)(shift + (size_t)mrow * 9216 + c); }
; #pragma unroll
;         for (int r = 0; r < R; ++r) {
;             float ss = 0.f;
; #pragma unroll
;             for (int j = 0; j < 2; ++j)
; #pragma unroll
	v_lshlrev_b32_e32 v116, 16, v172
	v_and_b32_e32 v117, 0xffff0000, v172
	v_lshlrev_b32_e32 v118, 16, v173
	v_and_b32_e32 v119, 0xffff0000, v173
	v_lshlrev_b32_e32 v120, 16, v174
	v_and_b32_e32 v121, 0xffff0000, v174
	v_lshlrev_b32_e32 v122, 16, v175
	v_and_b32_e32 v123, 0xffff0000, v175
	v_lshlrev_b32_e32 v124, 16, v176
	v_and_b32_e32 v125, 0xffff0000, v176
	v_lshlrev_b32_e32 v126, 16, v177
	v_and_b32_e32 v127, 0xffff0000, v177
	v_lshlrev_b32_e32 v128, 16, v178
	v_and_b32_e32 v129, 0xffff0000, v178
	v_lshlrev_b32_e32 v130, 16, v179
	v_and_b32_e32 v131, 0xffff0000, v179
	v_cvt_f32_f16_e32 v198, v88
	v_cvt_f32_f16_sdwa v199, v88 dst_sel:DWORD dst_unused:UNUSED_PAD src0_sel:WORD_1
	v_cvt_f32_f16_e32 v200, v89
	v_cvt_f32_f16_sdwa v201, v89 dst_sel:DWORD dst_unused:UNUSED_PAD src0_sel:WORD_1
	v_cvt_f32_f16_e32 v202, v90
	v_cvt_f32_f16_sdwa v203, v90 dst_sel:DWORD dst_unused:UNUSED_PAD src0_sel:WORD_1
	v_cvt_f32_f16_e32 v204, v91
	v_cvt_f32_f16_sdwa v205, v91 dst_sel:DWORD dst_unused:UNUSED_PAD src0_sel:WORD_1
	v_cvt_f32_f16_e32 v206, v92
	v_cvt_f32_f16_sdwa v207, v92 dst_sel:DWORD dst_unused:UNUSED_PAD src0_sel:WORD_1
	v_cvt_f32_f16_e32 v208, v93
	v_cvt_f32_f16_sdwa v209, v93 dst_sel:DWORD dst_unused:UNUSED_PAD src0_sel:WORD_1
	v_cvt_f32_f16_e32 v210, v94
	v_cvt_f32_f16_sdwa v211, v94 dst_sel:DWORD dst_unused:UNUSED_PAD src0_sel:WORD_1
	v_cvt_f32_f16_e32 v212, v95
	v_cvt_f32_f16_sdwa v213, v95 dst_sel:DWORD dst_unused:UNUSED_PAD src0_sel:WORD_1
	global_load_dwordx4 v[88:91], v186, s[42:43] offset:2048
	global_load_dwordx4 v[92:95], v186, s[42:43] offset:3072
	global_load_dwordx4 v[172:175], v186, s[44:45] offset:2048
	global_load_dwordx4 v[176:179], v186, s[44:45] offset:3072
	v_pk_mul_f32 v[140:141], v[116:117], v[116:117]
	v_pk_fma_f32 v[140:141], v[118:119], v[118:119], v[140:141]
	v_pk_fma_f32 v[140:141], v[120:121], v[120:121], v[140:141]
	v_pk_fma_f32 v[140:141], v[122:123], v[122:123], v[140:141]
	v_pk_fma_f32 v[140:141], v[124:125], v[124:125], v[140:141]
	v_pk_fma_f32 v[140:141], v[126:127], v[126:127], v[140:141]
	v_pk_fma_f32 v[140:141], v[128:129], v[128:129], v[140:141]
	v_pk_fma_f32 v[140:141], v[130:131], v[130:131], v[140:141]
	v_add_f32_e32 v140, v140, v141
	s_nop 1
	v_add_f32_dpp v140, v140, v140 quad_perm:[1,0,3,2] row_mask:0xf bank_mask:0xf
	s_nop 1
	v_add_f32_dpp v140, v140, v140 quad_perm:[2,3,0,1] row_mask:0xf bank_mask:0xf
	s_nop 1
	v_add_f32_dpp v140, v140, v140 row_ror:4 row_mask:0xf bank_mask:0xf
	s_nop 1
	v_add_f32_dpp v140, v140, v140 row_ror:8 row_mask:0xf bank_mask:0xf
	s_nop 1
	v_add_f32_dpp v140, v140, v140 row_bcast:15 row_mask:0xa bank_mask:0xf
	s_nop 1
	v_add_f32_dpp v140, v140, v140 row_bcast:31 row_mask:0xc bank_mask:0xf
	s_nop 1
	v_fmamk_f32 v140, v140, 0x3a800000, v224
	v_rsq_f32_e32 v140, v140
	s_nop 0
	v_mul_f32_e32 v140, v144, v140
	s_nop 0
	v_readlane_b32 s4, v140, 63
	s_nop 1
	v_pk_mul_f32 v[116:117], v[116:117], s[4:5] op_sel_hi:[1,0]
	v_pk_mul_f32 v[118:119], v[118:119], s[4:5] op_sel_hi:[1,0]
	v_pk_mul_f32 v[120:121], v[120:121], s[4:5] op_sel_hi:[1,0]
	v_pk_mul_f32 v[122:123], v[122:123], s[4:5] op_sel_hi:[1,0]
	v_pk_mul_f32 v[124:125], v[124:125], s[4:5] op_sel_hi:[1,0]
	v_pk_mul_f32 v[126:127], v[126:127], s[4:5] op_sel_hi:[1,0]
	v_pk_mul_f32 v[128:129], v[128:129], s[4:5] op_sel_hi:[1,0]
	v_pk_mul_f32 v[130:131], v[130:131], s[4:5] op_sel_hi:[1,0]
	v_pk_fma_f32 v[198:199], v[0:1], v[116:117], v[198:199]
	v_pk_fma_f32 v[200:201], v[2:3], v[118:119], v[200:201]
	v_pk_fma_f32 v[202:203], v[4:5], v[120:121], v[202:203]
	v_pk_fma_f32 v[204:205], v[6:7], v[122:123], v[204:205]
	v_pk_fma_f32 v[206:207], v[8:9], v[124:125], v[206:207]
	v_pk_fma_f32 v[208:209], v[10:11], v[126:127], v[208:209]
	v_pk_fma_f32 v[210:211], v[12:13], v[128:129], v[210:211]
	v_pk_fma_f32 v[212:213], v[14:15], v[130:131], v[212:213]
	v_cvt_f16_f32_e32 v132, v198
	v_cvt_f16_f32_e32 v133, v200
	v_cvt_f16_f32_e32 v134, v202
	v_cvt_f16_f32_e32 v135, v204
	v_cvt_f16_f32_e32 v136, v206
	v_cvt_f16_f32_e32 v137, v208
	v_cvt_f16_f32_e32 v138, v210
	v_cvt_f16_f32_e32 v139, v212
	v_cvt_f16_f32_sdwa v132, v199 dst_sel:WORD_1 dst_unused:UNUSED_PRESERVE src0_sel:DWORD
	v_cvt_f16_f32_sdwa v133, v201 dst_sel:WORD_1 dst_unused:UNUSED_PRESERVE src0_sel:DWORD
	v_cvt_f16_f32_sdwa v134, v203 dst_sel:WORD_1 dst_unused:UNUSED_PRESERVE src0_sel:DWORD
	v_cvt_f16_f32_sdwa v135, v205 dst_sel:WORD_1 dst_unused:UNUSED_PRESERVE src0_sel:DWORD
	v_cvt_f16_f32_sdwa v136, v207 dst_sel:WORD_1 dst_unused:UNUSED_PRESERVE src0_sel:DWORD
	v_cvt_f16_f32_sdwa v137, v209 dst_sel:WORD_1 dst_unused:UNUSED_PRESERVE src0_sel:DWORD
	v_cvt_f16_f32_sdwa v138, v211 dst_sel:WORD_1 dst_unused:UNUSED_PRESERVE src0_sel:DWORD
	v_cvt_f16_f32_sdwa v139, v213 dst_sel:WORD_1 dst_unused:UNUSED_PRESERVE src0_sel:DWORD
	s_nop 0
	global_store_dwordx4 v185, v[132:135], s[42:43] offset:2048 sc1
	global_store_dwordx4 v185, v[136:139], s[42:43] offset:3072 sc1
	v_pk_mul_f32 v[140:141], v[198:199], v[198:199]
	v_pk_fma_f32 v[140:141], v[200:201], v[200:201], v[140:141]
	v_pk_fma_f32 v[140:141], v[202:203], v[202:203], v[140:141]
	v_pk_fma_f32 v[140:141], v[204:205], v[204:205], v[140:141]
	v_pk_fma_f32 v[140:141], v[206:207], v[206:207], v[140:141]
	v_pk_fma_f32 v[140:141], v[208:209], v[208:209], v[140:141]
	v_pk_fma_f32 v[140:141], v[210:211], v[210:211], v[140:141]
	v_pk_fma_f32 v[140:141], v[212:213], v[212:213], v[140:141]
	v_add_f32_e32 v140, v140, v141
	s_nop 1
	v_add_f32_dpp v140, v140, v140 quad_perm:[1,0,3,2] row_mask:0xf bank_mask:0xf
	s_nop 1
	v_add_f32_dpp v140, v140, v140 quad_perm:[2,3,0,1] row_mask:0xf bank_mask:0xf
	s_nop 1
	v_add_f32_dpp v140, v140, v140 row_ror:4 row_mask:0xf bank_mask:0xf
; template <int R, bool SRCB> ...
;     ...
;         for (int r = 0; r < R; ++r) {
;             f32x4 y[2][2]; float ss = 0.f;
; #pragma unroll
;             for (int j = 0; j < 2; ++j) { const u32x4 t = yr[r][j];
;                 y[j][0] = (f32x4){bf_lo(t.x), bf_hi(t.x), bf_lo(t.y), bf_hi(t.y)}; y[j][1] = (f32x4){bf_lo(t.z), bf_hi(t.z), bf_lo(t.w), bf_hi(t.w)};
;                 if (R == 1 && YP) {
; #pragma unroll
;                     for (int k = 0; k < 2; ++k) { const float* pp = YP + (size_t)(row0 - M_LAT) * DM + 8 * lane + 512 * j + 4 * k; f32x4 s = *(const f32x4*)pp;
; #pragma unroll
;                         for (int q = 1; q < pg8::NSL; ++q) s = s + *(const f32x4*)(pp + (size_t)q * 2048 * DM);
;                         y[j][k] = s; } }
; #pragma unroll
;                 for (int k = 0; k < 2; ++k) ss += (y[j][k][0] * y[j][k][0] + y[j][k][1] * y[j][k][1]) + (y[j][k][2] * y[j][k][2] + y[j][k][3] * y[j][k][3]); }
;             const float rr = __builtin_amdgcn_rsqf(wave_sum(ss) * (1.0f / DM) + 1e-6f) * w;
; #pragma unroll
;             for (int j = 0; j < 2; ++j)
; #pragma unroll
;                 for (int k = 0; k < 2; ++k) h[r][j][k] = h[r][j][k] + gg[j][k] * (y[j][k] * rr);
;         }
;     }
; #pragma unroll
;     for (int r = 0; r < R; ++r)
; #pragma unroll
;         for (int j = 0; j < 2; ++j) { const int c = 8 * lane + 512 * j;
;             if (final_out) { *(f32x4*)(final_out + (size_t)(row0 + r) * DM + c) = h[r][j][0]; *(f32x4*)(final_out + (size_t)(row0 + r) * DM + c + 4) = h[r][j][1]; }
;             else { u32x4 t; t.x = pkh2(h[r][j][0][0], h[r][j][0][1]); t.y = pkh2(h[r][j][0][2], h[r][j][0][3]); t.z = pkh2(h[r][j][1][0], h[r][j][1][1]); t.w = pkh2(h[r][j][1][2], h[r][j][1][3]);
;                 *(u32x4*)(hout + (size_t)(row0 + r) * DM + c) = t; } }
;     if (U) {
;         f32x4 gp[2][2], sc1[2][2], sh[2][2];
; #pragma unroll
;         for (int j = 0; j < 2; ++j)
; #pragma unroll
;             for (int k = 0; k < 2; ++k) { const int c = 8 * lane + 512 * j + 4 * k; gp[j][k] = *(const f32x4*)(gpre + c); sc1[j][k] = *(const f32x4*)(scale + (size_t)mrow * 9216 + c) + 1.0f; sh[j][k] = *(const f32x4*)(shift + (size_t)mrow * 9216 + c); }
; #pragma unroll
;         for (int r = 0; r < R; ++r) {
;             float ss = 0.f;
; #pragma unroll
;             for (int j = 0; j < 2; ++j)
; #pragma unroll
	s_nop 1
	v_add_f32_dpp v140, v140, v140 row_ror:8 row_mask:0xf bank_mask:0xf
	s_nop 1
	v_add_f32_dpp v140, v140, v140 row_bcast:15 row_mask:0xa bank_mask:0xf
	s_nop 1
	v_add_f32_dpp v140, v140, v140 row_bcast:31 row_mask:0xc bank_mask:0xf
	s_nop 1
	v_fmamk_f32 v140, v140, 0x3a800000, v224
	v_rsq_f32_e32 v140, v140
	s_nop 0
	v_readlane_b32 s6, v140, 63
	s_nop 1
	v_pk_mul_f32 v[198:199], v[198:199], s[6:7] op_sel_hi:[1,0]
	v_pk_mul_f32 v[200:201], v[200:201], s[6:7] op_sel_hi:[1,0]
	v_pk_mul_f32 v[202:203], v[202:203], s[6:7] op_sel_hi:[1,0]
	v_pk_mul_f32 v[204:205], v[204:205], s[6:7] op_sel_hi:[1,0]
	v_pk_mul_f32 v[206:207], v[206:207], s[6:7] op_sel_hi:[1,0]
	v_pk_mul_f32 v[208:209], v[208:209], s[6:7] op_sel_hi:[1,0]
	v_pk_mul_f32 v[210:211], v[210:211], s[6:7] op_sel_hi:[1,0]
	v_pk_mul_f32 v[212:213], v[212:213], s[6:7] op_sel_hi:[1,0]
	v_pk_mul_f32 v[198:199], v[16:17], v[198:199]
	v_pk_mul_f32 v[200:201], v[18:19], v[200:201]
	v_pk_mul_f32 v[202:203], v[20:21], v[202:203]
	v_pk_mul_f32 v[204:205], v[22:23], v[204:205]
	v_pk_mul_f32 v[206:207], v[24:25], v[206:207]
	v_pk_mul_f32 v[208:209], v[26:27], v[208:209]
	v_pk_mul_f32 v[210:211], v[28:29], v[210:211]
	v_pk_mul_f32 v[212:213], v[30:31], v[212:213]
	v_pk_fma_f32 v[198:199], v[32:33], v[198:199], v[48:49]
	v_pk_fma_f32 v[200:201], v[34:35], v[200:201], v[50:51]
	v_pk_fma_f32 v[202:203], v[36:37], v[202:203], v[52:53]
	v_pk_fma_f32 v[204:205], v[38:39], v[204:205], v[54:55]
	v_pk_fma_f32 v[206:207], v[40:41], v[206:207], v[56:57]
	v_pk_fma_f32 v[208:209], v[42:43], v[208:209], v[58:59]
	v_pk_fma_f32 v[210:211], v[44:45], v[210:211], v[60:61]
	v_pk_fma_f32 v[212:213], v[46:47], v[212:213], v[62:63]
	v_cvt_pk_bf16_f32 v230, v198, v199
	v_cvt_pk_bf16_f32 v231, v200, v201
	v_cvt_pk_bf16_f32 v232, v202, v203
	v_cvt_pk_bf16_f32 v233, v204, v205
	v_cvt_pk_bf16_f32 v234, v206, v207
	v_cvt_pk_bf16_f32 v235, v208, v209
	v_cvt_pk_bf16_f32 v236, v210, v211
	v_cvt_pk_bf16_f32 v237, v212, v213
	global_store_dwordx4 v185, v[230:233], s[44:45] offset:2048 sc1
	global_store_dwordx4 v185, v[234:237], s[44:45] offset:3072 sc1
	s_waitcnt vmcnt(28)
	v_lshlrev_b32_e32 v116, 16, v148
	v_and_b32_e32 v117, 0xffff0000, v148
	v_lshlrev_b32_e32 v118, 16, v149
	v_and_b32_e32 v119, 0xffff0000, v149
	v_lshlrev_b32_e32 v120, 16, v150
	v_and_b32_e32 v121, 0xffff0000, v150
	v_lshlrev_b32_e32 v122, 16, v151
	v_and_b32_e32 v123, 0xffff0000, v151
	v_lshlrev_b32_e32 v124, 16, v152
	v_and_b32_e32 v125, 0xffff0000, v152
	v_lshlrev_b32_e32 v126, 16, v153
	v_and_b32_e32 v127, 0xffff0000, v153
	v_lshlrev_b32_e32 v128, 16, v154
	v_and_b32_e32 v129, 0xffff0000, v154
	v_lshlrev_b32_e32 v130, 16, v155
	v_and_b32_e32 v131, 0xffff0000, v155
	v_cvt_f32_f16_e32 v198, v64
	v_cvt_f32_f16_sdwa v199, v64 dst_sel:DWORD dst_unused:UNUSED_PAD src0_sel:WORD_1
	v_cvt_f32_f16_e32 v200, v65
	v_cvt_f32_f16_sdwa v201, v65 dst_sel:DWORD dst_unused:UNUSED_PAD src0_sel:WORD_1
	v_cvt_f32_f16_e32 v202, v66
	v_cvt_f32_f16_sdwa v203, v66 dst_sel:DWORD dst_unused:UNUSED_PAD src0_sel:WORD_1
	v_cvt_f32_f16_e32 v204, v67
	v_cvt_f32_f16_sdwa v205, v67 dst_sel:DWORD dst_unused:UNUSED_PAD src0_sel:WORD_1
	v_cvt_f32_f16_e32 v206, v68
	v_cvt_f32_f16_sdwa v207, v68 dst_sel:DWORD dst_unused:UNUSED_PAD src0_sel:WORD_1
	v_cvt_f32_f16_e32 v208, v69
	v_cvt_f32_f16_sdwa v209, v69 dst_sel:DWORD dst_unused:UNUSED_PAD src0_sel:WORD_1
	v_cvt_f32_f16_e32 v210, v70
	v_cvt_f32_f16_sdwa v211, v70 dst_sel:DWORD dst_unused:UNUSED_PAD src0_sel:WORD_1
	v_cvt_f32_f16_e32 v212, v71
	v_cvt_f32_f16_sdwa v213, v71 dst_sel:DWORD dst_unused:UNUSED_PAD src0_sel:WORD_1
	global_load_dwordx4 v[64:67], v187, s[42:43] offset:-4096
	global_load_dwordx4 v[68:71], v187, s[42:43] offset:-3072
	global_load_dwordx4 v[148:151], v187, s[44:45] offset:-4096
	global_load_dwordx4 v[152:155], v187, s[44:45] offset:-3072
	v_pk_mul_f32 v[140:141], v[116:117], v[116:117]
	v_pk_fma_f32 v[140:141], v[118:119], v[118:119], v[140:141]
	v_pk_fma_f32 v[140:141], v[120:121], v[120:121], v[140:141]
	v_pk_fma_f32 v[140:141], v[122:123], v[122:123], v[140:141]
	v_pk_fma_f32 v[140:141], v[124:125], v[124:125], v[140:141]
	v_pk_fma_f32 v[140:141], v[126:127], v[126:127], v[140:141]
	v_pk_fma_f32 v[140:141], v[128:129], v[128:129], v[140:141]
	v_pk_fma_f32 v[140:141], v[130:131], v[130:131], v[140:141]
	v_add_f32_e32 v140, v140, v141
	s_nop 1
	v_add_f32_dpp v140, v140, v140 quad_perm:[1,0,3,2] row_mask:0xf bank_mask:0xf
	s_nop 1
	v_add_f32_dpp v140, v140, v140 quad_perm:[2,3,0,1] row_mask:0xf bank_mask:0xf
	s_nop 1
	v_add_f32_dpp v140, v140, v140 row_ror:4 row_mask:0xf bank_mask:0xf
	s_nop 1
	v_add_f32_dpp v140, v140, v140 row_ror:8 row_mask:0xf bank_mask:0xf
	s_nop 1
	v_add_f32_dpp v140, v140, v140 row_bcast:15 row_mask:0xa bank_mask:0xf
	s_nop 1
	v_add_f32_dpp v140, v140, v140 row_bcast:31 row_mask:0xc bank_mask:0xf
	s_nop 1
	v_fmamk_f32 v140, v140, 0x3a800000, v224
	v_rsq_f32_e32 v140, v140
	s_nop 0
	v_mul_f32_e32 v140, v144, v140
	s_nop 0
	v_readlane_b32 s4, v140, 63
	s_nop 1
	v_pk_mul_f32 v[116:117], v[116:117], s[4:5] op_sel_hi:[1,0]
	v_pk_mul_f32 v[118:119], v[118:119], s[4:5] op_sel_hi:[1,0]
	v_pk_mul_f32 v[120:121], v[120:121], s[4:5] op_sel_hi:[1,0]
	v_pk_mul_f32 v[122:123], v[122:123], s[4:5] op_sel_hi:[1,0]
	v_pk_mul_f32 v[124:125], v[124:125], s[4:5] op_sel_hi:[1,0]
	v_pk_mul_f32 v[126:127], v[126:127], s[4:5] op_sel_hi:[1,0]
	v_pk_mul_f32 v[128:129], v[128:129], s[4:5] op_sel_hi:[1,0]
	v_pk_mul_f32 v[130:131], v[130:131], s[4:5] op_sel_hi:[1,0]
	v_pk_fma_f32 v[198:199], v[0:1], v[116:117], v[198:199]
	v_pk_fma_f32 v[200:201], v[2:3], v[118:119], v[200:201]
	v_pk_fma_f32 v[202:203], v[4:5], v[120:121], v[202:203]
; __device__ __forceinline__ unsigned pk2(float lo, float hi) { return pg8::cvt_pk_bf16(lo, hi); }
; __device__ __forceinline__ unsigned pkh2(float lo, float hi) { return (unsigned)__builtin_bit_cast(unsigned short, (_Float16)lo) | ((unsigned)__builtin_bit_cast(unsigned short, (_Float16)hi) << 16); }
; template <int R, bool SRCB> ...
;     ...
;                 for (int k = 0; k < 2; ++k) h[r][j][k] = h[r][j][k] + gg[j][k] * (y[j][k] * rr);
;         }
;     }
; #pragma unroll
;     for (int r = 0; r < R; ++r)
; #pragma unroll
;         for (int j = 0; j < 2; ++j) { const int c = 8 * lane + 512 * j;
;             if (final_out) { *(f32x4*)(final_out + (size_t)(row0 + r) * DM + c) = h[r][j][0]; *(f32x4*)(final_out + (size_t)(row0 + r) * DM + c + 4) = h[r][j][1]; }
;             else { u32x4 t; t.x = pkh2(h[r][j][0][0], h[r][j][0][1]); t.y = pkh2(h[r][j][0][2], h[r][j][0][3]); t.z = pkh2(h[r][j][1][0], h[r][j][1][1]); t.w = pkh2(h[r][j][1][2], h[r][j][1][3]);
;                 *(u32x4*)(hout + (size_t)(row0 + r) * DM + c) = t; } }
;     if (U) {
;         f32x4 gp[2][2], sc1[2][2], sh[2][2];
; #pragma unroll
;         for (int j = 0; j < 2; ++j)
; #pragma unroll
;             for (int k = 0; k < 2; ++k) { const int c = 8 * lane + 512 * j + 4 * k; gp[j][k] = *(const f32x4*)(gpre + c); sc1[j][k] = *(const f32x4*)(scale + (size_t)mrow * 9216 + c) + 1.0f; sh[j][k] = *(const f32x4*)(shift + (size_t)mrow * 9216 + c); }
; #pragma unroll
;         for (int r = 0; r < R; ++r) {
;             float ss = 0.f;
; #pragma unroll
;             for (int j = 0; j < 2; ++j)
; #pragma unroll
;                 for (int k = 0; k < 2; ++k) ss += (h[r][j][k][0] * h[r][j][k][0] + h[r][j][k][1] * h[r][j][k][1]) + (h[r][j][k][2] * h[r][j][k][2] + h[r][j][k][3] * h[r][j][k][3]);
;             const float rr = __builtin_amdgcn_rsqf(wave_sum(ss) * (1.0f / DM) + 1e-6f);
; #pragma unroll
;             for (int j = 0; j < 2; ++j) { const f32x4 v0 = (h[r][j][0] * rr * gp[j][0]) * sc1[j][0] + sh[j][0], v1 = (h[r][j][1] * rr * gp[j][1]) * sc1[j][1] + sh[j][1];
;                 u32x4 t; t.x = pk2(v0[0], v0[1]); t.y = pk2(v0[2], v0[3]); t.z = pk2(v1[0], v1[1]); t.w = pk2(v1[2], v1[3]);
;                 *(u32x4*)(U + (size_t)(row0 + r) * DM + 8 * lane + 512 * j) = t; }
	v_pk_fma_f32 v[204:205], v[6:7], v[122:123], v[204:205]
	v_pk_fma_f32 v[206:207], v[8:9], v[124:125], v[206:207]
	v_pk_fma_f32 v[208:209], v[10:11], v[126:127], v[208:209]
	v_pk_fma_f32 v[210:211], v[12:13], v[128:129], v[210:211]
	v_pk_fma_f32 v[212:213], v[14:15], v[130:131], v[212:213]
	v_cvt_f16_f32_e32 v132, v198
	v_cvt_f16_f32_e32 v133, v200
	v_cvt_f16_f32_e32 v134, v202
	v_cvt_f16_f32_e32 v135, v204
	v_cvt_f16_f32_e32 v136, v206
	v_cvt_f16_f32_e32 v137, v208
	v_cvt_f16_f32_e32 v138, v210
	v_cvt_f16_f32_e32 v139, v212
	v_cvt_f16_f32_sdwa v132, v199 dst_sel:WORD_1 dst_unused:UNUSED_PRESERVE src0_sel:DWORD
	v_cvt_f16_f32_sdwa v133, v201 dst_sel:WORD_1 dst_unused:UNUSED_PRESERVE src0_sel:DWORD
	v_cvt_f16_f32_sdwa v134, v203 dst_sel:WORD_1 dst_unused:UNUSED_PRESERVE src0_sel:DWORD
	v_cvt_f16_f32_sdwa v135, v205 dst_sel:WORD_1 dst_unused:UNUSED_PRESERVE src0_sel:DWORD
	v_cvt_f16_f32_sdwa v136, v207 dst_sel:WORD_1 dst_unused:UNUSED_PRESERVE src0_sel:DWORD
	v_cvt_f16_f32_sdwa v137, v209 dst_sel:WORD_1 dst_unused:UNUSED_PRESERVE src0_sel:DWORD
	v_cvt_f16_f32_sdwa v138, v211 dst_sel:WORD_1 dst_unused:UNUSED_PRESERVE src0_sel:DWORD
	v_cvt_f16_f32_sdwa v139, v213 dst_sel:WORD_1 dst_unused:UNUSED_PRESERVE src0_sel:DWORD
	s_nop 0
	global_store_dwordx4 v186, v[132:135], s[42:43] offset:-4096 sc1
	global_store_dwordx4 v186, v[136:139], s[42:43] offset:-3072 sc1
	v_pk_mul_f32 v[140:141], v[198:199], v[198:199]
	v_pk_fma_f32 v[140:141], v[200:201], v[200:201], v[140:141]
	v_pk_fma_f32 v[140:141], v[202:203], v[202:203], v[140:141]
	v_pk_fma_f32 v[140:141], v[204:205], v[204:205], v[140:141]
	v_pk_fma_f32 v[140:141], v[206:207], v[206:207], v[140:141]
	v_pk_fma_f32 v[140:141], v[208:209], v[208:209], v[140:141]
	v_pk_fma_f32 v[140:141], v[210:211], v[210:211], v[140:141]
	v_pk_fma_f32 v[140:141], v[212:213], v[212:213], v[140:141]
	v_add_f32_e32 v140, v140, v141
	s_nop 1
	v_add_f32_dpp v140, v140, v140 quad_perm:[1,0,3,2] row_mask:0xf bank_mask:0xf
	s_nop 1
	v_add_f32_dpp v140, v140, v140 quad_perm:[2,3,0,1] row_mask:0xf bank_mask:0xf
	s_nop 1
	v_add_f32_dpp v140, v140, v140 row_ror:4 row_mask:0xf bank_mask:0xf
	s_nop 1
	v_add_f32_dpp v140, v140, v140 row_ror:8 row_mask:0xf bank_mask:0xf
	s_nop 1
	v_add_f32_dpp v140, v140, v140 row_bcast:15 row_mask:0xa bank_mask:0xf
	s_nop 1
	v_add_f32_dpp v140, v140, v140 row_bcast:31 row_mask:0xc bank_mask:0xf
	s_nop 1
	v_fmamk_f32 v140, v140, 0x3a800000, v224
	v_rsq_f32_e32 v140, v140
	s_nop 0
	v_readlane_b32 s6, v140, 63
	s_nop 1
	v_pk_mul_f32 v[198:199], v[198:199], s[6:7] op_sel_hi:[1,0]
	v_pk_mul_f32 v[200:201], v[200:201], s[6:7] op_sel_hi:[1,0]
	v_pk_mul_f32 v[202:203], v[202:203], s[6:7] op_sel_hi:[1,0]
	v_pk_mul_f32 v[204:205], v[204:205], s[6:7] op_sel_hi:[1,0]
	v_pk_mul_f32 v[206:207], v[206:207], s[6:7] op_sel_hi:[1,0]
	v_pk_mul_f32 v[208:209], v[208:209], s[6:7] op_sel_hi:[1,0]
	v_pk_mul_f32 v[210:211], v[210:211], s[6:7] op_sel_hi:[1,0]
	v_pk_mul_f32 v[212:213], v[212:213], s[6:7] op_sel_hi:[1,0]
	v_pk_mul_f32 v[198:199], v[16:17], v[198:199]
	v_pk_mul_f32 v[200:201], v[18:19], v[200:201]
	v_pk_mul_f32 v[202:203], v[20:21], v[202:203]
	v_pk_mul_f32 v[204:205], v[22:23], v[204:205]
	v_pk_mul_f32 v[206:207], v[24:25], v[206:207]
	v_pk_mul_f32 v[208:209], v[26:27], v[208:209]
	v_pk_mul_f32 v[210:211], v[28:29], v[210:211]
	v_pk_mul_f32 v[212:213], v[30:31], v[212:213]
	v_pk_fma_f32 v[198:199], v[32:33], v[198:199], v[48:49]
	v_pk_fma_f32 v[200:201], v[34:35], v[200:201], v[50:51]
	v_pk_fma_f32 v[202:203], v[36:37], v[202:203], v[52:53]
	v_pk_fma_f32 v[204:205], v[38:39], v[204:205], v[54:55]
	v_pk_fma_f32 v[206:207], v[40:41], v[206:207], v[56:57]
	v_pk_fma_f32 v[208:209], v[42:43], v[208:209], v[58:59]
	v_pk_fma_f32 v[210:211], v[44:45], v[210:211], v[60:61]
	v_pk_fma_f32 v[212:213], v[46:47], v[212:213], v[62:63]
	v_cvt_pk_bf16_f32 v230, v198, v199
	v_cvt_pk_bf16_f32 v231, v200, v201
	v_cvt_pk_bf16_f32 v232, v202, v203
	v_cvt_pk_bf16_f32 v233, v204, v205
	v_cvt_pk_bf16_f32 v234, v206, v207
	v_cvt_pk_bf16_f32 v235, v208, v209
	v_cvt_pk_bf16_f32 v236, v210, v211
	v_cvt_pk_bf16_f32 v237, v212, v213
	global_store_dwordx4 v186, v[230:233], s[44:45] offset:-4096 sc1
	global_store_dwordx4 v186, v[234:237], s[44:45] offset:-3072 sc1
	s_waitcnt vmcnt(28)
; template <int R, bool SRCB> ...
;     ...
;         for (int r = 0; r < R; ++r) {
;             f32x4 y[2][2]; float ss = 0.f;
; #pragma unroll
;             for (int j = 0; j < 2; ++j) { const u32x4 t = yr[r][j];
;                 y[j][0] = (f32x4){bf_lo(t.x), bf_hi(t.x), bf_lo(t.y), bf_hi(t.y)}; y[j][1] = (f32x4){bf_lo(t.z), bf_hi(t.z), bf_lo(t.w), bf_hi(t.w)};
;                 if (R == 1 && YP) {
; #pragma unroll
;                     for (int k = 0; k < 2; ++k) { const float* pp = YP + (size_t)(row0 - M_LAT) * DM + 8 * lane + 512 * j + 4 * k; f32x4 s = *(const f32x4*)pp;
; #pragma unroll
;                         for (int q = 1; q < pg8::NSL; ++q) s = s + *(const f32x4*)(pp + (size_t)q * 2048 * DM);
;                         y[j][k] = s; } }
; #pragma unroll
;                 for (int k = 0; k < 2; ++k) ss += (y[j][k][0] * y[j][k][0] + y[j][k][1] * y[j][k][1]) + (y[j][k][2] * y[j][k][2] + y[j][k][3] * y[j][k][3]); }
;             const float rr = __builtin_amdgcn_rsqf(wave_sum(ss) * (1.0f / DM) + 1e-6f) * w;
; #pragma unroll
;             for (int j = 0; j < 2; ++j)
; #pragma unroll
;                 for (int k = 0; k < 2; ++k) h[r][j][k] = h[r][j][k] + gg[j][k] * (y[j][k] * rr);
;         }
;     }
; #pragma unroll
;     for (int r = 0; r < R; ++r)
; #pragma unroll
;         for (int j = 0; j < 2; ++j) { const int c = 8 * lane + 512 * j;
;             if (final_out) { *(f32x4*)(final_out + (size_t)(row0 + r) * DM + c) = h[r][j][0]; *(f32x4*)(final_out + (size_t)(row0 + r) * DM + c + 4) = h[r][j][1]; }
;             else { u32x4 t; t.x = pkh2(h[r][j][0][0], h[r][j][0][1]); t.y = pkh2(h[r][j][0][2], h[r][j][0][3]); t.z = pkh2(h[r][j][1][0], h[r][j][1][1]); t.w = pkh2(h[r][j][1][2], h[r][j][1][3]);
;                 *(u32x4*)(hout + (size_t)(row0 + r) * DM + c) = t; } }
;     if (U) {
;         f32x4 gp[2][2], sc1[2][2], sh[2][2];
; #pragma unroll
;         for (int j = 0; j < 2; ++j)
; #pragma unroll
;             for (int k = 0; k < 2; ++k) { const int c = 8 * lane + 512 * j + 4 * k; gp[j][k] = *(const f32x4*)(gpre + c); sc1[j][k] = *(const f32x4*)(scale + (size_t)mrow * 9216 + c) + 1.0f; sh[j][k] = *(const f32x4*)(shift + (size_t)mrow * 9216 + c); }
; #pragma unroll
;         for (int r = 0; r < R; ++r) {
;             float ss = 0.f;
; #pragma unroll
;             for (int j = 0; j < 2; ++j)
; #pragma unroll
	v_lshlrev_b32_e32 v116, 16, v156
	v_and_b32_e32 v117, 0xffff0000, v156
	v_lshlrev_b32_e32 v118, 16, v157
	v_and_b32_e32 v119, 0xffff0000, v157
	v_lshlrev_b32_e32 v120, 16, v158
	v_and_b32_e32 v121, 0xffff0000, v158
	v_lshlrev_b32_e32 v122, 16, v159
	v_and_b32_e32 v123, 0xffff0000, v159
	v_lshlrev_b32_e32 v124, 16, v160
	v_and_b32_e32 v125, 0xffff0000, v160
	v_lshlrev_b32_e32 v126, 16, v161
	v_and_b32_e32 v127, 0xffff0000, v161
	v_lshlrev_b32_e32 v128, 16, v162
	v_and_b32_e32 v129, 0xffff0000, v162
	v_lshlrev_b32_e32 v130, 16, v163
	v_and_b32_e32 v131, 0xffff0000, v163
	v_cvt_f32_f16_e32 v198, v72
	v_cvt_f32_f16_sdwa v199, v72 dst_sel:DWORD dst_unused:UNUSED_PAD src0_sel:WORD_1
	v_cvt_f32_f16_e32 v200, v73
	v_cvt_f32_f16_sdwa v201, v73 dst_sel:DWORD dst_unused:UNUSED_PAD src0_sel:WORD_1
	v_cvt_f32_f16_e32 v202, v74
	v_cvt_f32_f16_sdwa v203, v74 dst_sel:DWORD dst_unused:UNUSED_PAD src0_sel:WORD_1
	v_cvt_f32_f16_e32 v204, v75
	v_cvt_f32_f16_sdwa v205, v75 dst_sel:DWORD dst_unused:UNUSED_PAD src0_sel:WORD_1
	v_cvt_f32_f16_e32 v206, v76
	v_cvt_f32_f16_sdwa v207, v76 dst_sel:DWORD dst_unused:UNUSED_PAD src0_sel:WORD_1
	v_cvt_f32_f16_e32 v208, v77
	v_cvt_f32_f16_sdwa v209, v77 dst_sel:DWORD dst_unused:UNUSED_PAD src0_sel:WORD_1
	v_cvt_f32_f16_e32 v210, v78
	v_cvt_f32_f16_sdwa v211, v78 dst_sel:DWORD dst_unused:UNUSED_PAD src0_sel:WORD_1
	v_cvt_f32_f16_e32 v212, v79
	v_cvt_f32_f16_sdwa v213, v79 dst_sel:DWORD dst_unused:UNUSED_PAD src0_sel:WORD_1
	global_load_dwordx4 v[72:75], v187, s[42:43] offset:-2048
	global_load_dwordx4 v[76:79], v187, s[42:43] offset:-1024
	global_load_dwordx4 v[156:159], v187, s[44:45] offset:-2048
	global_load_dwordx4 v[160:163], v187, s[44:45] offset:-1024
	v_pk_mul_f32 v[140:141], v[116:117], v[116:117]
	v_pk_fma_f32 v[140:141], v[118:119], v[118:119], v[140:141]
	v_pk_fma_f32 v[140:141], v[120:121], v[120:121], v[140:141]
	v_pk_fma_f32 v[140:141], v[122:123], v[122:123], v[140:141]
	v_pk_fma_f32 v[140:141], v[124:125], v[124:125], v[140:141]
	v_pk_fma_f32 v[140:141], v[126:127], v[126:127], v[140:141]
	v_pk_fma_f32 v[140:141], v[128:129], v[128:129], v[140:141]
	v_pk_fma_f32 v[140:141], v[130:131], v[130:131], v[140:141]
	v_add_f32_e32 v140, v140, v141
	s_nop 1
	v_add_f32_dpp v140, v140, v140 quad_perm:[1,0,3,2] row_mask:0xf bank_mask:0xf
	s_nop 1
	v_add_f32_dpp v140, v140, v140 quad_perm:[2,3,0,1] row_mask:0xf bank_mask:0xf
	s_nop 1
	v_add_f32_dpp v140, v140, v140 row_ror:4 row_mask:0xf bank_mask:0xf
	s_nop 1
	v_add_f32_dpp v140, v140, v140 row_ror:8 row_mask:0xf bank_mask:0xf
	s_nop 1
	v_add_f32_dpp v140, v140, v140 row_bcast:15 row_mask:0xa bank_mask:0xf
	s_nop 1
	v_add_f32_dpp v140, v140, v140 row_bcast:31 row_mask:0xc bank_mask:0xf
	s_nop 1
	v_fmamk_f32 v140, v140, 0x3a800000, v224
	v_rsq_f32_e32 v140, v140
	s_nop 0
	v_mul_f32_e32 v140, v144, v140
	s_nop 0
	v_readlane_b32 s4, v140, 63
	s_nop 1
	v_pk_mul_f32 v[116:117], v[116:117], s[4:5] op_sel_hi:[1,0]
	v_pk_mul_f32 v[118:119], v[118:119], s[4:5] op_sel_hi:[1,0]
	v_pk_mul_f32 v[120:121], v[120:121], s[4:5] op_sel_hi:[1,0]
	v_pk_mul_f32 v[122:123], v[122:123], s[4:5] op_sel_hi:[1,0]
	v_pk_mul_f32 v[124:125], v[124:125], s[4:5] op_sel_hi:[1,0]
	v_pk_mul_f32 v[126:127], v[126:127], s[4:5] op_sel_hi:[1,0]
	v_pk_mul_f32 v[128:129], v[128:129], s[4:5] op_sel_hi:[1,0]
	v_pk_mul_f32 v[130:131], v[130:131], s[4:5] op_sel_hi:[1,0]
	v_pk_fma_f32 v[198:199], v[0:1], v[116:117], v[198:199]
	v_pk_fma_f32 v[200:201], v[2:3], v[118:119], v[200:201]
	v_pk_fma_f32 v[202:203], v[4:5], v[120:121], v[202:203]
	v_pk_fma_f32 v[204:205], v[6:7], v[122:123], v[204:205]
	v_pk_fma_f32 v[206:207], v[8:9], v[124:125], v[206:207]
	v_pk_fma_f32 v[208:209], v[10:11], v[126:127], v[208:209]
	v_pk_fma_f32 v[210:211], v[12:13], v[128:129], v[210:211]
	v_pk_fma_f32 v[212:213], v[14:15], v[130:131], v[212:213]
	v_cvt_f16_f32_e32 v132, v198
	v_cvt_f16_f32_e32 v133, v200
	v_cvt_f16_f32_e32 v134, v202
	v_cvt_f16_f32_e32 v135, v204
	v_cvt_f16_f32_e32 v136, v206
	v_cvt_f16_f32_e32 v137, v208
	v_cvt_f16_f32_e32 v138, v210
	v_cvt_f16_f32_e32 v139, v212
	v_cvt_f16_f32_sdwa v132, v199 dst_sel:WORD_1 dst_unused:UNUSED_PRESERVE src0_sel:DWORD
	v_cvt_f16_f32_sdwa v133, v201 dst_sel:WORD_1 dst_unused:UNUSED_PRESERVE src0_sel:DWORD
	v_cvt_f16_f32_sdwa v134, v203 dst_sel:WORD_1 dst_unused:UNUSED_PRESERVE src0_sel:DWORD
	v_cvt_f16_f32_sdwa v135, v205 dst_sel:WORD_1 dst_unused:UNUSED_PRESERVE src0_sel:DWORD
	v_cvt_f16_f32_sdwa v136, v207 dst_sel:WORD_1 dst_unused:UNUSED_PRESERVE src0_sel:DWORD
	v_cvt_f16_f32_sdwa v137, v209 dst_sel:WORD_1 dst_unused:UNUSED_PRESERVE src0_sel:DWORD
	v_cvt_f16_f32_sdwa v138, v211 dst_sel:WORD_1 dst_unused:UNUSED_PRESERVE src0_sel:DWORD
	v_cvt_f16_f32_sdwa v139, v213 dst_sel:WORD_1 dst_unused:UNUSED_PRESERVE src0_sel:DWORD
	s_nop 0
	global_store_dwordx4 v186, v[132:135], s[42:43] offset:-2048 sc1
	global_store_dwordx4 v186, v[136:139], s[42:43] offset:-1024 sc1
	v_pk_mul_f32 v[140:141], v[198:199], v[198:199]
	v_pk_fma_f32 v[140:141], v[200:201], v[200:201], v[140:141]
	v_pk_fma_f32 v[140:141], v[202:203], v[202:203], v[140:141]
	v_pk_fma_f32 v[140:141], v[204:205], v[204:205], v[140:141]
	v_pk_fma_f32 v[140:141], v[206:207], v[206:207], v[140:141]
	v_pk_fma_f32 v[140:141], v[208:209], v[208:209], v[140:141]
	v_pk_fma_f32 v[140:141], v[210:211], v[210:211], v[140:141]
	v_pk_fma_f32 v[140:141], v[212:213], v[212:213], v[140:141]
	v_add_f32_e32 v140, v140, v141
	s_nop 1
	v_add_f32_dpp v140, v140, v140 quad_perm:[1,0,3,2] row_mask:0xf bank_mask:0xf
	s_nop 1
	v_add_f32_dpp v140, v140, v140 quad_perm:[2,3,0,1] row_mask:0xf bank_mask:0xf
	s_nop 1
	v_add_f32_dpp v140, v140, v140 row_ror:4 row_mask:0xf bank_mask:0xf
; template <int R, bool SRCB> ...
;     ...
;         for (int r = 0; r < R; ++r) {
;             f32x4 y[2][2]; float ss = 0.f;
; #pragma unroll
;             for (int j = 0; j < 2; ++j) { const u32x4 t = yr[r][j];
;                 y[j][0] = (f32x4){bf_lo(t.x), bf_hi(t.x), bf_lo(t.y), bf_hi(t.y)}; y[j][1] = (f32x4){bf_lo(t.z), bf_hi(t.z), bf_lo(t.w), bf_hi(t.w)};
;                 if (R == 1 && YP) {
; #pragma unroll
;                     for (int k = 0; k < 2; ++k) { const float* pp = YP + (size_t)(row0 - M_LAT) * DM + 8 * lane + 512 * j + 4 * k; f32x4 s = *(const f32x4*)pp;
; #pragma unroll
;                         for (int q = 1; q < pg8::NSL; ++q) s = s + *(const f32x4*)(pp + (size_t)q * 2048 * DM);
;                         y[j][k] = s; } }
; #pragma unroll
;                 for (int k = 0; k < 2; ++k) ss += (y[j][k][0] * y[j][k][0] + y[j][k][1] * y[j][k][1]) + (y[j][k][2] * y[j][k][2] + y[j][k][3] * y[j][k][3]); }
;             const float rr = __builtin_amdgcn_rsqf(wave_sum(ss) * (1.0f / DM) + 1e-6f) * w;
; #pragma unroll
;             for (int j = 0; j < 2; ++j)
; #pragma unroll
;                 for (int k = 0; k < 2; ++k) h[r][j][k] = h[r][j][k] + gg[j][k] * (y[j][k] * rr);
;         }
;     }
; #pragma unroll
;     for (int r = 0; r < R; ++r)
; #pragma unroll
;         for (int j = 0; j < 2; ++j) { const int c = 8 * lane + 512 * j;
;             if (final_out) { *(f32x4*)(final_out + (size_t)(row0 + r) * DM + c) = h[r][j][0]; *(f32x4*)(final_out + (size_t)(row0 + r) * DM + c + 4) = h[r][j][1]; }
;             else { u32x4 t; t.x = pkh2(h[r][j][0][0], h[r][j][0][1]); t.y = pkh2(h[r][j][0][2], h[r][j][0][3]); t.z = pkh2(h[r][j][1][0], h[r][j][1][1]); t.w = pkh2(h[r][j][1][2], h[r][j][1][3]);
;                 *(u32x4*)(hout + (size_t)(row0 + r) * DM + c) = t; } }
;     if (U) {
;         f32x4 gp[2][2], sc1[2][2], sh[2][2];
; #pragma unroll
;         for (int j = 0; j < 2; ++j)
; #pragma unroll
;             for (int k = 0; k < 2; ++k) { const int c = 8 * lane + 512 * j + 4 * k; gp[j][k] = *(const f32x4*)(gpre + c); sc1[j][k] = *(const f32x4*)(scale + (size_t)mrow * 9216 + c) + 1.0f; sh[j][k] = *(const f32x4*)(shift + (size_t)mrow * 9216 + c); }
; #pragma unroll
;         for (int r = 0; r < R; ++r) {
;             float ss = 0.f;
; #pragma unroll
;             for (int j = 0; j < 2; ++j)
; #pragma unroll
	s_nop 1
	v_add_f32_dpp v140, v140, v140 row_ror:8 row_mask:0xf bank_mask:0xf
	s_nop 1
	v_add_f32_dpp v140, v140, v140 row_bcast:15 row_mask:0xa bank_mask:0xf
	s_nop 1
	v_add_f32_dpp v140, v140, v140 row_bcast:31 row_mask:0xc bank_mask:0xf
	s_nop 1
	v_fmamk_f32 v140, v140, 0x3a800000, v224
	v_rsq_f32_e32 v140, v140
	s_nop 0
	v_readlane_b32 s6, v140, 63
	s_nop 1
	v_pk_mul_f32 v[198:199], v[198:199], s[6:7] op_sel_hi:[1,0]
	v_pk_mul_f32 v[200:201], v[200:201], s[6:7] op_sel_hi:[1,0]
	v_pk_mul_f32 v[202:203], v[202:203], s[6:7] op_sel_hi:[1,0]
	v_pk_mul_f32 v[204:205], v[204:205], s[6:7] op_sel_hi:[1,0]
	v_pk_mul_f32 v[206:207], v[206:207], s[6:7] op_sel_hi:[1,0]
	v_pk_mul_f32 v[208:209], v[208:209], s[6:7] op_sel_hi:[1,0]
	v_pk_mul_f32 v[210:211], v[210:211], s[6:7] op_sel_hi:[1,0]
	v_pk_mul_f32 v[212:213], v[212:213], s[6:7] op_sel_hi:[1,0]
	v_pk_mul_f32 v[198:199], v[16:17], v[198:199]
	v_pk_mul_f32 v[200:201], v[18:19], v[200:201]
	v_pk_mul_f32 v[202:203], v[20:21], v[202:203]
	v_pk_mul_f32 v[204:205], v[22:23], v[204:205]
	v_pk_mul_f32 v[206:207], v[24:25], v[206:207]
	v_pk_mul_f32 v[208:209], v[26:27], v[208:209]
	v_pk_mul_f32 v[210:211], v[28:29], v[210:211]
	v_pk_mul_f32 v[212:213], v[30:31], v[212:213]
	v_pk_fma_f32 v[198:199], v[32:33], v[198:199], v[48:49]
	v_pk_fma_f32 v[200:201], v[34:35], v[200:201], v[50:51]
	v_pk_fma_f32 v[202:203], v[36:37], v[202:203], v[52:53]
	v_pk_fma_f32 v[204:205], v[38:39], v[204:205], v[54:55]
	v_pk_fma_f32 v[206:207], v[40:41], v[206:207], v[56:57]
	v_pk_fma_f32 v[208:209], v[42:43], v[208:209], v[58:59]
	v_pk_fma_f32 v[210:211], v[44:45], v[210:211], v[60:61]
	v_pk_fma_f32 v[212:213], v[46:47], v[212:213], v[62:63]
	v_cvt_pk_bf16_f32 v230, v198, v199
	v_cvt_pk_bf16_f32 v231, v200, v201
	v_cvt_pk_bf16_f32 v232, v202, v203
	v_cvt_pk_bf16_f32 v233, v204, v205
	v_cvt_pk_bf16_f32 v234, v206, v207
	v_cvt_pk_bf16_f32 v235, v208, v209
	v_cvt_pk_bf16_f32 v236, v210, v211
	v_cvt_pk_bf16_f32 v237, v212, v213
	global_store_dwordx4 v186, v[230:233], s[44:45] offset:-2048 sc1
	global_store_dwordx4 v186, v[234:237], s[44:45] offset:-1024 sc1
	s_waitcnt vmcnt(28)
	v_lshlrev_b32_e32 v116, 16, v164
	v_and_b32_e32 v117, 0xffff0000, v164
	v_lshlrev_b32_e32 v118, 16, v165
	v_and_b32_e32 v119, 0xffff0000, v165
	v_lshlrev_b32_e32 v120, 16, v166
	v_and_b32_e32 v121, 0xffff0000, v166
	v_lshlrev_b32_e32 v122, 16, v167
	v_and_b32_e32 v123, 0xffff0000, v167
	v_lshlrev_b32_e32 v124, 16, v168
	v_and_b32_e32 v125, 0xffff0000, v168
	v_lshlrev_b32_e32 v126, 16, v169
	v_and_b32_e32 v127, 0xffff0000, v169
	v_lshlrev_b32_e32 v128, 16, v170
	v_and_b32_e32 v129, 0xffff0000, v170
	v_lshlrev_b32_e32 v130, 16, v171
	v_and_b32_e32 v131, 0xffff0000, v171
	v_cvt_f32_f16_e32 v198, v80
	v_cvt_f32_f16_sdwa v199, v80 dst_sel:DWORD dst_unused:UNUSED_PAD src0_sel:WORD_1
	v_cvt_f32_f16_e32 v200, v81
	v_cvt_f32_f16_sdwa v201, v81 dst_sel:DWORD dst_unused:UNUSED_PAD src0_sel:WORD_1
	v_cvt_f32_f16_e32 v202, v82
	v_cvt_f32_f16_sdwa v203, v82 dst_sel:DWORD dst_unused:UNUSED_PAD src0_sel:WORD_1
	v_cvt_f32_f16_e32 v204, v83
	v_cvt_f32_f16_sdwa v205, v83 dst_sel:DWORD dst_unused:UNUSED_PAD src0_sel:WORD_1
	v_cvt_f32_f16_e32 v206, v84
	v_cvt_f32_f16_sdwa v207, v84 dst_sel:DWORD dst_unused:UNUSED_PAD src0_sel:WORD_1
	v_cvt_f32_f16_e32 v208, v85
	v_cvt_f32_f16_sdwa v209, v85 dst_sel:DWORD dst_unused:UNUSED_PAD src0_sel:WORD_1
	v_cvt_f32_f16_e32 v210, v86
	v_cvt_f32_f16_sdwa v211, v86 dst_sel:DWORD dst_unused:UNUSED_PAD src0_sel:WORD_1
	v_cvt_f32_f16_e32 v212, v87
	v_cvt_f32_f16_sdwa v213, v87 dst_sel:DWORD dst_unused:UNUSED_PAD src0_sel:WORD_1
	global_load_dwordx4 v[80:83], v187, s[42:43] offset:0
	global_load_dwordx4 v[84:87], v187, s[42:43] offset:1024
	global_load_dwordx4 v[164:167], v187, s[44:45] offset:0
	global_load_dwordx4 v[168:171], v187, s[44:45] offset:1024
	v_pk_mul_f32 v[140:141], v[116:117], v[116:117]
	v_pk_fma_f32 v[140:141], v[118:119], v[118:119], v[140:141]
	v_pk_fma_f32 v[140:141], v[120:121], v[120:121], v[140:141]
	v_pk_fma_f32 v[140:141], v[122:123], v[122:123], v[140:141]
	v_pk_fma_f32 v[140:141], v[124:125], v[124:125], v[140:141]
	v_pk_fma_f32 v[140:141], v[126:127], v[126:127], v[140:141]
	v_pk_fma_f32 v[140:141], v[128:129], v[128:129], v[140:141]
	v_pk_fma_f32 v[140:141], v[130:131], v[130:131], v[140:141]
	v_add_f32_e32 v140, v140, v141
	s_nop 1
	v_add_f32_dpp v140, v140, v140 quad_perm:[1,0,3,2] row_mask:0xf bank_mask:0xf
	s_nop 1
	v_add_f32_dpp v140, v140, v140 quad_perm:[2,3,0,1] row_mask:0xf bank_mask:0xf
	s_nop 1
	v_add_f32_dpp v140, v140, v140 row_ror:4 row_mask:0xf bank_mask:0xf
	s_nop 1
	v_add_f32_dpp v140, v140, v140 row_ror:8 row_mask:0xf bank_mask:0xf
	s_nop 1
	v_add_f32_dpp v140, v140, v140 row_bcast:15 row_mask:0xa bank_mask:0xf
	s_nop 1
	v_add_f32_dpp v140, v140, v140 row_bcast:31 row_mask:0xc bank_mask:0xf
	s_nop 1
	v_fmamk_f32 v140, v140, 0x3a800000, v224
	v_rsq_f32_e32 v140, v140
	s_nop 0
	v_mul_f32_e32 v140, v144, v140
	s_nop 0
	v_readlane_b32 s4, v140, 63
	s_nop 1
	v_pk_mul_f32 v[116:117], v[116:117], s[4:5] op_sel_hi:[1,0]
	v_pk_mul_f32 v[118:119], v[118:119], s[4:5] op_sel_hi:[1,0]
	v_pk_mul_f32 v[120:121], v[120:121], s[4:5] op_sel_hi:[1,0]
	v_pk_mul_f32 v[122:123], v[122:123], s[4:5] op_sel_hi:[1,0]
	v_pk_mul_f32 v[124:125], v[124:125], s[4:5] op_sel_hi:[1,0]
	v_pk_mul_f32 v[126:127], v[126:127], s[4:5] op_sel_hi:[1,0]
	v_pk_mul_f32 v[128:129], v[128:129], s[4:5] op_sel_hi:[1,0]
	v_pk_mul_f32 v[130:131], v[130:131], s[4:5] op_sel_hi:[1,0]
	v_pk_fma_f32 v[198:199], v[0:1], v[116:117], v[198:199]
	v_pk_fma_f32 v[200:201], v[2:3], v[118:119], v[200:201]
	v_pk_fma_f32 v[202:203], v[4:5], v[120:121], v[202:203]
; __device__ __forceinline__ unsigned pk2(float lo, float hi) { return pg8::cvt_pk_bf16(lo, hi); }
; __device__ __forceinline__ unsigned pkh2(float lo, float hi) { return (unsigned)__builtin_bit_cast(unsigned short, (_Float16)lo) | ((unsigned)__builtin_bit_cast(unsigned short, (_Float16)hi) << 16); }
; template <int R, bool SRCB> ...
;     ...
;                 for (int k = 0; k < 2; ++k) h[r][j][k] = h[r][j][k] + gg[j][k] * (y[j][k] * rr);
;         }
;     }
; #pragma unroll
;     for (int r = 0; r < R; ++r)
; #pragma unroll
;         for (int j = 0; j < 2; ++j) { const int c = 8 * lane + 512 * j;
;             if (final_out) { *(f32x4*)(final_out + (size_t)(row0 + r) * DM + c) = h[r][j][0]; *(f32x4*)(final_out + (size_t)(row0 + r) * DM + c + 4) = h[r][j][1]; }
;             else { u32x4 t; t.x = pkh2(h[r][j][0][0], h[r][j][0][1]); t.y = pkh2(h[r][j][0][2], h[r][j][0][3]); t.z = pkh2(h[r][j][1][0], h[r][j][1][1]); t.w = pkh2(h[r][j][1][2], h[r][j][1][3]);
;                 *(u32x4*)(hout + (size_t)(row0 + r) * DM + c) = t; } }
;     if (U) {
;         f32x4 gp[2][2], sc1[2][2], sh[2][2];
; #pragma unroll
;         for (int j = 0; j < 2; ++j)
; #pragma unroll
;             for (int k = 0; k < 2; ++k) { const int c = 8 * lane + 512 * j + 4 * k; gp[j][k] = *(const f32x4*)(gpre + c); sc1[j][k] = *(const f32x4*)(scale + (size_t)mrow * 9216 + c) + 1.0f; sh[j][k] = *(const f32x4*)(shift + (size_t)mrow * 9216 + c); }
; #pragma unroll
;         for (int r = 0; r < R; ++r) {
;             float ss = 0.f;
; #pragma unroll
;             for (int j = 0; j < 2; ++j)
; #pragma unroll
;                 for (int k = 0; k < 2; ++k) ss += (h[r][j][k][0] * h[r][j][k][0] + h[r][j][k][1] * h[r][j][k][1]) + (h[r][j][k][2] * h[r][j][k][2] + h[r][j][k][3] * h[r][j][k][3]);
;             const float rr = __builtin_amdgcn_rsqf(wave_sum(ss) * (1.0f / DM) + 1e-6f);
; #pragma unroll
;             for (int j = 0; j < 2; ++j) { const f32x4 v0 = (h[r][j][0] * rr * gp[j][0]) * sc1[j][0] + sh[j][0], v1 = (h[r][j][1] * rr * gp[j][1]) * sc1[j][1] + sh[j][1];
;                 u32x4 t; t.x = pk2(v0[0], v0[1]); t.y = pk2(v0[2], v0[3]); t.z = pk2(v1[0], v1[1]); t.w = pk2(v1[2], v1[3]);
;                 *(u32x4*)(U + (size_t)(row0 + r) * DM + 8 * lane + 512 * j) = t; }
	v_pk_fma_f32 v[204:205], v[6:7], v[122:123], v[204:205]
	v_pk_fma_f32 v[206:207], v[8:9], v[124:125], v[206:207]
	v_pk_fma_f32 v[208:209], v[10:11], v[126:127], v[208:209]
	v_pk_fma_f32 v[210:211], v[12:13], v[128:129], v[210:211]
	v_pk_fma_f32 v[212:213], v[14:15], v[130:131], v[212:213]
	v_cvt_f16_f32_e32 v132, v198
	v_cvt_f16_f32_e32 v133, v200
	v_cvt_f16_f32_e32 v134, v202
	v_cvt_f16_f32_e32 v135, v204
	v_cvt_f16_f32_e32 v136, v206
	v_cvt_f16_f32_e32 v137, v208
	v_cvt_f16_f32_e32 v138, v210
	v_cvt_f16_f32_e32 v139, v212
	v_cvt_f16_f32_sdwa v132, v199 dst_sel:WORD_1 dst_unused:UNUSED_PRESERVE src0_sel:DWORD
	v_cvt_f16_f32_sdwa v133, v201 dst_sel:WORD_1 dst_unused:UNUSED_PRESERVE src0_sel:DWORD
	v_cvt_f16_f32_sdwa v134, v203 dst_sel:WORD_1 dst_unused:UNUSED_PRESERVE src0_sel:DWORD
	v_cvt_f16_f32_sdwa v135, v205 dst_sel:WORD_1 dst_unused:UNUSED_PRESERVE src0_sel:DWORD
	v_cvt_f16_f32_sdwa v136, v207 dst_sel:WORD_1 dst_unused:UNUSED_PRESERVE src0_sel:DWORD
	v_cvt_f16_f32_sdwa v137, v209 dst_sel:WORD_1 dst_unused:UNUSED_PRESERVE src0_sel:DWORD
	v_cvt_f16_f32_sdwa v138, v211 dst_sel:WORD_1 dst_unused:UNUSED_PRESERVE src0_sel:DWORD
	v_cvt_f16_f32_sdwa v139, v213 dst_sel:WORD_1 dst_unused:UNUSED_PRESERVE src0_sel:DWORD
	s_nop 0
	global_store_dwordx4 v186, v[132:135], s[42:43] offset:0 sc1
	global_store_dwordx4 v186, v[136:139], s[42:43] offset:1024 sc1
	v_pk_mul_f32 v[140:141], v[198:199], v[198:199]
	v_pk_fma_f32 v[140:141], v[200:201], v[200:201], v[140:141]
	v_pk_fma_f32 v[140:141], v[202:203], v[202:203], v[140:141]
	v_pk_fma_f32 v[140:141], v[204:205], v[204:205], v[140:141]
	v_pk_fma_f32 v[140:141], v[206:207], v[206:207], v[140:141]
	v_pk_fma_f32 v[140:141], v[208:209], v[208:209], v[140:141]
	v_pk_fma_f32 v[140:141], v[210:211], v[210:211], v[140:141]
	v_pk_fma_f32 v[140:141], v[212:213], v[212:213], v[140:141]
	v_add_f32_e32 v140, v140, v141
	s_nop 1
	v_add_f32_dpp v140, v140, v140 quad_perm:[1,0,3,2] row_mask:0xf bank_mask:0xf
	s_nop 1
	v_add_f32_dpp v140, v140, v140 quad_perm:[2,3,0,1] row_mask:0xf bank_mask:0xf
	s_nop 1
	v_add_f32_dpp v140, v140, v140 row_ror:4 row_mask:0xf bank_mask:0xf
	s_nop 1
	v_add_f32_dpp v140, v140, v140 row_ror:8 row_mask:0xf bank_mask:0xf
	s_nop 1
	v_add_f32_dpp v140, v140, v140 row_bcast:15 row_mask:0xa bank_mask:0xf
	s_nop 1
	v_add_f32_dpp v140, v140, v140 row_bcast:31 row_mask:0xc bank_mask:0xf
	s_nop 1
	v_fmamk_f32 v140, v140, 0x3a800000, v224
	v_rsq_f32_e32 v140, v140
	s_nop 0
	v_readlane_b32 s6, v140, 63
	s_nop 1
	v_pk_mul_f32 v[198:199], v[198:199], s[6:7] op_sel_hi:[1,0]
	v_pk_mul_f32 v[200:201], v[200:201], s[6:7] op_sel_hi:[1,0]
	v_pk_mul_f32 v[202:203], v[202:203], s[6:7] op_sel_hi:[1,0]
	v_pk_mul_f32 v[204:205], v[204:205], s[6:7] op_sel_hi:[1,0]
	v_pk_mul_f32 v[206:207], v[206:207], s[6:7] op_sel_hi:[1,0]
	v_pk_mul_f32 v[208:209], v[208:209], s[6:7] op_sel_hi:[1,0]
	v_pk_mul_f32 v[210:211], v[210:211], s[6:7] op_sel_hi:[1,0]
	v_pk_mul_f32 v[212:213], v[212:213], s[6:7] op_sel_hi:[1,0]
	v_pk_mul_f32 v[198:199], v[16:17], v[198:199]
	v_pk_mul_f32 v[200:201], v[18:19], v[200:201]
	v_pk_mul_f32 v[202:203], v[20:21], v[202:203]
	v_pk_mul_f32 v[204:205], v[22:23], v[204:205]
	v_pk_mul_f32 v[206:207], v[24:25], v[206:207]
	v_pk_mul_f32 v[208:209], v[26:27], v[208:209]
	v_pk_mul_f32 v[210:211], v[28:29], v[210:211]
	v_pk_mul_f32 v[212:213], v[30:31], v[212:213]
	v_pk_fma_f32 v[198:199], v[32:33], v[198:199], v[48:49]
	v_pk_fma_f32 v[200:201], v[34:35], v[200:201], v[50:51]
	v_pk_fma_f32 v[202:203], v[36:37], v[202:203], v[52:53]
	v_pk_fma_f32 v[204:205], v[38:39], v[204:205], v[54:55]
	v_pk_fma_f32 v[206:207], v[40:41], v[206:207], v[56:57]
	v_pk_fma_f32 v[208:209], v[42:43], v[208:209], v[58:59]
	v_pk_fma_f32 v[210:211], v[44:45], v[210:211], v[60:61]
	v_pk_fma_f32 v[212:213], v[46:47], v[212:213], v[62:63]
	v_cvt_pk_bf16_f32 v230, v198, v199
	v_cvt_pk_bf16_f32 v231, v200, v201
	v_cvt_pk_bf16_f32 v232, v202, v203
	v_cvt_pk_bf16_f32 v233, v204, v205
	v_cvt_pk_bf16_f32 v234, v206, v207
	v_cvt_pk_bf16_f32 v235, v208, v209
	v_cvt_pk_bf16_f32 v236, v210, v211
	v_cvt_pk_bf16_f32 v237, v212, v213
	global_store_dwordx4 v186, v[230:233], s[44:45] offset:0 sc1
	global_store_dwordx4 v186, v[234:237], s[44:45] offset:1024 sc1
	s_waitcnt vmcnt(28)
; template <int R, bool SRCB> ...
;     ...
;         for (int r = 0; r < R; ++r) {
;             f32x4 y[2][2]; float ss = 0.f;
; #pragma unroll
;             for (int j = 0; j < 2; ++j) { const u32x4 t = yr[r][j];
;                 y[j][0] = (f32x4){bf_lo(t.x), bf_hi(t.x), bf_lo(t.y), bf_hi(t.y)}; y[j][1] = (f32x4){bf_lo(t.z), bf_hi(t.z), bf_lo(t.w), bf_hi(t.w)};
;                 if (R == 1 && YP) {
; #pragma unroll
;                     for (int k = 0; k < 2; ++k) { const float* pp = YP + (size_t)(row0 - M_LAT) * DM + 8 * lane + 512 * j + 4 * k; f32x4 s = *(const f32x4*)pp;
; #pragma unroll
;                         for (int q = 1; q < pg8::NSL; ++q) s = s + *(const f32x4*)(pp + (size_t)q * 2048 * DM);
;                         y[j][k] = s; } }
; #pragma unroll
;                 for (int k = 0; k < 2; ++k) ss += (y[j][k][0] * y[j][k][0] + y[j][k][1] * y[j][k][1]) + (y[j][k][2] * y[j][k][2] + y[j][k][3] * y[j][k][3]); }
;             const float rr = __builtin_amdgcn_rsqf(wave_sum(ss) * (1.0f / DM) + 1e-6f) * w;
; #pragma unroll
;             for (int j = 0; j < 2; ++j)
; #pragma unroll
;                 for (int k = 0; k < 2; ++k) h[r][j][k] = h[r][j][k] + gg[j][k] * (y[j][k] * rr);
;         }
;     }
; #pragma unroll
;     for (int r = 0; r < R; ++r)
; #pragma unroll
;         for (int j = 0; j < 2; ++j) { const int c = 8 * lane + 512 * j;
;             if (final_out) { *(f32x4*)(final_out + (size_t)(row0 + r) * DM + c) = h[r][j][0]; *(f32x4*)(final_out + (size_t)(row0 + r) * DM + c + 4) = h[r][j][1]; }
;             else { u32x4 t; t.x = pkh2(h[r][j][0][0], h[r][j][0][1]); t.y = pkh2(h[r][j][0][2], h[r][j][0][3]); t.z = pkh2(h[r][j][1][0], h[r][j][1][1]); t.w = pkh2(h[r][j][1][2], h[r][j][1][3]);
;                 *(u32x4*)(hout + (size_t)(row0 + r) * DM + c) = t; } }
;     if (U) {
;         f32x4 gp[2][2], sc1[2][2], sh[2][2];
; #pragma unroll
;         for (int j = 0; j < 2; ++j)
; #pragma unroll
;             for (int k = 0; k < 2; ++k) { const int c = 8 * lane + 512 * j + 4 * k; gp[j][k] = *(const f32x4*)(gpre + c); sc1[j][k] = *(const f32x4*)(scale + (size_t)mrow * 9216 + c) + 1.0f; sh[j][k] = *(const f32x4*)(shift + (size_t)mrow * 9216 + c); }
; #pragma unroll
;         for (int r = 0; r < R; ++r) {
;             float ss = 0.f;
; #pragma unroll
;             for (int j = 0; j < 2; ++j)
; #pragma unroll
	v_lshlrev_b32_e32 v116, 16, v172
	v_and_b32_e32 v117, 0xffff0000, v172
	v_lshlrev_b32_e32 v118, 16, v173
	v_and_b32_e32 v119, 0xffff0000, v173
	v_lshlrev_b32_e32 v120, 16, v174
	v_and_b32_e32 v121, 0xffff0000, v174
	v_lshlrev_b32_e32 v122, 16, v175
	v_and_b32_e32 v123, 0xffff0000, v175
	v_lshlrev_b32_e32 v124, 16, v176
	v_and_b32_e32 v125, 0xffff0000, v176
	v_lshlrev_b32_e32 v126, 16, v177
	v_and_b32_e32 v127, 0xffff0000, v177
	v_lshlrev_b32_e32 v128, 16, v178
	v_and_b32_e32 v129, 0xffff0000, v178
	v_lshlrev_b32_e32 v130, 16, v179
	v_and_b32_e32 v131, 0xffff0000, v179
	v_cvt_f32_f16_e32 v198, v88
	v_cvt_f32_f16_sdwa v199, v88 dst_sel:DWORD dst_unused:UNUSED_PAD src0_sel:WORD_1
	v_cvt_f32_f16_e32 v200, v89
	v_cvt_f32_f16_sdwa v201, v89 dst_sel:DWORD dst_unused:UNUSED_PAD src0_sel:WORD_1
	v_cvt_f32_f16_e32 v202, v90
	v_cvt_f32_f16_sdwa v203, v90 dst_sel:DWORD dst_unused:UNUSED_PAD src0_sel:WORD_1
	v_cvt_f32_f16_e32 v204, v91
	v_cvt_f32_f16_sdwa v205, v91 dst_sel:DWORD dst_unused:UNUSED_PAD src0_sel:WORD_1
	v_cvt_f32_f16_e32 v206, v92
	v_cvt_f32_f16_sdwa v207, v92 dst_sel:DWORD dst_unused:UNUSED_PAD src0_sel:WORD_1
	v_cvt_f32_f16_e32 v208, v93
	v_cvt_f32_f16_sdwa v209, v93 dst_sel:DWORD dst_unused:UNUSED_PAD src0_sel:WORD_1
	v_cvt_f32_f16_e32 v210, v94
	v_cvt_f32_f16_sdwa v211, v94 dst_sel:DWORD dst_unused:UNUSED_PAD src0_sel:WORD_1
	v_cvt_f32_f16_e32 v212, v95
	v_cvt_f32_f16_sdwa v213, v95 dst_sel:DWORD dst_unused:UNUSED_PAD src0_sel:WORD_1
	global_load_dwordx4 v[88:91], v187, s[42:43] offset:2048
	global_load_dwordx4 v[92:95], v187, s[42:43] offset:3072
	global_load_dwordx4 v[172:175], v187, s[44:45] offset:2048
	global_load_dwordx4 v[176:179], v187, s[44:45] offset:3072
	v_pk_mul_f32 v[140:141], v[116:117], v[116:117]
	v_pk_fma_f32 v[140:141], v[118:119], v[118:119], v[140:141]
	v_pk_fma_f32 v[140:141], v[120:121], v[120:121], v[140:141]
	v_pk_fma_f32 v[140:141], v[122:123], v[122:123], v[140:141]
	v_pk_fma_f32 v[140:141], v[124:125], v[124:125], v[140:141]
	v_pk_fma_f32 v[140:141], v[126:127], v[126:127], v[140:141]
	v_pk_fma_f32 v[140:141], v[128:129], v[128:129], v[140:141]
	v_pk_fma_f32 v[140:141], v[130:131], v[130:131], v[140:141]
	v_add_f32_e32 v140, v140, v141
	s_nop 1
	v_add_f32_dpp v140, v140, v140 quad_perm:[1,0,3,2] row_mask:0xf bank_mask:0xf
	s_nop 1
	v_add_f32_dpp v140, v140, v140 quad_perm:[2,3,0,1] row_mask:0xf bank_mask:0xf
	s_nop 1
	v_add_f32_dpp v140, v140, v140 row_ror:4 row_mask:0xf bank_mask:0xf
	s_nop 1
	v_add_f32_dpp v140, v140, v140 row_ror:8 row_mask:0xf bank_mask:0xf
	s_nop 1
	v_add_f32_dpp v140, v140, v140 row_bcast:15 row_mask:0xa bank_mask:0xf
	s_nop 1
	v_add_f32_dpp v140, v140, v140 row_bcast:31 row_mask:0xc bank_mask:0xf
	s_nop 1
	v_fmamk_f32 v140, v140, 0x3a800000, v224
	v_rsq_f32_e32 v140, v140
	s_nop 0
	v_mul_f32_e32 v140, v144, v140
	s_nop 0
	v_readlane_b32 s4, v140, 63
	s_nop 1
	v_pk_mul_f32 v[116:117], v[116:117], s[4:5] op_sel_hi:[1,0]
	v_pk_mul_f32 v[118:119], v[118:119], s[4:5] op_sel_hi:[1,0]
	v_pk_mul_f32 v[120:121], v[120:121], s[4:5] op_sel_hi:[1,0]
	v_pk_mul_f32 v[122:123], v[122:123], s[4:5] op_sel_hi:[1,0]
	v_pk_mul_f32 v[124:125], v[124:125], s[4:5] op_sel_hi:[1,0]
	v_pk_mul_f32 v[126:127], v[126:127], s[4:5] op_sel_hi:[1,0]
	v_pk_mul_f32 v[128:129], v[128:129], s[4:5] op_sel_hi:[1,0]
	v_pk_mul_f32 v[130:131], v[130:131], s[4:5] op_sel_hi:[1,0]
	v_pk_fma_f32 v[198:199], v[0:1], v[116:117], v[198:199]
	v_pk_fma_f32 v[200:201], v[2:3], v[118:119], v[200:201]
	v_pk_fma_f32 v[202:203], v[4:5], v[120:121], v[202:203]
	v_pk_fma_f32 v[204:205], v[6:7], v[122:123], v[204:205]
	v_pk_fma_f32 v[206:207], v[8:9], v[124:125], v[206:207]
	v_pk_fma_f32 v[208:209], v[10:11], v[126:127], v[208:209]
	v_pk_fma_f32 v[210:211], v[12:13], v[128:129], v[210:211]
	v_pk_fma_f32 v[212:213], v[14:15], v[130:131], v[212:213]
	v_cvt_f16_f32_e32 v132, v198
	v_cvt_f16_f32_e32 v133, v200
	v_cvt_f16_f32_e32 v134, v202
	v_cvt_f16_f32_e32 v135, v204
	v_cvt_f16_f32_e32 v136, v206
	v_cvt_f16_f32_e32 v137, v208
	v_cvt_f16_f32_e32 v138, v210
	v_cvt_f16_f32_e32 v139, v212
	v_cvt_f16_f32_sdwa v132, v199 dst_sel:WORD_1 dst_unused:UNUSED_PRESERVE src0_sel:DWORD
	v_cvt_f16_f32_sdwa v133, v201 dst_sel:WORD_1 dst_unused:UNUSED_PRESERVE src0_sel:DWORD
	v_cvt_f16_f32_sdwa v134, v203 dst_sel:WORD_1 dst_unused:UNUSED_PRESERVE src0_sel:DWORD
	v_cvt_f16_f32_sdwa v135, v205 dst_sel:WORD_1 dst_unused:UNUSED_PRESERVE src0_sel:DWORD
	v_cvt_f16_f32_sdwa v136, v207 dst_sel:WORD_1 dst_unused:UNUSED_PRESERVE src0_sel:DWORD
	v_cvt_f16_f32_sdwa v137, v209 dst_sel:WORD_1 dst_unused:UNUSED_PRESERVE src0_sel:DWORD
	v_cvt_f16_f32_sdwa v138, v211 dst_sel:WORD_1 dst_unused:UNUSED_PRESERVE src0_sel:DWORD
	v_cvt_f16_f32_sdwa v139, v213 dst_sel:WORD_1 dst_unused:UNUSED_PRESERVE src0_sel:DWORD
	s_nop 0
	global_store_dwordx4 v186, v[132:135], s[42:43] offset:2048 sc1
	global_store_dwordx4 v186, v[136:139], s[42:43] offset:3072 sc1
	v_pk_mul_f32 v[140:141], v[198:199], v[198:199]
	v_pk_fma_f32 v[140:141], v[200:201], v[200:201], v[140:141]
	v_pk_fma_f32 v[140:141], v[202:203], v[202:203], v[140:141]
	v_pk_fma_f32 v[140:141], v[204:205], v[204:205], v[140:141]
	v_pk_fma_f32 v[140:141], v[206:207], v[206:207], v[140:141]
	v_pk_fma_f32 v[140:141], v[208:209], v[208:209], v[140:141]
	v_pk_fma_f32 v[140:141], v[210:211], v[210:211], v[140:141]
	v_pk_fma_f32 v[140:141], v[212:213], v[212:213], v[140:141]
	v_add_f32_e32 v140, v140, v141
	s_nop 1
	v_add_f32_dpp v140, v140, v140 quad_perm:[1,0,3,2] row_mask:0xf bank_mask:0xf
	s_nop 1
	v_add_f32_dpp v140, v140, v140 quad_perm:[2,3,0,1] row_mask:0xf bank_mask:0xf
	s_nop 1
	v_add_f32_dpp v140, v140, v140 row_ror:4 row_mask:0xf bank_mask:0xf
; template <int R, bool SRCB> ...
;     ...
;         for (int r = 0; r < R; ++r) {
;             f32x4 y[2][2]; float ss = 0.f;
; #pragma unroll
;             for (int j = 0; j < 2; ++j) { const u32x4 t = yr[r][j];
;                 y[j][0] = (f32x4){bf_lo(t.x), bf_hi(t.x), bf_lo(t.y), bf_hi(t.y)}; y[j][1] = (f32x4){bf_lo(t.z), bf_hi(t.z), bf_lo(t.w), bf_hi(t.w)};
;                 if (R == 1 && YP) {
; #pragma unroll
;                     for (int k = 0; k < 2; ++k) { const float* pp = YP + (size_t)(row0 - M_LAT) * DM + 8 * lane + 512 * j + 4 * k; f32x4 s = *(const f32x4*)pp;
; #pragma unroll
;                         for (int q = 1; q < pg8::NSL; ++q) s = s + *(const f32x4*)(pp + (size_t)q * 2048 * DM);
;                         y[j][k] = s; } }
; #pragma unroll
;                 for (int k = 0; k < 2; ++k) ss += (y[j][k][0] * y[j][k][0] + y[j][k][1] * y[j][k][1]) + (y[j][k][2] * y[j][k][2] + y[j][k][3] * y[j][k][3]); }
;             const float rr = __builtin_amdgcn_rsqf(wave_sum(ss) * (1.0f / DM) + 1e-6f) * w;
; #pragma unroll
;             for (int j = 0; j < 2; ++j)
; #pragma unroll
;                 for (int k = 0; k < 2; ++k) h[r][j][k] = h[r][j][k] + gg[j][k] * (y[j][k] * rr);
;         }
;     }
; #pragma unroll
;     for (int r = 0; r < R; ++r)
; #pragma unroll
;         for (int j = 0; j < 2; ++j) { const int c = 8 * lane + 512 * j;
;             if (final_out) { *(f32x4*)(final_out + (size_t)(row0 + r) * DM + c) = h[r][j][0]; *(f32x4*)(final_out + (size_t)(row0 + r) * DM + c + 4) = h[r][j][1]; }
;             else { u32x4 t; t.x = pkh2(h[r][j][0][0], h[r][j][0][1]); t.y = pkh2(h[r][j][0][2], h[r][j][0][3]); t.z = pkh2(h[r][j][1][0], h[r][j][1][1]); t.w = pkh2(h[r][j][1][2], h[r][j][1][3]);
;                 *(u32x4*)(hout + (size_t)(row0 + r) * DM + c) = t; } }
;     if (U) {
;         f32x4 gp[2][2], sc1[2][2], sh[2][2];
; #pragma unroll
;         for (int j = 0; j < 2; ++j)
; #pragma unroll
;             for (int k = 0; k < 2; ++k) { const int c = 8 * lane + 512 * j + 4 * k; gp[j][k] = *(const f32x4*)(gpre + c); sc1[j][k] = *(const f32x4*)(scale + (size_t)mrow * 9216 + c) + 1.0f; sh[j][k] = *(const f32x4*)(shift + (size_t)mrow * 9216 + c); }
; #pragma unroll
;         for (int r = 0; r < R; ++r) {
;             float ss = 0.f;
; #pragma unroll
;             for (int j = 0; j < 2; ++j)
; #pragma unroll
	s_nop 1
	v_add_f32_dpp v140, v140, v140 row_ror:8 row_mask:0xf bank_mask:0xf
	s_nop 1
	v_add_f32_dpp v140, v140, v140 row_bcast:15 row_mask:0xa bank_mask:0xf
	s_nop 1
	v_add_f32_dpp v140, v140, v140 row_bcast:31 row_mask:0xc bank_mask:0xf
	s_nop 1
	v_fmamk_f32 v140, v140, 0x3a800000, v224
	v_rsq_f32_e32 v140, v140
	s_nop 0
	v_readlane_b32 s6, v140, 63
	s_nop 1
	v_pk_mul_f32 v[198:199], v[198:199], s[6:7] op_sel_hi:[1,0]
	v_pk_mul_f32 v[200:201], v[200:201], s[6:7] op_sel_hi:[1,0]
	v_pk_mul_f32 v[202:203], v[202:203], s[6:7] op_sel_hi:[1,0]
	v_pk_mul_f32 v[204:205], v[204:205], s[6:7] op_sel_hi:[1,0]
	v_pk_mul_f32 v[206:207], v[206:207], s[6:7] op_sel_hi:[1,0]
	v_pk_mul_f32 v[208:209], v[208:209], s[6:7] op_sel_hi:[1,0]
	v_pk_mul_f32 v[210:211], v[210:211], s[6:7] op_sel_hi:[1,0]
	v_pk_mul_f32 v[212:213], v[212:213], s[6:7] op_sel_hi:[1,0]
	v_pk_mul_f32 v[198:199], v[16:17], v[198:199]
	v_pk_mul_f32 v[200:201], v[18:19], v[200:201]
	v_pk_mul_f32 v[202:203], v[20:21], v[202:203]
	v_pk_mul_f32 v[204:205], v[22:23], v[204:205]
	v_pk_mul_f32 v[206:207], v[24:25], v[206:207]
	v_pk_mul_f32 v[208:209], v[26:27], v[208:209]
	v_pk_mul_f32 v[210:211], v[28:29], v[210:211]
	v_pk_mul_f32 v[212:213], v[30:31], v[212:213]
	v_pk_fma_f32 v[198:199], v[32:33], v[198:199], v[48:49]
	v_pk_fma_f32 v[200:201], v[34:35], v[200:201], v[50:51]
	v_pk_fma_f32 v[202:203], v[36:37], v[202:203], v[52:53]
	v_pk_fma_f32 v[204:205], v[38:39], v[204:205], v[54:55]
	v_pk_fma_f32 v[206:207], v[40:41], v[206:207], v[56:57]
	v_pk_fma_f32 v[208:209], v[42:43], v[208:209], v[58:59]
	v_pk_fma_f32 v[210:211], v[44:45], v[210:211], v[60:61]
	v_pk_fma_f32 v[212:213], v[46:47], v[212:213], v[62:63]
	v_cvt_pk_bf16_f32 v230, v198, v199
	v_cvt_pk_bf16_f32 v231, v200, v201
	v_cvt_pk_bf16_f32 v232, v202, v203
	v_cvt_pk_bf16_f32 v233, v204, v205
	v_cvt_pk_bf16_f32 v234, v206, v207
	v_cvt_pk_bf16_f32 v235, v208, v209
	v_cvt_pk_bf16_f32 v236, v210, v211
	v_cvt_pk_bf16_f32 v237, v212, v213
	global_store_dwordx4 v186, v[230:233], s[44:45] offset:2048 sc1
	global_store_dwordx4 v186, v[234:237], s[44:45] offset:3072 sc1
	s_waitcnt vmcnt(28)
	v_lshlrev_b32_e32 v116, 16, v148
	v_and_b32_e32 v117, 0xffff0000, v148
	v_lshlrev_b32_e32 v118, 16, v149
	v_and_b32_e32 v119, 0xffff0000, v149
	v_lshlrev_b32_e32 v120, 16, v150
	v_and_b32_e32 v121, 0xffff0000, v150
	v_lshlrev_b32_e32 v122, 16, v151
	v_and_b32_e32 v123, 0xffff0000, v151
	v_lshlrev_b32_e32 v124, 16, v152
	v_and_b32_e32 v125, 0xffff0000, v152
	v_lshlrev_b32_e32 v126, 16, v153
	v_and_b32_e32 v127, 0xffff0000, v153
	v_lshlrev_b32_e32 v128, 16, v154
	v_and_b32_e32 v129, 0xffff0000, v154
	v_lshlrev_b32_e32 v130, 16, v155
	v_and_b32_e32 v131, 0xffff0000, v155
	v_cvt_f32_f16_e32 v198, v64
	v_cvt_f32_f16_sdwa v199, v64 dst_sel:DWORD dst_unused:UNUSED_PAD src0_sel:WORD_1
	v_cvt_f32_f16_e32 v200, v65
	v_cvt_f32_f16_sdwa v201, v65 dst_sel:DWORD dst_unused:UNUSED_PAD src0_sel:WORD_1
	v_cvt_f32_f16_e32 v202, v66
	v_cvt_f32_f16_sdwa v203, v66 dst_sel:DWORD dst_unused:UNUSED_PAD src0_sel:WORD_1
	v_cvt_f32_f16_e32 v204, v67
	v_cvt_f32_f16_sdwa v205, v67 dst_sel:DWORD dst_unused:UNUSED_PAD src0_sel:WORD_1
	v_cvt_f32_f16_e32 v206, v68
	v_cvt_f32_f16_sdwa v207, v68 dst_sel:DWORD dst_unused:UNUSED_PAD src0_sel:WORD_1
	v_cvt_f32_f16_e32 v208, v69
	v_cvt_f32_f16_sdwa v209, v69 dst_sel:DWORD dst_unused:UNUSED_PAD src0_sel:WORD_1
	v_cvt_f32_f16_e32 v210, v70
	v_cvt_f32_f16_sdwa v211, v70 dst_sel:DWORD dst_unused:UNUSED_PAD src0_sel:WORD_1
	v_cvt_f32_f16_e32 v212, v71
	v_cvt_f32_f16_sdwa v213, v71 dst_sel:DWORD dst_unused:UNUSED_PAD src0_sel:WORD_1
	v_pk_mul_f32 v[140:141], v[116:117], v[116:117]
	v_pk_fma_f32 v[140:141], v[118:119], v[118:119], v[140:141]
	v_pk_fma_f32 v[140:141], v[120:121], v[120:121], v[140:141]
	v_pk_fma_f32 v[140:141], v[122:123], v[122:123], v[140:141]
	v_pk_fma_f32 v[140:141], v[124:125], v[124:125], v[140:141]
	v_pk_fma_f32 v[140:141], v[126:127], v[126:127], v[140:141]
	v_pk_fma_f32 v[140:141], v[128:129], v[128:129], v[140:141]
	v_pk_fma_f32 v[140:141], v[130:131], v[130:131], v[140:141]
	v_add_f32_e32 v140, v140, v141
	s_nop 1
	v_add_f32_dpp v140, v140, v140 quad_perm:[1,0,3,2] row_mask:0xf bank_mask:0xf
	s_nop 1
	v_add_f32_dpp v140, v140, v140 quad_perm:[2,3,0,1] row_mask:0xf bank_mask:0xf
	s_nop 1
	v_add_f32_dpp v140, v140, v140 row_ror:4 row_mask:0xf bank_mask:0xf
	s_nop 1
	v_add_f32_dpp v140, v140, v140 row_ror:8 row_mask:0xf bank_mask:0xf
	s_nop 1
	v_add_f32_dpp v140, v140, v140 row_bcast:15 row_mask:0xa bank_mask:0xf
	s_nop 1
	v_add_f32_dpp v140, v140, v140 row_bcast:31 row_mask:0xc bank_mask:0xf
	s_nop 1
	v_fmamk_f32 v140, v140, 0x3a800000, v224
	v_rsq_f32_e32 v140, v140
	s_nop 0
	v_mul_f32_e32 v140, v144, v140
	s_nop 0
	v_readlane_b32 s4, v140, 63
	s_nop 1
	v_pk_mul_f32 v[116:117], v[116:117], s[4:5] op_sel_hi:[1,0]
	v_pk_mul_f32 v[118:119], v[118:119], s[4:5] op_sel_hi:[1,0]
	v_pk_mul_f32 v[120:121], v[120:121], s[4:5] op_sel_hi:[1,0]
	v_pk_mul_f32 v[122:123], v[122:123], s[4:5] op_sel_hi:[1,0]
	v_pk_mul_f32 v[124:125], v[124:125], s[4:5] op_sel_hi:[1,0]
	v_pk_mul_f32 v[126:127], v[126:127], s[4:5] op_sel_hi:[1,0]
	v_pk_mul_f32 v[128:129], v[128:129], s[4:5] op_sel_hi:[1,0]
	v_pk_mul_f32 v[130:131], v[130:131], s[4:5] op_sel_hi:[1,0]
	v_pk_fma_f32 v[198:199], v[0:1], v[116:117], v[198:199]
	v_pk_fma_f32 v[200:201], v[2:3], v[118:119], v[200:201]
	v_pk_fma_f32 v[202:203], v[4:5], v[120:121], v[202:203]
	v_pk_fma_f32 v[204:205], v[6:7], v[122:123], v[204:205]
	v_pk_fma_f32 v[206:207], v[8:9], v[124:125], v[206:207]
	v_pk_fma_f32 v[208:209], v[10:11], v[126:127], v[208:209]
	v_pk_fma_f32 v[210:211], v[12:13], v[128:129], v[210:211]
; template <int R, bool SRCB> ...
;     ...
;         for (int r = 0; r < R; ++r) {
;             f32x4 y[2][2]; float ss = 0.f;
; #pragma unroll
;             for (int j = 0; j < 2; ++j) { const u32x4 t = yr[r][j];
;                 y[j][0] = (f32x4){bf_lo(t.x), bf_hi(t.x), bf_lo(t.y), bf_hi(t.y)}; y[j][1] = (f32x4){bf_lo(t.z), bf_hi(t.z), bf_lo(t.w), bf_hi(t.w)};
;                 if (R == 1 && YP) {
; #pragma unroll
;                     for (int k = 0; k < 2; ++k) { const float* pp = YP + (size_t)(row0 - M_LAT) * DM + 8 * lane + 512 * j + 4 * k; f32x4 s = *(const f32x4*)pp;
; #pragma unroll
;                         for (int q = 1; q < pg8::NSL; ++q) s = s + *(const f32x4*)(pp + (size_t)q * 2048 * DM);
;                         y[j][k] = s; } }
; #pragma unroll
;                 for (int k = 0; k < 2; ++k) ss += (y[j][k][0] * y[j][k][0] + y[j][k][1] * y[j][k][1]) + (y[j][k][2] * y[j][k][2] + y[j][k][3] * y[j][k][3]); }
;             const float rr = __builtin_amdgcn_rsqf(wave_sum(ss) * (1.0f / DM) + 1e-6f) * w;
; #pragma unroll
;             for (int j = 0; j < 2; ++j)
; #pragma unroll
;                 for (int k = 0; k < 2; ++k) h[r][j][k] = h[r][j][k] + gg[j][k] * (y[j][k] * rr);
;         }
;     }
; #pragma unroll
;     for (int r = 0; r < R; ++r)
; #pragma unroll
;         for (int j = 0; j < 2; ++j) { const int c = 8 * lane + 512 * j;
;             if (final_out) { *(f32x4*)(final_out + (size_t)(row0 + r) * DM + c) = h[r][j][0]; *(f32x4*)(final_out + (size_t)(row0 + r) * DM + c + 4) = h[r][j][1]; }
;             else { u32x4 t; t.x = pkh2(h[r][j][0][0], h[r][j][0][1]); t.y = pkh2(h[r][j][0][2], h[r][j][0][3]); t.z = pkh2(h[r][j][1][0], h[r][j][1][1]); t.w = pkh2(h[r][j][1][2], h[r][j][1][3]);
;                 *(u32x4*)(hout + (size_t)(row0 + r) * DM + c) = t; } }
;     if (U) {
;         f32x4 gp[2][2], sc1[2][2], sh[2][2];
; #pragma unroll
;         for (int j = 0; j < 2; ++j)
; #pragma unroll
;             for (int k = 0; k < 2; ++k) { const int c = 8 * lane + 512 * j + 4 * k; gp[j][k] = *(const f32x4*)(gpre + c); sc1[j][k] = *(const f32x4*)(scale + (size_t)mrow * 9216 + c) + 1.0f; sh[j][k] = *(const f32x4*)(shift + (size_t)mrow * 9216 + c); }
; #pragma unroll
;         for (int r = 0; r < R; ++r) {
;             float ss = 0.f;
; #pragma unroll
;             for (int j = 0; j < 2; ++j)
; #pragma unroll
	v_pk_fma_f32 v[212:213], v[14:15], v[130:131], v[212:213]
	v_cvt_f16_f32_e32 v132, v198
	v_cvt_f16_f32_e32 v133, v200
	v_cvt_f16_f32_e32 v134, v202
	v_cvt_f16_f32_e32 v135, v204
	v_cvt_f16_f32_e32 v136, v206
	v_cvt_f16_f32_e32 v137, v208
	v_cvt_f16_f32_e32 v138, v210
	v_cvt_f16_f32_e32 v139, v212
	v_cvt_f16_f32_sdwa v132, v199 dst_sel:WORD_1 dst_unused:UNUSED_PRESERVE src0_sel:DWORD
	v_cvt_f16_f32_sdwa v133, v201 dst_sel:WORD_1 dst_unused:UNUSED_PRESERVE src0_sel:DWORD
	v_cvt_f16_f32_sdwa v134, v203 dst_sel:WORD_1 dst_unused:UNUSED_PRESERVE src0_sel:DWORD
	v_cvt_f16_f32_sdwa v135, v205 dst_sel:WORD_1 dst_unused:UNUSED_PRESERVE src0_sel:DWORD
	v_cvt_f16_f32_sdwa v136, v207 dst_sel:WORD_1 dst_unused:UNUSED_PRESERVE src0_sel:DWORD
	v_cvt_f16_f32_sdwa v137, v209 dst_sel:WORD_1 dst_unused:UNUSED_PRESERVE src0_sel:DWORD
	v_cvt_f16_f32_sdwa v138, v211 dst_sel:WORD_1 dst_unused:UNUSED_PRESERVE src0_sel:DWORD
	v_cvt_f16_f32_sdwa v139, v213 dst_sel:WORD_1 dst_unused:UNUSED_PRESERVE src0_sel:DWORD
	s_nop 0
	global_store_dwordx4 v187, v[132:135], s[42:43] offset:-4096 sc1
	global_store_dwordx4 v187, v[136:139], s[42:43] offset:-3072 sc1
	v_pk_mul_f32 v[140:141], v[198:199], v[198:199]
	v_pk_fma_f32 v[140:141], v[200:201], v[200:201], v[140:141]
	v_pk_fma_f32 v[140:141], v[202:203], v[202:203], v[140:141]
	v_pk_fma_f32 v[140:141], v[204:205], v[204:205], v[140:141]
	v_pk_fma_f32 v[140:141], v[206:207], v[206:207], v[140:141]
	v_pk_fma_f32 v[140:141], v[208:209], v[208:209], v[140:141]
	v_pk_fma_f32 v[140:141], v[210:211], v[210:211], v[140:141]
	v_pk_fma_f32 v[140:141], v[212:213], v[212:213], v[140:141]
	v_add_f32_e32 v140, v140, v141
	s_nop 1
	v_add_f32_dpp v140, v140, v140 quad_perm:[1,0,3,2] row_mask:0xf bank_mask:0xf
	s_nop 1
	v_add_f32_dpp v140, v140, v140 quad_perm:[2,3,0,1] row_mask:0xf bank_mask:0xf
	s_nop 1
	v_add_f32_dpp v140, v140, v140 row_ror:4 row_mask:0xf bank_mask:0xf
	s_nop 1
	v_add_f32_dpp v140, v140, v140 row_ror:8 row_mask:0xf bank_mask:0xf
	s_nop 1
	v_add_f32_dpp v140, v140, v140 row_bcast:15 row_mask:0xa bank_mask:0xf
	s_nop 1
	v_add_f32_dpp v140, v140, v140 row_bcast:31 row_mask:0xc bank_mask:0xf
	s_nop 1
	v_fmamk_f32 v140, v140, 0x3a800000, v224
	v_rsq_f32_e32 v140, v140
	s_nop 0
	v_readlane_b32 s6, v140, 63
	s_nop 1
	v_pk_mul_f32 v[198:199], v[198:199], s[6:7] op_sel_hi:[1,0]
	v_pk_mul_f32 v[200:201], v[200:201], s[6:7] op_sel_hi:[1,0]
	v_pk_mul_f32 v[202:203], v[202:203], s[6:7] op_sel_hi:[1,0]
	v_pk_mul_f32 v[204:205], v[204:205], s[6:7] op_sel_hi:[1,0]
	v_pk_mul_f32 v[206:207], v[206:207], s[6:7] op_sel_hi:[1,0]
	v_pk_mul_f32 v[208:209], v[208:209], s[6:7] op_sel_hi:[1,0]
	v_pk_mul_f32 v[210:211], v[210:211], s[6:7] op_sel_hi:[1,0]
	v_pk_mul_f32 v[212:213], v[212:213], s[6:7] op_sel_hi:[1,0]
	v_pk_mul_f32 v[198:199], v[16:17], v[198:199]
	v_pk_mul_f32 v[200:201], v[18:19], v[200:201]
	v_pk_mul_f32 v[202:203], v[20:21], v[202:203]
	v_pk_mul_f32 v[204:205], v[22:23], v[204:205]
	v_pk_mul_f32 v[206:207], v[24:25], v[206:207]
	v_pk_mul_f32 v[208:209], v[26:27], v[208:209]
	v_pk_mul_f32 v[210:211], v[28:29], v[210:211]
	v_pk_mul_f32 v[212:213], v[30:31], v[212:213]
	v_pk_fma_f32 v[198:199], v[32:33], v[198:199], v[48:49]
	v_pk_fma_f32 v[200:201], v[34:35], v[200:201], v[50:51]
	v_pk_fma_f32 v[202:203], v[36:37], v[202:203], v[52:53]
	v_pk_fma_f32 v[204:205], v[38:39], v[204:205], v[54:55]
	v_pk_fma_f32 v[206:207], v[40:41], v[206:207], v[56:57]
	v_pk_fma_f32 v[208:209], v[42:43], v[208:209], v[58:59]
	v_pk_fma_f32 v[210:211], v[44:45], v[210:211], v[60:61]
	v_pk_fma_f32 v[212:213], v[46:47], v[212:213], v[62:63]
	v_cvt_pk_bf16_f32 v230, v198, v199
	v_cvt_pk_bf16_f32 v231, v200, v201
	v_cvt_pk_bf16_f32 v232, v202, v203
	v_cvt_pk_bf16_f32 v233, v204, v205
	v_cvt_pk_bf16_f32 v234, v206, v207
	v_cvt_pk_bf16_f32 v235, v208, v209
	v_cvt_pk_bf16_f32 v236, v210, v211
	v_cvt_pk_bf16_f32 v237, v212, v213
	global_store_dwordx4 v187, v[230:233], s[44:45] offset:-4096 sc1
	global_store_dwordx4 v187, v[234:237], s[44:45] offset:-3072 sc1
	s_waitcnt vmcnt(24)
	v_lshlrev_b32_e32 v116, 16, v156
	v_and_b32_e32 v117, 0xffff0000, v156
	v_lshlrev_b32_e32 v118, 16, v157
	v_and_b32_e32 v119, 0xffff0000, v157
	v_lshlrev_b32_e32 v120, 16, v158
	v_and_b32_e32 v121, 0xffff0000, v158
	v_lshlrev_b32_e32 v122, 16, v159
	v_and_b32_e32 v123, 0xffff0000, v159
	v_lshlrev_b32_e32 v124, 16, v160
	v_and_b32_e32 v125, 0xffff0000, v160
	v_lshlrev_b32_e32 v126, 16, v161
	v_and_b32_e32 v127, 0xffff0000, v161
	v_lshlrev_b32_e32 v128, 16, v162
	v_and_b32_e32 v129, 0xffff0000, v162
	v_lshlrev_b32_e32 v130, 16, v163
	v_and_b32_e32 v131, 0xffff0000, v163
	v_cvt_f32_f16_e32 v198, v72
	v_cvt_f32_f16_sdwa v199, v72 dst_sel:DWORD dst_unused:UNUSED_PAD src0_sel:WORD_1
	v_cvt_f32_f16_e32 v200, v73
	v_cvt_f32_f16_sdwa v201, v73 dst_sel:DWORD dst_unused:UNUSED_PAD src0_sel:WORD_1
	v_cvt_f32_f16_e32 v202, v74
	v_cvt_f32_f16_sdwa v203, v74 dst_sel:DWORD dst_unused:UNUSED_PAD src0_sel:WORD_1
	v_cvt_f32_f16_e32 v204, v75
	v_cvt_f32_f16_sdwa v205, v75 dst_sel:DWORD dst_unused:UNUSED_PAD src0_sel:WORD_1
	v_cvt_f32_f16_e32 v206, v76
	v_cvt_f32_f16_sdwa v207, v76 dst_sel:DWORD dst_unused:UNUSED_PAD src0_sel:WORD_1
	v_cvt_f32_f16_e32 v208, v77
	v_cvt_f32_f16_sdwa v209, v77 dst_sel:DWORD dst_unused:UNUSED_PAD src0_sel:WORD_1
	v_cvt_f32_f16_e32 v210, v78
	v_cvt_f32_f16_sdwa v211, v78 dst_sel:DWORD dst_unused:UNUSED_PAD src0_sel:WORD_1
	v_cvt_f32_f16_e32 v212, v79
	v_cvt_f32_f16_sdwa v213, v79 dst_sel:DWORD dst_unused:UNUSED_PAD src0_sel:WORD_1
	v_pk_mul_f32 v[140:141], v[116:117], v[116:117]
	v_pk_fma_f32 v[140:141], v[118:119], v[118:119], v[140:141]
	v_pk_fma_f32 v[140:141], v[120:121], v[120:121], v[140:141]
; __device__ __forceinline__ unsigned pk2(float lo, float hi) { return pg8::cvt_pk_bf16(lo, hi); }
; template <int R, bool SRCB> ...
;     ...
;                 for (int k = 0; k < 2; ++k) ss += (y[j][k][0] * y[j][k][0] + y[j][k][1] * y[j][k][1]) + (y[j][k][2] * y[j][k][2] + y[j][k][3] * y[j][k][3]); }
;             const float rr = __builtin_amdgcn_rsqf(wave_sum(ss) * (1.0f / DM) + 1e-6f) * w;
; #pragma unroll
;             for (int j = 0; j < 2; ++j)
; #pragma unroll
;                 for (int k = 0; k < 2; ++k) h[r][j][k] = h[r][j][k] + gg[j][k] * (y[j][k] * rr);
;         }
;     }
; #pragma unroll
;     for (int r = 0; r < R; ++r)
; #pragma unroll
;         for (int j = 0; j < 2; ++j) { const int c = 8 * lane + 512 * j;
;             if (final_out) { *(f32x4*)(final_out + (size_t)(row0 + r) * DM + c) = h[r][j][0]; *(f32x4*)(final_out + (size_t)(row0 + r) * DM + c + 4) = h[r][j][1]; }
;             else { u32x4 t; t.x = pkh2(h[r][j][0][0], h[r][j][0][1]); t.y = pkh2(h[r][j][0][2], h[r][j][0][3]); t.z = pkh2(h[r][j][1][0], h[r][j][1][1]); t.w = pkh2(h[r][j][1][2], h[r][j][1][3]);
;                 *(u32x4*)(hout + (size_t)(row0 + r) * DM + c) = t; } }
;     if (U) {
;         f32x4 gp[2][2], sc1[2][2], sh[2][2];
; #pragma unroll
;         for (int j = 0; j < 2; ++j)
; #pragma unroll
;             for (int k = 0; k < 2; ++k) { const int c = 8 * lane + 512 * j + 4 * k; gp[j][k] = *(const f32x4*)(gpre + c); sc1[j][k] = *(const f32x4*)(scale + (size_t)mrow * 9216 + c) + 1.0f; sh[j][k] = *(const f32x4*)(shift + (size_t)mrow * 9216 + c); }
; #pragma unroll
;         for (int r = 0; r < R; ++r) {
;             float ss = 0.f;
; #pragma unroll
;             for (int j = 0; j < 2; ++j)
; #pragma unroll
;                 for (int k = 0; k < 2; ++k) ss += (h[r][j][k][0] * h[r][j][k][0] + h[r][j][k][1] * h[r][j][k][1]) + (h[r][j][k][2] * h[r][j][k][2] + h[r][j][k][3] * h[r][j][k][3]);
;             const float rr = __builtin_amdgcn_rsqf(wave_sum(ss) * (1.0f / DM) + 1e-6f);
; #pragma unroll
;             for (int j = 0; j < 2; ++j) { const f32x4 v0 = (h[r][j][0] * rr * gp[j][0]) * sc1[j][0] + sh[j][0], v1 = (h[r][j][1] * rr * gp[j][1]) * sc1[j][1] + sh[j][1];
;                 u32x4 t; t.x = pk2(v0[0], v0[1]); t.y = pk2(v0[2], v0[3]); t.z = pk2(v1[0], v1[1]); t.w = pk2(v1[2], v1[3]);
;                 *(u32x4*)(U + (size_t)(row0 + r) * DM + 8 * lane + 512 * j) = t; }
	v_pk_fma_f32 v[140:141], v[122:123], v[122:123], v[140:141]
	v_pk_fma_f32 v[140:141], v[124:125], v[124:125], v[140:141]
	v_pk_fma_f32 v[140:141], v[126:127], v[126:127], v[140:141]
	v_pk_fma_f32 v[140:141], v[128:129], v[128:129], v[140:141]
	v_pk_fma_f32 v[140:141], v[130:131], v[130:131], v[140:141]
	v_add_f32_e32 v140, v140, v141
	s_nop 1
	v_add_f32_dpp v140, v140, v140 quad_perm:[1,0,3,2] row_mask:0xf bank_mask:0xf
	s_nop 1
	v_add_f32_dpp v140, v140, v140 quad_perm:[2,3,0,1] row_mask:0xf bank_mask:0xf
	s_nop 1
	v_add_f32_dpp v140, v140, v140 row_ror:4 row_mask:0xf bank_mask:0xf
	s_nop 1
	v_add_f32_dpp v140, v140, v140 row_ror:8 row_mask:0xf bank_mask:0xf
	s_nop 1
	v_add_f32_dpp v140, v140, v140 row_bcast:15 row_mask:0xa bank_mask:0xf
	s_nop 1
	v_add_f32_dpp v140, v140, v140 row_bcast:31 row_mask:0xc bank_mask:0xf
	s_nop 1
	v_fmamk_f32 v140, v140, 0x3a800000, v224
	v_rsq_f32_e32 v140, v140
	s_nop 0
	v_mul_f32_e32 v140, v144, v140
	s_nop 0
	v_readlane_b32 s4, v140, 63
	s_nop 1
	v_pk_mul_f32 v[116:117], v[116:117], s[4:5] op_sel_hi:[1,0]
	v_pk_mul_f32 v[118:119], v[118:119], s[4:5] op_sel_hi:[1,0]
	v_pk_mul_f32 v[120:121], v[120:121], s[4:5] op_sel_hi:[1,0]
	v_pk_mul_f32 v[122:123], v[122:123], s[4:5] op_sel_hi:[1,0]
	v_pk_mul_f32 v[124:125], v[124:125], s[4:5] op_sel_hi:[1,0]
	v_pk_mul_f32 v[126:127], v[126:127], s[4:5] op_sel_hi:[1,0]
	v_pk_mul_f32 v[128:129], v[128:129], s[4:5] op_sel_hi:[1,0]
	v_pk_mul_f32 v[130:131], v[130:131], s[4:5] op_sel_hi:[1,0]
	v_pk_fma_f32 v[198:199], v[0:1], v[116:117], v[198:199]
	v_pk_fma_f32 v[200:201], v[2:3], v[118:119], v[200:201]
	v_pk_fma_f32 v[202:203], v[4:5], v[120:121], v[202:203]
	v_pk_fma_f32 v[204:205], v[6:7], v[122:123], v[204:205]
	v_pk_fma_f32 v[206:207], v[8:9], v[124:125], v[206:207]
	v_pk_fma_f32 v[208:209], v[10:11], v[126:127], v[208:209]
	v_pk_fma_f32 v[210:211], v[12:13], v[128:129], v[210:211]
	v_pk_fma_f32 v[212:213], v[14:15], v[130:131], v[212:213]
	v_cvt_f16_f32_e32 v132, v198
	v_cvt_f16_f32_e32 v133, v200
	v_cvt_f16_f32_e32 v134, v202
	v_cvt_f16_f32_e32 v135, v204
	v_cvt_f16_f32_e32 v136, v206
	v_cvt_f16_f32_e32 v137, v208
	v_cvt_f16_f32_e32 v138, v210
	v_cvt_f16_f32_e32 v139, v212
	v_cvt_f16_f32_sdwa v132, v199 dst_sel:WORD_1 dst_unused:UNUSED_PRESERVE src0_sel:DWORD
	v_cvt_f16_f32_sdwa v133, v201 dst_sel:WORD_1 dst_unused:UNUSED_PRESERVE src0_sel:DWORD
	v_cvt_f16_f32_sdwa v134, v203 dst_sel:WORD_1 dst_unused:UNUSED_PRESERVE src0_sel:DWORD
	v_cvt_f16_f32_sdwa v135, v205 dst_sel:WORD_1 dst_unused:UNUSED_PRESERVE src0_sel:DWORD
	v_cvt_f16_f32_sdwa v136, v207 dst_sel:WORD_1 dst_unused:UNUSED_PRESERVE src0_sel:DWORD
	v_cvt_f16_f32_sdwa v137, v209 dst_sel:WORD_1 dst_unused:UNUSED_PRESERVE src0_sel:DWORD
	v_cvt_f16_f32_sdwa v138, v211 dst_sel:WORD_1 dst_unused:UNUSED_PRESERVE src0_sel:DWORD
	v_cvt_f16_f32_sdwa v139, v213 dst_sel:WORD_1 dst_unused:UNUSED_PRESERVE src0_sel:DWORD
	s_nop 0
	global_store_dwordx4 v187, v[132:135], s[42:43] offset:-2048 sc1
	global_store_dwordx4 v187, v[136:139], s[42:43] offset:-1024 sc1
	v_pk_mul_f32 v[140:141], v[198:199], v[198:199]
	v_pk_fma_f32 v[140:141], v[200:201], v[200:201], v[140:141]
	v_pk_fma_f32 v[140:141], v[202:203], v[202:203], v[140:141]
	v_pk_fma_f32 v[140:141], v[204:205], v[204:205], v[140:141]
	v_pk_fma_f32 v[140:141], v[206:207], v[206:207], v[140:141]
	v_pk_fma_f32 v[140:141], v[208:209], v[208:209], v[140:141]
	v_pk_fma_f32 v[140:141], v[210:211], v[210:211], v[140:141]
	v_pk_fma_f32 v[140:141], v[212:213], v[212:213], v[140:141]
	v_add_f32_e32 v140, v140, v141
	s_nop 1
	v_add_f32_dpp v140, v140, v140 quad_perm:[1,0,3,2] row_mask:0xf bank_mask:0xf
	s_nop 1
	v_add_f32_dpp v140, v140, v140 quad_perm:[2,3,0,1] row_mask:0xf bank_mask:0xf
	s_nop 1
	v_add_f32_dpp v140, v140, v140 row_ror:4 row_mask:0xf bank_mask:0xf
	s_nop 1
	v_add_f32_dpp v140, v140, v140 row_ror:8 row_mask:0xf bank_mask:0xf
	s_nop 1
	v_add_f32_dpp v140, v140, v140 row_bcast:15 row_mask:0xa bank_mask:0xf
	s_nop 1
	v_add_f32_dpp v140, v140, v140 row_bcast:31 row_mask:0xc bank_mask:0xf
	s_nop 1
	v_fmamk_f32 v140, v140, 0x3a800000, v224
	v_rsq_f32_e32 v140, v140
	s_nop 0
	v_readlane_b32 s6, v140, 63
	s_nop 1
	v_pk_mul_f32 v[198:199], v[198:199], s[6:7] op_sel_hi:[1,0]
	v_pk_mul_f32 v[200:201], v[200:201], s[6:7] op_sel_hi:[1,0]
	v_pk_mul_f32 v[202:203], v[202:203], s[6:7] op_sel_hi:[1,0]
	v_pk_mul_f32 v[204:205], v[204:205], s[6:7] op_sel_hi:[1,0]
	v_pk_mul_f32 v[206:207], v[206:207], s[6:7] op_sel_hi:[1,0]
	v_pk_mul_f32 v[208:209], v[208:209], s[6:7] op_sel_hi:[1,0]
	v_pk_mul_f32 v[210:211], v[210:211], s[6:7] op_sel_hi:[1,0]
	v_pk_mul_f32 v[212:213], v[212:213], s[6:7] op_sel_hi:[1,0]
	v_pk_mul_f32 v[198:199], v[16:17], v[198:199]
	v_pk_mul_f32 v[200:201], v[18:19], v[200:201]
	v_pk_mul_f32 v[202:203], v[20:21], v[202:203]
	v_pk_mul_f32 v[204:205], v[22:23], v[204:205]
	v_pk_mul_f32 v[206:207], v[24:25], v[206:207]
	v_pk_mul_f32 v[208:209], v[26:27], v[208:209]
	v_pk_mul_f32 v[210:211], v[28:29], v[210:211]
	v_pk_mul_f32 v[212:213], v[30:31], v[212:213]
	v_pk_fma_f32 v[198:199], v[32:33], v[198:199], v[48:49]
	v_pk_fma_f32 v[200:201], v[34:35], v[200:201], v[50:51]
	v_pk_fma_f32 v[202:203], v[36:37], v[202:203], v[52:53]
	v_pk_fma_f32 v[204:205], v[38:39], v[204:205], v[54:55]
	v_pk_fma_f32 v[206:207], v[40:41], v[206:207], v[56:57]
	v_pk_fma_f32 v[208:209], v[42:43], v[208:209], v[58:59]
	v_pk_fma_f32 v[210:211], v[44:45], v[210:211], v[60:61]
	v_pk_fma_f32 v[212:213], v[46:47], v[212:213], v[62:63]
	v_cvt_pk_bf16_f32 v230, v198, v199
	v_cvt_pk_bf16_f32 v231, v200, v201
	v_cvt_pk_bf16_f32 v232, v202, v203
	v_cvt_pk_bf16_f32 v233, v204, v205
	v_cvt_pk_bf16_f32 v234, v206, v207
	v_cvt_pk_bf16_f32 v235, v208, v209
	v_cvt_pk_bf16_f32 v236, v210, v211
	v_cvt_pk_bf16_f32 v237, v212, v213
	global_store_dwordx4 v187, v[230:233], s[44:45] offset:-2048 sc1
	global_store_dwordx4 v187, v[234:237], s[44:45] offset:-1024 sc1
	s_waitcnt vmcnt(20)
; template <int R, bool SRCB> ...
;     ...
;         for (int r = 0; r < R; ++r) {
;             f32x4 y[2][2]; float ss = 0.f;
; #pragma unroll
;             for (int j = 0; j < 2; ++j) { const u32x4 t = yr[r][j];
;                 y[j][0] = (f32x4){bf_lo(t.x), bf_hi(t.x), bf_lo(t.y), bf_hi(t.y)}; y[j][1] = (f32x4){bf_lo(t.z), bf_hi(t.z), bf_lo(t.w), bf_hi(t.w)};
;                 if (R == 1 && YP) {
; #pragma unroll
;                     for (int k = 0; k < 2; ++k) { const float* pp = YP + (size_t)(row0 - M_LAT) * DM + 8 * lane + 512 * j + 4 * k; f32x4 s = *(const f32x4*)pp;
; #pragma unroll
;                         for (int q = 1; q < pg8::NSL; ++q) s = s + *(const f32x4*)(pp + (size_t)q * 2048 * DM);
;                         y[j][k] = s; } }
; #pragma unroll
;                 for (int k = 0; k < 2; ++k) ss += (y[j][k][0] * y[j][k][0] + y[j][k][1] * y[j][k][1]) + (y[j][k][2] * y[j][k][2] + y[j][k][3] * y[j][k][3]); }
;             const float rr = __builtin_amdgcn_rsqf(wave_sum(ss) * (1.0f / DM) + 1e-6f) * w;
; #pragma unroll
;             for (int j = 0; j < 2; ++j)
; #pragma unroll
;                 for (int k = 0; k < 2; ++k) h[r][j][k] = h[r][j][k] + gg[j][k] * (y[j][k] * rr);
;         }
;     }
; #pragma unroll
;     for (int r = 0; r < R; ++r)
; #pragma unroll
;         for (int j = 0; j < 2; ++j) { const int c = 8 * lane + 512 * j;
;             if (final_out) { *(f32x4*)(final_out + (size_t)(row0 + r) * DM + c) = h[r][j][0]; *(f32x4*)(final_out + (size_t)(row0 + r) * DM + c + 4) = h[r][j][1]; }
;             else { u32x4 t; t.x = pkh2(h[r][j][0][0], h[r][j][0][1]); t.y = pkh2(h[r][j][0][2], h[r][j][0][3]); t.z = pkh2(h[r][j][1][0], h[r][j][1][1]); t.w = pkh2(h[r][j][1][2], h[r][j][1][3]);
;                 *(u32x4*)(hout + (size_t)(row0 + r) * DM + c) = t; } }
;     if (U) {
;         f32x4 gp[2][2], sc1[2][2], sh[2][2];
; #pragma unroll
;         for (int j = 0; j < 2; ++j)
; #pragma unroll
;             for (int k = 0; k < 2; ++k) { const int c = 8 * lane + 512 * j + 4 * k; gp[j][k] = *(const f32x4*)(gpre + c); sc1[j][k] = *(const f32x4*)(scale + (size_t)mrow * 9216 + c) + 1.0f; sh[j][k] = *(const f32x4*)(shift + (size_t)mrow * 9216 + c); }
; #pragma unroll
;         for (int r = 0; r < R; ++r) {
;             float ss = 0.f;
; #pragma unroll
;             for (int j = 0; j < 2; ++j)
; #pragma unroll
	v_lshlrev_b32_e32 v116, 16, v164
	v_and_b32_e32 v117, 0xffff0000, v164
	v_lshlrev_b32_e32 v118, 16, v165
	v_and_b32_e32 v119, 0xffff0000, v165
	v_lshlrev_b32_e32 v120, 16, v166
	v_and_b32_e32 v121, 0xffff0000, v166
	v_lshlrev_b32_e32 v122, 16, v167
	v_and_b32_e32 v123, 0xffff0000, v167
	v_lshlrev_b32_e32 v124, 16, v168
	v_and_b32_e32 v125, 0xffff0000, v168
	v_lshlrev_b32_e32 v126, 16, v169
	v_and_b32_e32 v127, 0xffff0000, v169
	v_lshlrev_b32_e32 v128, 16, v170
	v_and_b32_e32 v129, 0xffff0000, v170
	v_lshlrev_b32_e32 v130, 16, v171
	v_and_b32_e32 v131, 0xffff0000, v171
	v_cvt_f32_f16_e32 v198, v80
	v_cvt_f32_f16_sdwa v199, v80 dst_sel:DWORD dst_unused:UNUSED_PAD src0_sel:WORD_1
	v_cvt_f32_f16_e32 v200, v81
	v_cvt_f32_f16_sdwa v201, v81 dst_sel:DWORD dst_unused:UNUSED_PAD src0_sel:WORD_1
	v_cvt_f32_f16_e32 v202, v82
	v_cvt_f32_f16_sdwa v203, v82 dst_sel:DWORD dst_unused:UNUSED_PAD src0_sel:WORD_1
	v_cvt_f32_f16_e32 v204, v83
	v_cvt_f32_f16_sdwa v205, v83 dst_sel:DWORD dst_unused:UNUSED_PAD src0_sel:WORD_1
	v_cvt_f32_f16_e32 v206, v84
	v_cvt_f32_f16_sdwa v207, v84 dst_sel:DWORD dst_unused:UNUSED_PAD src0_sel:WORD_1
	v_cvt_f32_f16_e32 v208, v85
	v_cvt_f32_f16_sdwa v209, v85 dst_sel:DWORD dst_unused:UNUSED_PAD src0_sel:WORD_1
	v_cvt_f32_f16_e32 v210, v86
	v_cvt_f32_f16_sdwa v211, v86 dst_sel:DWORD dst_unused:UNUSED_PAD src0_sel:WORD_1
	v_cvt_f32_f16_e32 v212, v87
	v_cvt_f32_f16_sdwa v213, v87 dst_sel:DWORD dst_unused:UNUSED_PAD src0_sel:WORD_1
	v_pk_mul_f32 v[140:141], v[116:117], v[116:117]
	v_pk_fma_f32 v[140:141], v[118:119], v[118:119], v[140:141]
	v_pk_fma_f32 v[140:141], v[120:121], v[120:121], v[140:141]
	v_pk_fma_f32 v[140:141], v[122:123], v[122:123], v[140:141]
	v_pk_fma_f32 v[140:141], v[124:125], v[124:125], v[140:141]
	v_pk_fma_f32 v[140:141], v[126:127], v[126:127], v[140:141]
	v_pk_fma_f32 v[140:141], v[128:129], v[128:129], v[140:141]
	v_pk_fma_f32 v[140:141], v[130:131], v[130:131], v[140:141]
	v_add_f32_e32 v140, v140, v141
	s_nop 1
	v_add_f32_dpp v140, v140, v140 quad_perm:[1,0,3,2] row_mask:0xf bank_mask:0xf
	s_nop 1
	v_add_f32_dpp v140, v140, v140 quad_perm:[2,3,0,1] row_mask:0xf bank_mask:0xf
	s_nop 1
	v_add_f32_dpp v140, v140, v140 row_ror:4 row_mask:0xf bank_mask:0xf
	s_nop 1
	v_add_f32_dpp v140, v140, v140 row_ror:8 row_mask:0xf bank_mask:0xf
	s_nop 1
	v_add_f32_dpp v140, v140, v140 row_bcast:15 row_mask:0xa bank_mask:0xf
	s_nop 1
	v_add_f32_dpp v140, v140, v140 row_bcast:31 row_mask:0xc bank_mask:0xf
	s_nop 1
	v_fmamk_f32 v140, v140, 0x3a800000, v224
	v_rsq_f32_e32 v140, v140
	s_nop 0
	v_mul_f32_e32 v140, v144, v140
	s_nop 0
	v_readlane_b32 s4, v140, 63
	s_nop 1
	v_pk_mul_f32 v[116:117], v[116:117], s[4:5] op_sel_hi:[1,0]
	v_pk_mul_f32 v[118:119], v[118:119], s[4:5] op_sel_hi:[1,0]
	v_pk_mul_f32 v[120:121], v[120:121], s[4:5] op_sel_hi:[1,0]
	v_pk_mul_f32 v[122:123], v[122:123], s[4:5] op_sel_hi:[1,0]
	v_pk_mul_f32 v[124:125], v[124:125], s[4:5] op_sel_hi:[1,0]
	v_pk_mul_f32 v[126:127], v[126:127], s[4:5] op_sel_hi:[1,0]
	v_pk_mul_f32 v[128:129], v[128:129], s[4:5] op_sel_hi:[1,0]
	v_pk_mul_f32 v[130:131], v[130:131], s[4:5] op_sel_hi:[1,0]
	v_pk_fma_f32 v[198:199], v[0:1], v[116:117], v[198:199]
	v_pk_fma_f32 v[200:201], v[2:3], v[118:119], v[200:201]
	v_pk_fma_f32 v[202:203], v[4:5], v[120:121], v[202:203]
	v_pk_fma_f32 v[204:205], v[6:7], v[122:123], v[204:205]
	v_pk_fma_f32 v[206:207], v[8:9], v[124:125], v[206:207]
	v_pk_fma_f32 v[208:209], v[10:11], v[126:127], v[208:209]
	v_pk_fma_f32 v[210:211], v[12:13], v[128:129], v[210:211]
	v_pk_fma_f32 v[212:213], v[14:15], v[130:131], v[212:213]
	v_cvt_f16_f32_e32 v132, v198
	v_cvt_f16_f32_e32 v133, v200
	v_cvt_f16_f32_e32 v134, v202
	v_cvt_f16_f32_e32 v135, v204
	v_cvt_f16_f32_e32 v136, v206
	v_cvt_f16_f32_e32 v137, v208
	v_cvt_f16_f32_e32 v138, v210
	v_cvt_f16_f32_e32 v139, v212
	v_cvt_f16_f32_sdwa v132, v199 dst_sel:WORD_1 dst_unused:UNUSED_PRESERVE src0_sel:DWORD
	v_cvt_f16_f32_sdwa v133, v201 dst_sel:WORD_1 dst_unused:UNUSED_PRESERVE src0_sel:DWORD
	v_cvt_f16_f32_sdwa v134, v203 dst_sel:WORD_1 dst_unused:UNUSED_PRESERVE src0_sel:DWORD
	v_cvt_f16_f32_sdwa v135, v205 dst_sel:WORD_1 dst_unused:UNUSED_PRESERVE src0_sel:DWORD
	v_cvt_f16_f32_sdwa v136, v207 dst_sel:WORD_1 dst_unused:UNUSED_PRESERVE src0_sel:DWORD
	v_cvt_f16_f32_sdwa v137, v209 dst_sel:WORD_1 dst_unused:UNUSED_PRESERVE src0_sel:DWORD
	v_cvt_f16_f32_sdwa v138, v211 dst_sel:WORD_1 dst_unused:UNUSED_PRESERVE src0_sel:DWORD
	v_cvt_f16_f32_sdwa v139, v213 dst_sel:WORD_1 dst_unused:UNUSED_PRESERVE src0_sel:DWORD
	s_nop 0
	global_store_dwordx4 v187, v[132:135], s[42:43] offset:0 sc1
	global_store_dwordx4 v187, v[136:139], s[42:43] offset:1024 sc1
	v_pk_mul_f32 v[140:141], v[198:199], v[198:199]
	v_pk_fma_f32 v[140:141], v[200:201], v[200:201], v[140:141]
	v_pk_fma_f32 v[140:141], v[202:203], v[202:203], v[140:141]
	v_pk_fma_f32 v[140:141], v[204:205], v[204:205], v[140:141]
	v_pk_fma_f32 v[140:141], v[206:207], v[206:207], v[140:141]
	v_pk_fma_f32 v[140:141], v[208:209], v[208:209], v[140:141]
	v_pk_fma_f32 v[140:141], v[210:211], v[210:211], v[140:141]
	v_pk_fma_f32 v[140:141], v[212:213], v[212:213], v[140:141]
	v_add_f32_e32 v140, v140, v141
	s_nop 1
	v_add_f32_dpp v140, v140, v140 quad_perm:[1,0,3,2] row_mask:0xf bank_mask:0xf
	s_nop 1
	v_add_f32_dpp v140, v140, v140 quad_perm:[2,3,0,1] row_mask:0xf bank_mask:0xf
	s_nop 1
	v_add_f32_dpp v140, v140, v140 row_ror:4 row_mask:0xf bank_mask:0xf
	s_nop 1
	v_add_f32_dpp v140, v140, v140 row_ror:8 row_mask:0xf bank_mask:0xf
	s_nop 1
	v_add_f32_dpp v140, v140, v140 row_bcast:15 row_mask:0xa bank_mask:0xf
	s_nop 1
	v_add_f32_dpp v140, v140, v140 row_bcast:31 row_mask:0xc bank_mask:0xf
; __device__ __forceinline__ unsigned pk2(float lo, float hi) { return pg8::cvt_pk_bf16(lo, hi); }
; template <int R, bool SRCB> ...
;     ...
;             const float rr = __builtin_amdgcn_rsqf(wave_sum(ss) * (1.0f / DM) + 1e-6f) * w;
; #pragma unroll
;             for (int j = 0; j < 2; ++j)
; #pragma unroll
;                 for (int k = 0; k < 2; ++k) h[r][j][k] = h[r][j][k] + gg[j][k] * (y[j][k] * rr);
;         }
;     }
; #pragma unroll
;     for (int r = 0; r < R; ++r)
; #pragma unroll
;         for (int j = 0; j < 2; ++j) { const int c = 8 * lane + 512 * j;
;             if (final_out) { *(f32x4*)(final_out + (size_t)(row0 + r) * DM + c) = h[r][j][0]; *(f32x4*)(final_out + (size_t)(row0 + r) * DM + c + 4) = h[r][j][1]; }
;             else { u32x4 t; t.x = pkh2(h[r][j][0][0], h[r][j][0][1]); t.y = pkh2(h[r][j][0][2], h[r][j][0][3]); t.z = pkh2(h[r][j][1][0], h[r][j][1][1]); t.w = pkh2(h[r][j][1][2], h[r][j][1][3]);
;                 *(u32x4*)(hout + (size_t)(row0 + r) * DM + c) = t; } }
;     if (U) {
;         f32x4 gp[2][2], sc1[2][2], sh[2][2];
; #pragma unroll
;         for (int j = 0; j < 2; ++j)
; #pragma unroll
;             for (int k = 0; k < 2; ++k) { const int c = 8 * lane + 512 * j + 4 * k; gp[j][k] = *(const f32x4*)(gpre + c); sc1[j][k] = *(const f32x4*)(scale + (size_t)mrow * 9216 + c) + 1.0f; sh[j][k] = *(const f32x4*)(shift + (size_t)mrow * 9216 + c); }
; #pragma unroll
;         for (int r = 0; r < R; ++r) {
;             float ss = 0.f;
; #pragma unroll
;             for (int j = 0; j < 2; ++j)
; #pragma unroll
;                 for (int k = 0; k < 2; ++k) ss += (h[r][j][k][0] * h[r][j][k][0] + h[r][j][k][1] * h[r][j][k][1]) + (h[r][j][k][2] * h[r][j][k][2] + h[r][j][k][3] * h[r][j][k][3]);
;             const float rr = __builtin_amdgcn_rsqf(wave_sum(ss) * (1.0f / DM) + 1e-6f);
; #pragma unroll
;             for (int j = 0; j < 2; ++j) { const f32x4 v0 = (h[r][j][0] * rr * gp[j][0]) * sc1[j][0] + sh[j][0], v1 = (h[r][j][1] * rr * gp[j][1]) * sc1[j][1] + sh[j][1];
;                 u32x4 t; t.x = pk2(v0[0], v0[1]); t.y = pk2(v0[2], v0[3]); t.z = pk2(v1[0], v1[1]); t.w = pk2(v1[2], v1[3]);
;                 *(u32x4*)(U + (size_t)(row0 + r) * DM + 8 * lane + 512 * j) = t; }
	s_nop 1
	v_fmamk_f32 v140, v140, 0x3a800000, v224
	v_rsq_f32_e32 v140, v140
	s_nop 0
	v_readlane_b32 s6, v140, 63
	s_nop 1
	v_pk_mul_f32 v[198:199], v[198:199], s[6:7] op_sel_hi:[1,0]
	v_pk_mul_f32 v[200:201], v[200:201], s[6:7] op_sel_hi:[1,0]
	v_pk_mul_f32 v[202:203], v[202:203], s[6:7] op_sel_hi:[1,0]
	v_pk_mul_f32 v[204:205], v[204:205], s[6:7] op_sel_hi:[1,0]
	v_pk_mul_f32 v[206:207], v[206:207], s[6:7] op_sel_hi:[1,0]
	v_pk_mul_f32 v[208:209], v[208:209], s[6:7] op_sel_hi:[1,0]
	v_pk_mul_f32 v[210:211], v[210:211], s[6:7] op_sel_hi:[1,0]
	v_pk_mul_f32 v[212:213], v[212:213], s[6:7] op_sel_hi:[1,0]
	v_pk_mul_f32 v[198:199], v[16:17], v[198:199]
	v_pk_mul_f32 v[200:201], v[18:19], v[200:201]
	v_pk_mul_f32 v[202:203], v[20:21], v[202:203]
	v_pk_mul_f32 v[204:205], v[22:23], v[204:205]
	v_pk_mul_f32 v[206:207], v[24:25], v[206:207]
	v_pk_mul_f32 v[208:209], v[26:27], v[208:209]
	v_pk_mul_f32 v[210:211], v[28:29], v[210:211]
	v_pk_mul_f32 v[212:213], v[30:31], v[212:213]
	v_pk_fma_f32 v[198:199], v[32:33], v[198:199], v[48:49]
	v_pk_fma_f32 v[200:201], v[34:35], v[200:201], v[50:51]
	v_pk_fma_f32 v[202:203], v[36:37], v[202:203], v[52:53]
	v_pk_fma_f32 v[204:205], v[38:39], v[204:205], v[54:55]
	v_pk_fma_f32 v[206:207], v[40:41], v[206:207], v[56:57]
	v_pk_fma_f32 v[208:209], v[42:43], v[208:209], v[58:59]
	v_pk_fma_f32 v[210:211], v[44:45], v[210:211], v[60:61]
	v_pk_fma_f32 v[212:213], v[46:47], v[212:213], v[62:63]
	v_cvt_pk_bf16_f32 v230, v198, v199
	v_cvt_pk_bf16_f32 v231, v200, v201
	v_cvt_pk_bf16_f32 v232, v202, v203
	v_cvt_pk_bf16_f32 v233, v204, v205
	v_cvt_pk_bf16_f32 v234, v206, v207
	v_cvt_pk_bf16_f32 v235, v208, v209
	v_cvt_pk_bf16_f32 v236, v210, v211
	v_cvt_pk_bf16_f32 v237, v212, v213
	global_store_dwordx4 v187, v[230:233], s[44:45] offset:0 sc1
	global_store_dwordx4 v187, v[234:237], s[44:45] offset:1024 sc1
	s_waitcnt vmcnt(16)
	v_lshlrev_b32_e32 v116, 16, v172
	v_and_b32_e32 v117, 0xffff0000, v172
	v_lshlrev_b32_e32 v118, 16, v173
	v_and_b32_e32 v119, 0xffff0000, v173
	v_lshlrev_b32_e32 v120, 16, v174
	v_and_b32_e32 v121, 0xffff0000, v174
	v_lshlrev_b32_e32 v122, 16, v175
	v_and_b32_e32 v123, 0xffff0000, v175
	v_lshlrev_b32_e32 v124, 16, v176
	v_and_b32_e32 v125, 0xffff0000, v176
	v_lshlrev_b32_e32 v126, 16, v177
	v_and_b32_e32 v127, 0xffff0000, v177
	v_lshlrev_b32_e32 v128, 16, v178
	v_and_b32_e32 v129, 0xffff0000, v178
	v_lshlrev_b32_e32 v130, 16, v179
	v_and_b32_e32 v131, 0xffff0000, v179
	v_cvt_f32_f16_e32 v198, v88
	v_cvt_f32_f16_sdwa v199, v88 dst_sel:DWORD dst_unused:UNUSED_PAD src0_sel:WORD_1
	v_cvt_f32_f16_e32 v200, v89
	v_cvt_f32_f16_sdwa v201, v89 dst_sel:DWORD dst_unused:UNUSED_PAD src0_sel:WORD_1
	v_cvt_f32_f16_e32 v202, v90
	v_cvt_f32_f16_sdwa v203, v90 dst_sel:DWORD dst_unused:UNUSED_PAD src0_sel:WORD_1
	v_cvt_f32_f16_e32 v204, v91
	v_cvt_f32_f16_sdwa v205, v91 dst_sel:DWORD dst_unused:UNUSED_PAD src0_sel:WORD_1
	v_cvt_f32_f16_e32 v206, v92
	v_cvt_f32_f16_sdwa v207, v92 dst_sel:DWORD dst_unused:UNUSED_PAD src0_sel:WORD_1
	v_cvt_f32_f16_e32 v208, v93
	v_cvt_f32_f16_sdwa v209, v93 dst_sel:DWORD dst_unused:UNUSED_PAD src0_sel:WORD_1
	v_cvt_f32_f16_e32 v210, v94
	v_cvt_f32_f16_sdwa v211, v94 dst_sel:DWORD dst_unused:UNUSED_PAD src0_sel:WORD_1
	v_cvt_f32_f16_e32 v212, v95
	v_cvt_f32_f16_sdwa v213, v95 dst_sel:DWORD dst_unused:UNUSED_PAD src0_sel:WORD_1
	v_pk_mul_f32 v[140:141], v[116:117], v[116:117]
	v_pk_fma_f32 v[140:141], v[118:119], v[118:119], v[140:141]
	v_pk_fma_f32 v[140:141], v[120:121], v[120:121], v[140:141]
	v_pk_fma_f32 v[140:141], v[122:123], v[122:123], v[140:141]
	v_pk_fma_f32 v[140:141], v[124:125], v[124:125], v[140:141]
	v_pk_fma_f32 v[140:141], v[126:127], v[126:127], v[140:141]
	v_pk_fma_f32 v[140:141], v[128:129], v[128:129], v[140:141]
	v_pk_fma_f32 v[140:141], v[130:131], v[130:131], v[140:141]
	v_add_f32_e32 v140, v140, v141
	s_nop 1
	v_add_f32_dpp v140, v140, v140 quad_perm:[1,0,3,2] row_mask:0xf bank_mask:0xf
	s_nop 1
	v_add_f32_dpp v140, v140, v140 quad_perm:[2,3,0,1] row_mask:0xf bank_mask:0xf
	s_nop 1
	v_add_f32_dpp v140, v140, v140 row_ror:4 row_mask:0xf bank_mask:0xf
	s_nop 1
	v_add_f32_dpp v140, v140, v140 row_ror:8 row_mask:0xf bank_mask:0xf
	s_nop 1
	v_add_f32_dpp v140, v140, v140 row_bcast:15 row_mask:0xa bank_mask:0xf
	s_nop 1
	v_add_f32_dpp v140, v140, v140 row_bcast:31 row_mask:0xc bank_mask:0xf
	s_nop 1
	v_fmamk_f32 v140, v140, 0x3a800000, v224
	v_rsq_f32_e32 v140, v140
	s_nop 0
	v_mul_f32_e32 v140, v144, v140
	s_nop 0
	v_readlane_b32 s4, v140, 63
	s_nop 1
	v_pk_mul_f32 v[116:117], v[116:117], s[4:5] op_sel_hi:[1,0]
	v_pk_mul_f32 v[118:119], v[118:119], s[4:5] op_sel_hi:[1,0]
	v_pk_mul_f32 v[120:121], v[120:121], s[4:5] op_sel_hi:[1,0]
	v_pk_mul_f32 v[122:123], v[122:123], s[4:5] op_sel_hi:[1,0]
; __device__ __forceinline__ unsigned pk2(float lo, float hi) { return pg8::cvt_pk_bf16(lo, hi); }
; template <int R, bool SRCB> ...
;     ...
;                 for (int k = 0; k < 2; ++k) h[r][j][k] = h[r][j][k] + gg[j][k] * (y[j][k] * rr);
;         }
;     }
; #pragma unroll
;     for (int r = 0; r < R; ++r)
; #pragma unroll
;         for (int j = 0; j < 2; ++j) { const int c = 8 * lane + 512 * j;
;             if (final_out) { *(f32x4*)(final_out + (size_t)(row0 + r) * DM + c) = h[r][j][0]; *(f32x4*)(final_out + (size_t)(row0 + r) * DM + c + 4) = h[r][j][1]; }
;             else { u32x4 t; t.x = pkh2(h[r][j][0][0], h[r][j][0][1]); t.y = pkh2(h[r][j][0][2], h[r][j][0][3]); t.z = pkh2(h[r][j][1][0], h[r][j][1][1]); t.w = pkh2(h[r][j][1][2], h[r][j][1][3]);
;                 *(u32x4*)(hout + (size_t)(row0 + r) * DM + c) = t; } }
;     if (U) {
;         f32x4 gp[2][2], sc1[2][2], sh[2][2];
; #pragma unroll
;         for (int j = 0; j < 2; ++j)
; #pragma unroll
;             for (int k = 0; k < 2; ++k) { const int c = 8 * lane + 512 * j + 4 * k; gp[j][k] = *(const f32x4*)(gpre + c); sc1[j][k] = *(const f32x4*)(scale + (size_t)mrow * 9216 + c) + 1.0f; sh[j][k] = *(const f32x4*)(shift + (size_t)mrow * 9216 + c); }
; #pragma unroll
;         for (int r = 0; r < R; ++r) {
;             float ss = 0.f;
; #pragma unroll
;             for (int j = 0; j < 2; ++j)
; #pragma unroll
;                 for (int k = 0; k < 2; ++k) ss += (h[r][j][k][0] * h[r][j][k][0] + h[r][j][k][1] * h[r][j][k][1]) + (h[r][j][k][2] * h[r][j][k][2] + h[r][j][k][3] * h[r][j][k][3]);
;             const float rr = __builtin_amdgcn_rsqf(wave_sum(ss) * (1.0f / DM) + 1e-6f);
; #pragma unroll
;             for (int j = 0; j < 2; ++j) { const f32x4 v0 = (h[r][j][0] * rr * gp[j][0]) * sc1[j][0] + sh[j][0], v1 = (h[r][j][1] * rr * gp[j][1]) * sc1[j][1] + sh[j][1];
;                 u32x4 t; t.x = pk2(v0[0], v0[1]); t.y = pk2(v0[2], v0[3]); t.z = pk2(v1[0], v1[1]); t.w = pk2(v1[2], v1[3]);
;                 *(u32x4*)(U + (size_t)(row0 + r) * DM + 8 * lane + 512 * j) = t; }
; template <bool SRCB> ...
;     ...
;     for (int g = gw; g < M_LAT / 4; g += NGW) norm_rows<4, SRCB>(4 * g, g >> 10, SRCB ? (const void*)((const bf16_t*)hsrc_lat + (size_t)g * 4 * DM) : (const void*)((const float*)hsrc_lat + (size_t)g * 4 * DM), hout, final_out, Y, nullptr, w, gpost, gate, U, gpre, shift, scale, lane);
	v_pk_mul_f32 v[124:125], v[124:125], s[4:5] op_sel_hi:[1,0]
	v_pk_mul_f32 v[126:127], v[126:127], s[4:5] op_sel_hi:[1,0]
	v_pk_mul_f32 v[128:129], v[128:129], s[4:5] op_sel_hi:[1,0]
	v_pk_mul_f32 v[130:131], v[130:131], s[4:5] op_sel_hi:[1,0]
	v_pk_fma_f32 v[198:199], v[0:1], v[116:117], v[198:199]
	v_pk_fma_f32 v[200:201], v[2:3], v[118:119], v[200:201]
	v_pk_fma_f32 v[202:203], v[4:5], v[120:121], v[202:203]
	v_pk_fma_f32 v[204:205], v[6:7], v[122:123], v[204:205]
	v_pk_fma_f32 v[206:207], v[8:9], v[124:125], v[206:207]
	v_pk_fma_f32 v[208:209], v[10:11], v[126:127], v[208:209]
	v_pk_fma_f32 v[210:211], v[12:13], v[128:129], v[210:211]
	v_pk_fma_f32 v[212:213], v[14:15], v[130:131], v[212:213]
	v_cvt_f16_f32_e32 v132, v198
	v_cvt_f16_f32_e32 v133, v200
	v_cvt_f16_f32_e32 v134, v202
	v_cvt_f16_f32_e32 v135, v204
	v_cvt_f16_f32_e32 v136, v206
	v_cvt_f16_f32_e32 v137, v208
	v_cvt_f16_f32_e32 v138, v210
	v_cvt_f16_f32_e32 v139, v212
	v_cvt_f16_f32_sdwa v132, v199 dst_sel:WORD_1 dst_unused:UNUSED_PRESERVE src0_sel:DWORD
	v_cvt_f16_f32_sdwa v133, v201 dst_sel:WORD_1 dst_unused:UNUSED_PRESERVE src0_sel:DWORD
	v_cvt_f16_f32_sdwa v134, v203 dst_sel:WORD_1 dst_unused:UNUSED_PRESERVE src0_sel:DWORD
	v_cvt_f16_f32_sdwa v135, v205 dst_sel:WORD_1 dst_unused:UNUSED_PRESERVE src0_sel:DWORD
	v_cvt_f16_f32_sdwa v136, v207 dst_sel:WORD_1 dst_unused:UNUSED_PRESERVE src0_sel:DWORD
	v_cvt_f16_f32_sdwa v137, v209 dst_sel:WORD_1 dst_unused:UNUSED_PRESERVE src0_sel:DWORD
	v_cvt_f16_f32_sdwa v138, v211 dst_sel:WORD_1 dst_unused:UNUSED_PRESERVE src0_sel:DWORD
	v_cvt_f16_f32_sdwa v139, v213 dst_sel:WORD_1 dst_unused:UNUSED_PRESERVE src0_sel:DWORD
	s_nop 0
	global_store_dwordx4 v187, v[132:135], s[42:43] offset:2048 sc1
	global_store_dwordx4 v187, v[136:139], s[42:43] offset:3072 sc1
	v_pk_mul_f32 v[140:141], v[198:199], v[198:199]
	v_pk_fma_f32 v[140:141], v[200:201], v[200:201], v[140:141]
	v_pk_fma_f32 v[140:141], v[202:203], v[202:203], v[140:141]
	v_pk_fma_f32 v[140:141], v[204:205], v[204:205], v[140:141]
	v_pk_fma_f32 v[140:141], v[206:207], v[206:207], v[140:141]
	v_pk_fma_f32 v[140:141], v[208:209], v[208:209], v[140:141]
	v_pk_fma_f32 v[140:141], v[210:211], v[210:211], v[140:141]
	v_pk_fma_f32 v[140:141], v[212:213], v[212:213], v[140:141]
	v_add_f32_e32 v140, v140, v141
	s_nop 1
	v_add_f32_dpp v140, v140, v140 quad_perm:[1,0,3,2] row_mask:0xf bank_mask:0xf
	s_nop 1
	v_add_f32_dpp v140, v140, v140 quad_perm:[2,3,0,1] row_mask:0xf bank_mask:0xf
	s_nop 1
	v_add_f32_dpp v140, v140, v140 row_ror:4 row_mask:0xf bank_mask:0xf
	s_nop 1
	v_add_f32_dpp v140, v140, v140 row_ror:8 row_mask:0xf bank_mask:0xf
	s_nop 1
	v_add_f32_dpp v140, v140, v140 row_bcast:15 row_mask:0xa bank_mask:0xf
	s_nop 1
	v_add_f32_dpp v140, v140, v140 row_bcast:31 row_mask:0xc bank_mask:0xf
	s_nop 1
	v_fmamk_f32 v140, v140, 0x3a800000, v224
	v_rsq_f32_e32 v140, v140
	s_nop 0
	v_readlane_b32 s6, v140, 63
	s_nop 1
	v_pk_mul_f32 v[198:199], v[198:199], s[6:7] op_sel_hi:[1,0]
	v_pk_mul_f32 v[200:201], v[200:201], s[6:7] op_sel_hi:[1,0]
	v_pk_mul_f32 v[202:203], v[202:203], s[6:7] op_sel_hi:[1,0]
	v_pk_mul_f32 v[204:205], v[204:205], s[6:7] op_sel_hi:[1,0]
	v_pk_mul_f32 v[206:207], v[206:207], s[6:7] op_sel_hi:[1,0]
	v_pk_mul_f32 v[208:209], v[208:209], s[6:7] op_sel_hi:[1,0]
	v_pk_mul_f32 v[210:211], v[210:211], s[6:7] op_sel_hi:[1,0]
	v_pk_mul_f32 v[212:213], v[212:213], s[6:7] op_sel_hi:[1,0]
	v_pk_mul_f32 v[198:199], v[16:17], v[198:199]
	v_pk_mul_f32 v[200:201], v[18:19], v[200:201]
	v_pk_mul_f32 v[202:203], v[20:21], v[202:203]
	v_pk_mul_f32 v[204:205], v[22:23], v[204:205]
	v_pk_mul_f32 v[206:207], v[24:25], v[206:207]
	v_pk_mul_f32 v[208:209], v[26:27], v[208:209]
	v_pk_mul_f32 v[210:211], v[28:29], v[210:211]
	v_pk_mul_f32 v[212:213], v[30:31], v[212:213]
	v_pk_fma_f32 v[198:199], v[32:33], v[198:199], v[48:49]
	v_pk_fma_f32 v[200:201], v[34:35], v[200:201], v[50:51]
	v_pk_fma_f32 v[202:203], v[36:37], v[202:203], v[52:53]
	v_pk_fma_f32 v[204:205], v[38:39], v[204:205], v[54:55]
	v_pk_fma_f32 v[206:207], v[40:41], v[206:207], v[56:57]
	v_pk_fma_f32 v[208:209], v[42:43], v[208:209], v[58:59]
	v_pk_fma_f32 v[210:211], v[44:45], v[210:211], v[60:61]
	v_pk_fma_f32 v[212:213], v[46:47], v[212:213], v[62:63]
	v_cvt_pk_bf16_f32 v230, v198, v199
	v_cvt_pk_bf16_f32 v231, v200, v201
	v_cvt_pk_bf16_f32 v232, v202, v203
	v_cvt_pk_bf16_f32 v233, v204, v205
	v_cvt_pk_bf16_f32 v234, v206, v207
	v_cvt_pk_bf16_f32 v235, v208, v209
	v_cvt_pk_bf16_f32 v236, v210, v211
	v_cvt_pk_bf16_f32 v237, v212, v213
	global_store_dwordx4 v187, v[230:233], s[44:45] offset:2048 sc1
	global_store_dwordx4 v187, v[234:237], s[44:45] offset:3072 sc1
	s_add_i32 s23, s23, s76
	s_cmpk_lt_i32 s23, 0x800
	s_cbranch_scc1 nrmx_chunk
	s_branch .LBB0_245
